# v030 + in-projection gelu blocks re-emitted with fewer VALU ops (abs-modifier form, no compare/select)
# baseline (speedup 1.0000x reference)
; __device__ __forceinline__ f32x2 gelu_pk(f32x2 v) {
;     const f32x2 av = __builtin_elementwise_abs(v), d = av * 0.2316418882f + 1.0f;
;     f32x2 t; t.x = __builtin_amdgcn_rcpf(d.x); t.y = __builtin_amdgcn_rcpf(d.y);
;     f32x2 q = t * 0.5307027145f + (-0.7265760135f); q = q * t + 0.7107068705f; q = q * t + (-0.142248368f); q = q * t + 0.127414796f; q = q * t;
;     const f32x2 s = (v * v) * (-0.72134752044f);
;     f32x2 e; e.x = __builtin_amdgcn_exp2f(s.x); e.y = __builtin_amdgcn_exp2f(s.y);
;     const f32x2 m = v * (q * e), r = v - m;
;     f32x2 o; o.x = v.x < 0.f ? m.x : r.x; o.y = v.y < 0.f ? m.y : r.y; return o;
; }
;     __device__ __forceinline__ void operator()(const f32x4 (&acc)[2][2][4][2], const Unit& u, int wr, int wc, int fr, int fq) const {
;     ...
;                         f32x2 a = gelu_pk((f32x2){v0[0], v0[1]}), b = gelu_pk((f32x2){v0[2], v0[3]}), c = gelu_pk((f32x2){v1[0], v1[1]}), d = gelu_pk((f32x2){v1[2], v1[3]});
;                         v0 = (f32x4){a.x, a.y, b.x, b.y}; v1 = (f32x4){c.x, c.y, d.x, d.y};
;                         if (pn >= 9) { const float t1 = (v0[0] + v0[1]) + (v0[2] + v0[3]) + (v1[0] + v1[1]) + (v1[2] + v1[3]);
;                             const float t2 = (v0[0] * v0[0] + v0[1] * v0[1]) + (v0[2] * v0[2] + v0[3] * v0[3]) + (v1[0] * v1[0] + v1[1] * v1[1]) + (v1[2] * v1[2] + v1[3] * v1[3]);
;                             if (bj == 0) { ps = t1; pss = t2; } else { ps += t1; pss += t2; } }
.LBB0_216:
	s_andn2_b64 vcc, exec, s[12:13]
	s_cbranch_vccnz .LBB0_219
	v_mov_b64_e32 v[254:255], s[66:67]
	v_fma_f32 v248, |v126|, s62, 1.0
	v_fma_f32 v249, |v127|, s62, 1.0
	v_pk_mul_f32 v[252:253], v[126:127], v[126:127]
	v_rcp_f32_e32 v248, v248
	v_rcp_f32_e32 v249, v249
	v_pk_mul_f32 v[252:253], v[252:253], s[74:75] op_sel_hi:[1,0]
	v_pk_fma_f32 v[250:251], v[248:249], s[64:65], v[254:255] op_sel_hi:[1,0,0]
	v_exp_f32_e32 v252, v252
	v_exp_f32_e32 v253, v253
	v_pk_fma_f32 v[250:251], v[248:249], v[250:251], s[68:69] op_sel_hi:[1,1,0]
	v_pk_fma_f32 v[250:251], v[248:249], v[250:251], s[70:71] op_sel_hi:[1,1,0]
	v_pk_fma_f32 v[250:251], v[248:249], v[250:251], s[72:73] op_sel_hi:[1,1,0]
	v_pk_mul_f32 v[250:251], v[248:249], v[250:251]
	v_pk_fma_f32 v[250:251], v[250:251], v[252:253], 0.5 op_sel_hi:[1,1,0] neg_lo:[1,0,0] neg_hi:[1,0,0]
	v_pk_mul_f32 v[248:249], v[126:127], 0.5 op_sel_hi:[1,0]
	v_fma_f32 v186, |v126|, v250, v248
	v_fma_f32 v188, |v127|, v251, v249
	v_fma_f32 v248, |v128|, s62, 1.0
	v_fma_f32 v249, |v129|, s62, 1.0
	v_pk_mul_f32 v[252:253], v[128:129], v[128:129]
	v_rcp_f32_e32 v248, v248
	v_rcp_f32_e32 v249, v249
	v_pk_mul_f32 v[252:253], v[252:253], s[74:75] op_sel_hi:[1,0]
	v_pk_fma_f32 v[250:251], v[248:249], s[64:65], v[254:255] op_sel_hi:[1,0,0]
	v_exp_f32_e32 v252, v252
	v_exp_f32_e32 v253, v253
	v_pk_fma_f32 v[250:251], v[248:249], v[250:251], s[68:69] op_sel_hi:[1,1,0]
	v_pk_fma_f32 v[250:251], v[248:249], v[250:251], s[70:71] op_sel_hi:[1,1,0]
	v_pk_fma_f32 v[250:251], v[248:249], v[250:251], s[72:73] op_sel_hi:[1,1,0]
	v_pk_mul_f32 v[250:251], v[248:249], v[250:251]
	v_pk_fma_f32 v[250:251], v[250:251], v[252:253], 0.5 op_sel_hi:[1,1,0] neg_lo:[1,0,0] neg_hi:[1,0,0]
	v_pk_mul_f32 v[248:249], v[128:129], 0.5 op_sel_hi:[1,0]
	v_fma_f32 v187, |v128|, v250, v248
	v_fma_f32 v189, |v129|, v251, v249
	v_fma_f32 v248, |v124|, s62, 1.0
	v_fma_f32 v249, |v125|, s62, 1.0
	v_pk_mul_f32 v[252:253], v[124:125], v[124:125]
	v_rcp_f32_e32 v248, v248
	v_rcp_f32_e32 v249, v249
	v_pk_mul_f32 v[252:253], v[252:253], s[74:75] op_sel_hi:[1,0]
	v_pk_fma_f32 v[250:251], v[248:249], s[64:65], v[254:255] op_sel_hi:[1,0,0]
	v_exp_f32_e32 v252, v252
	v_exp_f32_e32 v253, v253
	v_pk_fma_f32 v[250:251], v[248:249], v[250:251], s[68:69] op_sel_hi:[1,1,0]
	v_pk_fma_f32 v[250:251], v[248:249], v[250:251], s[70:71] op_sel_hi:[1,1,0]
	v_pk_fma_f32 v[250:251], v[248:249], v[250:251], s[72:73] op_sel_hi:[1,1,0]
	v_pk_mul_f32 v[250:251], v[248:249], v[250:251]
	v_pk_fma_f32 v[250:251], v[250:251], v[252:253], 0.5 op_sel_hi:[1,1,0] neg_lo:[1,0,0] neg_hi:[1,0,0]
	v_pk_mul_f32 v[248:249], v[124:125], 0.5 op_sel_hi:[1,0]
	v_fma_f32 v192, |v124|, v250, v248
	v_fma_f32 v191, |v125|, v251, v249
	v_fma_f32 v248, |v122|, s62, 1.0
	v_fma_f32 v249, |v123|, s62, 1.0
	v_pk_mul_f32 v[252:253], v[122:123], v[122:123]
	v_rcp_f32_e32 v248, v248
	v_rcp_f32_e32 v249, v249
	v_pk_mul_f32 v[252:253], v[252:253], s[74:75] op_sel_hi:[1,0]
	v_pk_fma_f32 v[250:251], v[248:249], s[64:65], v[254:255] op_sel_hi:[1,0,0]
	v_exp_f32_e32 v252, v252
	v_exp_f32_e32 v253, v253
	v_pk_fma_f32 v[250:251], v[248:249], v[250:251], s[68:69] op_sel_hi:[1,1,0]
	v_pk_fma_f32 v[250:251], v[248:249], v[250:251], s[70:71] op_sel_hi:[1,1,0]
	v_pk_fma_f32 v[250:251], v[248:249], v[250:251], s[72:73] op_sel_hi:[1,1,0]
	v_pk_mul_f32 v[250:251], v[248:249], v[250:251]
	v_pk_fma_f32 v[250:251], v[250:251], v[252:253], 0.5 op_sel_hi:[1,1,0] neg_lo:[1,0,0] neg_hi:[1,0,0]
	v_pk_mul_f32 v[248:249], v[122:123], 0.5 op_sel_hi:[1,0]
	v_fma_f32 v190, |v122|, v250, v248
	v_fma_f32 v194, |v123|, v251, v249
	s_andn2_b64 vcc, exec, s[90:91]
	s_cbranch_vccnz .LBB0_219
	v_mov_b32_e32 v195, v191
	v_pk_add_f32 v[208:209], v[190:191], v[194:195]
	v_pk_mul_f32 v[210:211], v[190:191], v[194:195]
	v_mov_b32_e32 v184, v190
	v_mov_b32_e32 v209, v211
	v_pk_mul_f32 v[210:211], v[188:189], v[188:189]
	v_mov_b32_e32 v185, v194
	v_pk_add_f32 v[206:207], v[186:187], v[188:189]
	v_pk_fma_f32 v[210:211], v[186:187], v[186:187], v[210:211]
	v_mul_f32_e32 v154, v184, v184
	v_pk_add_f32 v[210:211], v[210:211], v[210:211] op_sel_hi:[0,1]
	v_pk_fma_f32 v[184:185], v[184:185], v[184:185], v[154:155] op_sel_hi:[1,1,0]
	v_mul_f32_e32 v154, v192, v192
	v_pk_add_f32 v[206:207], v[206:207], v[206:207] op_sel:[0,1] op_sel_hi:[1,0]
	v_mov_b32_e32 v193, v211
	v_mov_b32_e32 v184, v191
	v_mov_b32_e32 v207, v154
	v_pk_add_f32 v[184:185], v[192:193], v[184:185]
	v_pk_add_f32 v[206:207], v[206:207], v[208:209]
	s_mov_b64 s[12:13], 0
	v_pk_add_f32 v[184:185], v[206:207], v[184:185]
	s_branch .LBB0_220

; __device__ __forceinline__ f32x2 gelu_pk(f32x2 v) {
;     const f32x2 av = __builtin_elementwise_abs(v), d = av * 0.2316418882f + 1.0f;
;     f32x2 t; t.x = __builtin_amdgcn_rcpf(d.x); t.y = __builtin_amdgcn_rcpf(d.y);
;     f32x2 q = t * 0.5307027145f + (-0.7265760135f); q = q * t + 0.7107068705f; q = q * t + (-0.142248368f); q = q * t + 0.127414796f; q = q * t;
;     const f32x2 s = (v * v) * (-0.72134752044f);
;     f32x2 e; e.x = __builtin_amdgcn_exp2f(s.x); e.y = __builtin_amdgcn_exp2f(s.y);
;     const f32x2 m = v * (q * e), r = v - m;
;     f32x2 o; o.x = v.x < 0.f ? m.x : r.x; o.y = v.y < 0.f ? m.y : r.y; return o;
; }
;     __device__ __forceinline__ void operator()(const f32x4 (&acc)[2][2][4][2], const Unit& u, int wr, int wc, int fr, int fq) const {
;     ...
;                         f32x2 a = gelu_pk((f32x2){v0[0], v0[1]}), b = gelu_pk((f32x2){v0[2], v0[3]}), c = gelu_pk((f32x2){v1[0], v1[1]}), d = gelu_pk((f32x2){v1[2], v1[3]});
;                         v0 = (f32x4){a.x, a.y, b.x, b.y}; v1 = (f32x4){c.x, c.y, d.x, d.y};
;                         if (pn >= 9) { const float t1 = (v0[0] + v0[1]) + (v0[2] + v0[3]) + (v1[0] + v1[1]) + (v1[2] + v1[3]);
;                             const float t2 = (v0[0] * v0[0] + v0[1] * v0[1]) + (v0[2] * v0[2] + v0[3] * v0[3]) + (v1[0] * v1[0] + v1[1] * v1[1]) + (v1[2] * v1[2] + v1[3] * v1[3]);
;                             if (bj == 0) { ps = t1; pss = t2; } else { ps += t1; pss += t2; } }
.LBB0_227:
	s_andn2_b64 vcc, exec, s[38:39]
	v_mov_b64_e32 v[190:191], v[184:185]
	s_cbranch_vccnz .LBB0_230
	v_mov_b64_e32 v[254:255], s[66:67]
	v_fma_f32 v248, |v118|, s62, 1.0
	v_fma_f32 v249, |v119|, s62, 1.0
	v_pk_mul_f32 v[252:253], v[118:119], v[118:119]
	v_rcp_f32_e32 v248, v248
	v_rcp_f32_e32 v249, v249
	v_pk_mul_f32 v[252:253], v[252:253], s[74:75] op_sel_hi:[1,0]
	v_pk_fma_f32 v[250:251], v[248:249], s[64:65], v[254:255] op_sel_hi:[1,0,0]
	v_exp_f32_e32 v252, v252
	v_exp_f32_e32 v253, v253
	v_pk_fma_f32 v[250:251], v[248:249], v[250:251], s[68:69] op_sel_hi:[1,1,0]
	v_pk_fma_f32 v[250:251], v[248:249], v[250:251], s[70:71] op_sel_hi:[1,1,0]
	v_pk_fma_f32 v[250:251], v[248:249], v[250:251], s[72:73] op_sel_hi:[1,1,0]
	v_pk_mul_f32 v[250:251], v[248:249], v[250:251]
	v_pk_fma_f32 v[250:251], v[250:251], v[252:253], 0.5 op_sel_hi:[1,1,0] neg_lo:[1,0,0] neg_hi:[1,0,0]
	v_pk_mul_f32 v[248:249], v[118:119], 0.5 op_sel_hi:[1,0]
	v_fma_f32 v124, |v118|, v250, v248
	v_fma_f32 v126, |v119|, v251, v249
	v_fma_f32 v248, |v120|, s62, 1.0
	v_fma_f32 v249, |v121|, s62, 1.0
	v_pk_mul_f32 v[252:253], v[120:121], v[120:121]
	v_rcp_f32_e32 v248, v248
	v_rcp_f32_e32 v249, v249
	v_pk_mul_f32 v[252:253], v[252:253], s[74:75] op_sel_hi:[1,0]
	v_pk_fma_f32 v[250:251], v[248:249], s[64:65], v[254:255] op_sel_hi:[1,0,0]
	v_exp_f32_e32 v252, v252
	v_exp_f32_e32 v253, v253
	v_pk_fma_f32 v[250:251], v[248:249], v[250:251], s[68:69] op_sel_hi:[1,1,0]
	v_pk_fma_f32 v[250:251], v[248:249], v[250:251], s[70:71] op_sel_hi:[1,1,0]
	v_pk_fma_f32 v[250:251], v[248:249], v[250:251], s[72:73] op_sel_hi:[1,1,0]
	v_pk_mul_f32 v[250:251], v[248:249], v[250:251]
	v_pk_fma_f32 v[250:251], v[250:251], v[252:253], 0.5 op_sel_hi:[1,1,0] neg_lo:[1,0,0] neg_hi:[1,0,0]
	v_pk_mul_f32 v[248:249], v[120:121], 0.5 op_sel_hi:[1,0]
	v_fma_f32 v125, |v120|, v250, v248
	v_fma_f32 v127, |v121|, v251, v249
	v_fma_f32 v248, |v116|, s62, 1.0
	v_fma_f32 v249, |v117|, s62, 1.0
	v_pk_mul_f32 v[252:253], v[116:117], v[116:117]
	v_rcp_f32_e32 v248, v248
	v_rcp_f32_e32 v249, v249
	v_pk_mul_f32 v[252:253], v[252:253], s[74:75] op_sel_hi:[1,0]
	v_pk_fma_f32 v[250:251], v[248:249], s[64:65], v[254:255] op_sel_hi:[1,0,0]
	v_exp_f32_e32 v252, v252
	v_exp_f32_e32 v253, v253
	v_pk_fma_f32 v[250:251], v[248:249], v[250:251], s[68:69] op_sel_hi:[1,1,0]
	v_pk_fma_f32 v[250:251], v[248:249], v[250:251], s[70:71] op_sel_hi:[1,1,0]
	v_pk_fma_f32 v[250:251], v[248:249], v[250:251], s[72:73] op_sel_hi:[1,1,0]
	v_pk_mul_f32 v[250:251], v[248:249], v[250:251]
	v_pk_fma_f32 v[250:251], v[250:251], v[252:253], 0.5 op_sel_hi:[1,1,0] neg_lo:[1,0,0] neg_hi:[1,0,0]
	v_pk_mul_f32 v[248:249], v[116:117], 0.5 op_sel_hi:[1,0]
	v_fma_f32 v186, |v116|, v250, v248
	v_fma_f32 v129, |v117|, v251, v249
	v_fma_f32 v248, |v114|, s62, 1.0
	v_fma_f32 v249, |v115|, s62, 1.0
	v_pk_mul_f32 v[252:253], v[114:115], v[114:115]
	v_rcp_f32_e32 v248, v248
	v_rcp_f32_e32 v249, v249
	v_pk_mul_f32 v[252:253], v[252:253], s[74:75] op_sel_hi:[1,0]
	v_pk_fma_f32 v[250:251], v[248:249], s[64:65], v[254:255] op_sel_hi:[1,0,0]
	v_exp_f32_e32 v252, v252
	v_exp_f32_e32 v253, v253
	v_pk_fma_f32 v[250:251], v[248:249], v[250:251], s[68:69] op_sel_hi:[1,1,0]
	v_pk_fma_f32 v[250:251], v[248:249], v[250:251], s[70:71] op_sel_hi:[1,1,0]
	v_pk_fma_f32 v[250:251], v[248:249], v[250:251], s[72:73] op_sel_hi:[1,1,0]
	v_pk_mul_f32 v[250:251], v[248:249], v[250:251]
	v_pk_fma_f32 v[250:251], v[250:251], v[252:253], 0.5 op_sel_hi:[1,1,0] neg_lo:[1,0,0] neg_hi:[1,0,0]
	v_pk_mul_f32 v[248:249], v[114:115], 0.5 op_sel_hi:[1,0]
	v_fma_f32 v128, |v114|, v250, v248
	v_fma_f32 v188, |v115|, v251, v249
	s_andn2_b64 vcc, exec, s[90:91]
	v_mov_b64_e32 v[190:191], v[184:185]
	s_cbranch_vccnz .LBB0_230
	v_mov_b32_e32 v189, v129
	v_pk_add_f32 v[194:195], v[128:129], v[188:189]
	v_pk_mul_f32 v[206:207], v[128:129], v[188:189]
	v_mov_b32_e32 v190, v128
	v_mov_b32_e32 v195, v207
	v_pk_mul_f32 v[206:207], v[126:127], v[126:127]
	v_mov_b32_e32 v191, v188
	v_pk_add_f32 v[192:193], v[124:125], v[126:127]
	v_pk_fma_f32 v[206:207], v[124:125], v[124:125], v[206:207]
	v_mul_f32_e32 v154, v190, v190
	v_pk_add_f32 v[206:207], v[206:207], v[206:207] op_sel_hi:[0,1]
	v_pk_fma_f32 v[190:191], v[190:191], v[190:191], v[154:155] op_sel_hi:[1,1,0]
	v_mul_f32_e32 v154, v186, v186
	v_pk_add_f32 v[192:193], v[192:193], v[192:193] op_sel:[0,1] op_sel_hi:[1,0]
	v_mov_b32_e32 v187, v207
	v_mov_b32_e32 v190, v129
	v_mov_b32_e32 v193, v154
	v_pk_add_f32 v[190:191], v[186:187], v[190:191]
	v_pk_add_f32 v[192:193], v[192:193], v[194:195]
	s_nop 0
	v_pk_add_f32 v[190:191], v[192:193], v[190:191]
	s_nop 0
	v_pk_add_f32 v[190:191], v[190:191], v[184:185]

; __device__ __forceinline__ f32x2 gelu_pk(f32x2 v) {
;     const f32x2 av = __builtin_elementwise_abs(v), d = av * 0.2316418882f + 1.0f;
;     f32x2 t; t.x = __builtin_amdgcn_rcpf(d.x); t.y = __builtin_amdgcn_rcpf(d.y);
;     f32x2 q = t * 0.5307027145f + (-0.7265760135f); q = q * t + 0.7107068705f; q = q * t + (-0.142248368f); q = q * t + 0.127414796f; q = q * t;
;     const f32x2 s = (v * v) * (-0.72134752044f);
;     f32x2 e; e.x = __builtin_amdgcn_exp2f(s.x); e.y = __builtin_amdgcn_exp2f(s.y);
;     const f32x2 m = v * (q * e), r = v - m;
;     f32x2 o; o.x = v.x < 0.f ? m.x : r.x; o.y = v.y < 0.f ? m.y : r.y; return o;
; }
;     __device__ __forceinline__ void operator()(const f32x4 (&acc)[2][2][4][2], const Unit& u, int wr, int wc, int fr, int fq) const {
;     ...
;                         f32x2 a = gelu_pk((f32x2){v0[0], v0[1]}), b = gelu_pk((f32x2){v0[2], v0[3]}), c = gelu_pk((f32x2){v1[0], v1[1]}), d = gelu_pk((f32x2){v1[2], v1[3]});
;                         v0 = (f32x4){a.x, a.y, b.x, b.y}; v1 = (f32x4){c.x, c.y, d.x, d.y};
;                         if (pn >= 9) { const float t1 = (v0[0] + v0[1]) + (v0[2] + v0[3]) + (v1[0] + v1[1]) + (v1[2] + v1[3]);
;                             const float t2 = (v0[0] * v0[0] + v0[1] * v0[1]) + (v0[2] * v0[2] + v0[3] * v0[3]) + (v1[0] * v1[0] + v1[1] * v1[1]) + (v1[2] * v1[2] + v1[3] * v1[3]);
;                             if (bj == 0) { ps = t1; pss = t2; } else { ps += t1; pss += t2; } }
.LBB0_244:
	s_andn2_b64 vcc, exec, s[20:21]
	s_cbranch_vccnz .LBB0_247
	v_mov_b64_e32 v[254:255], s[66:67]
	v_fma_f32 v248, |v110|, s62, 1.0
	v_fma_f32 v249, |v111|, s62, 1.0
	v_pk_mul_f32 v[252:253], v[110:111], v[110:111]
	v_rcp_f32_e32 v248, v248
	v_rcp_f32_e32 v249, v249
	v_pk_mul_f32 v[252:253], v[252:253], s[74:75] op_sel_hi:[1,0]
	v_pk_fma_f32 v[250:251], v[248:249], s[64:65], v[254:255] op_sel_hi:[1,0,0]
	v_exp_f32_e32 v252, v252
	v_exp_f32_e32 v253, v253
	v_pk_fma_f32 v[250:251], v[248:249], v[250:251], s[68:69] op_sel_hi:[1,1,0]
	v_pk_fma_f32 v[250:251], v[248:249], v[250:251], s[70:71] op_sel_hi:[1,1,0]
	v_pk_fma_f32 v[250:251], v[248:249], v[250:251], s[72:73] op_sel_hi:[1,1,0]
	v_pk_mul_f32 v[250:251], v[248:249], v[250:251]
	v_pk_fma_f32 v[250:251], v[250:251], v[252:253], 0.5 op_sel_hi:[1,1,0] neg_lo:[1,0,0] neg_hi:[1,0,0]
	v_pk_mul_f32 v[248:249], v[110:111], 0.5 op_sel_hi:[1,0]
	v_fma_f32 v134, |v110|, v250, v248
	v_fma_f32 v136, |v111|, v251, v249
	v_fma_f32 v248, |v112|, s62, 1.0
	v_fma_f32 v249, |v113|, s62, 1.0
	v_pk_mul_f32 v[252:253], v[112:113], v[112:113]
	v_rcp_f32_e32 v248, v248
	v_rcp_f32_e32 v249, v249
	v_pk_mul_f32 v[252:253], v[252:253], s[74:75] op_sel_hi:[1,0]
	v_pk_fma_f32 v[250:251], v[248:249], s[64:65], v[254:255] op_sel_hi:[1,0,0]
	v_exp_f32_e32 v252, v252
	v_exp_f32_e32 v253, v253
	v_pk_fma_f32 v[250:251], v[248:249], v[250:251], s[68:69] op_sel_hi:[1,1,0]
	v_pk_fma_f32 v[250:251], v[248:249], v[250:251], s[70:71] op_sel_hi:[1,1,0]
	v_pk_fma_f32 v[250:251], v[248:249], v[250:251], s[72:73] op_sel_hi:[1,1,0]
	v_pk_mul_f32 v[250:251], v[248:249], v[250:251]
	v_pk_fma_f32 v[250:251], v[250:251], v[252:253], 0.5 op_sel_hi:[1,1,0] neg_lo:[1,0,0] neg_hi:[1,0,0]
	v_pk_mul_f32 v[248:249], v[112:113], 0.5 op_sel_hi:[1,0]
	v_fma_f32 v135, |v112|, v250, v248
	v_fma_f32 v137, |v113|, v251, v249
	v_fma_f32 v248, |v108|, s62, 1.0
	v_fma_f32 v249, |v109|, s62, 1.0
	v_pk_mul_f32 v[252:253], v[108:109], v[108:109]
	v_rcp_f32_e32 v248, v248
	v_rcp_f32_e32 v249, v249
	v_pk_mul_f32 v[252:253], v[252:253], s[74:75] op_sel_hi:[1,0]
	v_pk_fma_f32 v[250:251], v[248:249], s[64:65], v[254:255] op_sel_hi:[1,0,0]
	v_exp_f32_e32 v252, v252
	v_exp_f32_e32 v253, v253
	v_pk_fma_f32 v[250:251], v[248:249], v[250:251], s[68:69] op_sel_hi:[1,1,0]
	v_pk_fma_f32 v[250:251], v[248:249], v[250:251], s[70:71] op_sel_hi:[1,1,0]
	v_pk_fma_f32 v[250:251], v[248:249], v[250:251], s[72:73] op_sel_hi:[1,1,0]
	v_pk_mul_f32 v[250:251], v[248:249], v[250:251]
	v_pk_fma_f32 v[250:251], v[250:251], v[252:253], 0.5 op_sel_hi:[1,1,0] neg_lo:[1,0,0] neg_hi:[1,0,0]
	v_pk_mul_f32 v[248:249], v[108:109], 0.5 op_sel_hi:[1,0]
	v_fma_f32 v140, |v108|, v250, v248
	v_fma_f32 v139, |v109|, v251, v249
	v_fma_f32 v248, |v106|, s62, 1.0
	v_fma_f32 v249, |v107|, s62, 1.0
	v_pk_mul_f32 v[252:253], v[106:107], v[106:107]
	v_rcp_f32_e32 v248, v248
	v_rcp_f32_e32 v249, v249
	v_pk_mul_f32 v[252:253], v[252:253], s[74:75] op_sel_hi:[1,0]
	v_pk_fma_f32 v[250:251], v[248:249], s[64:65], v[254:255] op_sel_hi:[1,0,0]
	v_exp_f32_e32 v252, v252
	v_exp_f32_e32 v253, v253
	v_pk_fma_f32 v[250:251], v[248:249], v[250:251], s[68:69] op_sel_hi:[1,1,0]
	v_pk_fma_f32 v[250:251], v[248:249], v[250:251], s[70:71] op_sel_hi:[1,1,0]
	v_pk_fma_f32 v[250:251], v[248:249], v[250:251], s[72:73] op_sel_hi:[1,1,0]
	v_pk_mul_f32 v[250:251], v[248:249], v[250:251]
	v_pk_fma_f32 v[250:251], v[250:251], v[252:253], 0.5 op_sel_hi:[1,1,0] neg_lo:[1,0,0] neg_hi:[1,0,0]
	v_pk_mul_f32 v[248:249], v[106:107], 0.5 op_sel_hi:[1,0]
	v_fma_f32 v138, |v106|, v250, v248
	v_fma_f32 v142, |v107|, v251, v249
	s_andn2_b64 vcc, exec, s[90:91]
	s_cbranch_vccnz .LBB0_247
	v_mov_b32_e32 v143, v139
	v_pk_add_f32 v[184:185], v[138:139], v[142:143]
	v_pk_mul_f32 v[186:187], v[138:139], v[142:143]
	v_mov_b32_e32 v132, v138
	v_mov_b32_e32 v185, v187
	v_pk_mul_f32 v[186:187], v[136:137], v[136:137]
	v_mov_b32_e32 v133, v142
	v_pk_add_f32 v[144:145], v[134:135], v[136:137]
	v_pk_fma_f32 v[186:187], v[134:135], v[134:135], v[186:187]
	v_mul_f32_e32 v154, v132, v132
	v_pk_add_f32 v[186:187], v[186:187], v[186:187] op_sel_hi:[0,1]
	v_pk_fma_f32 v[132:133], v[132:133], v[132:133], v[154:155] op_sel_hi:[1,1,0]
	v_mul_f32_e32 v143, v140, v140
	v_pk_add_f32 v[144:145], v[144:145], v[144:145] op_sel:[0,1] op_sel_hi:[1,0]
	v_mov_b32_e32 v141, v187
	v_mov_b32_e32 v132, v139
	v_mov_b32_e32 v145, v143
	v_pk_add_f32 v[132:133], v[140:141], v[132:133]
	v_pk_add_f32 v[144:145], v[144:145], v[184:185]
	s_nop 0
	v_pk_add_f32 v[132:133], v[144:145], v[132:133]
	s_branch .LBB0_248

; __device__ __forceinline__ f32x2 gelu_pk(f32x2 v) {
;     const f32x2 av = __builtin_elementwise_abs(v), d = av * 0.2316418882f + 1.0f;
;     f32x2 t; t.x = __builtin_amdgcn_rcpf(d.x); t.y = __builtin_amdgcn_rcpf(d.y);
;     f32x2 q = t * 0.5307027145f + (-0.7265760135f); q = q * t + 0.7107068705f; q = q * t + (-0.142248368f); q = q * t + 0.127414796f; q = q * t;
;     const f32x2 s = (v * v) * (-0.72134752044f);
;     f32x2 e; e.x = __builtin_amdgcn_exp2f(s.x); e.y = __builtin_amdgcn_exp2f(s.y);
;     const f32x2 m = v * (q * e), r = v - m;
;     f32x2 o; o.x = v.x < 0.f ? m.x : r.x; o.y = v.y < 0.f ? m.y : r.y; return o;
; }
;     __device__ __forceinline__ void operator()(const f32x4 (&acc)[2][2][4][2], const Unit& u, int wr, int wc, int fr, int fq) const {
;     ...
;                         f32x2 a = gelu_pk((f32x2){v0[0], v0[1]}), b = gelu_pk((f32x2){v0[2], v0[3]}), c = gelu_pk((f32x2){v1[0], v1[1]}), d = gelu_pk((f32x2){v1[2], v1[3]});
;                         v0 = (f32x4){a.x, a.y, b.x, b.y}; v1 = (f32x4){c.x, c.y, d.x, d.y};
;                         if (pn >= 9) { const float t1 = (v0[0] + v0[1]) + (v0[2] + v0[3]) + (v1[0] + v1[1]) + (v1[2] + v1[3]);
;                             const float t2 = (v0[0] * v0[0] + v0[1] * v0[1]) + (v0[2] * v0[2] + v0[3] * v0[3]) + (v1[0] * v1[0] + v1[1] * v1[1]) + (v1[2] * v1[2] + v1[3] * v1[3]);
;                             if (bj == 0) { ps = t1; pss = t2; } else { ps += t1; pss += t2; } }
.LBB0_256:
	s_andn2_b64 vcc, exec, s[20:21]
	v_mov_b64_e32 v[138:139], v[132:133]
	s_cbranch_vccnz .LBB0_259
	v_mov_b64_e32 v[254:255], s[66:67]
	v_fma_f32 v248, |v102|, s62, 1.0
	v_fma_f32 v249, |v103|, s62, 1.0
	v_pk_mul_f32 v[252:253], v[102:103], v[102:103]
	v_rcp_f32_e32 v248, v248
	v_rcp_f32_e32 v249, v249
	v_pk_mul_f32 v[252:253], v[252:253], s[74:75] op_sel_hi:[1,0]
	v_pk_fma_f32 v[250:251], v[248:249], s[64:65], v[254:255] op_sel_hi:[1,0,0]
	v_exp_f32_e32 v252, v252
	v_exp_f32_e32 v253, v253
	v_pk_fma_f32 v[250:251], v[248:249], v[250:251], s[68:69] op_sel_hi:[1,1,0]
	v_pk_fma_f32 v[250:251], v[248:249], v[250:251], s[70:71] op_sel_hi:[1,1,0]
	v_pk_fma_f32 v[250:251], v[248:249], v[250:251], s[72:73] op_sel_hi:[1,1,0]
	v_pk_mul_f32 v[250:251], v[248:249], v[250:251]
	v_pk_fma_f32 v[250:251], v[250:251], v[252:253], 0.5 op_sel_hi:[1,1,0] neg_lo:[1,0,0] neg_hi:[1,0,0]
	v_pk_mul_f32 v[248:249], v[102:103], 0.5 op_sel_hi:[1,0]
	v_fma_f32 v108, |v102|, v250, v248
	v_fma_f32 v110, |v103|, v251, v249
	v_fma_f32 v248, |v104|, s62, 1.0
	v_fma_f32 v249, |v105|, s62, 1.0
	v_pk_mul_f32 v[252:253], v[104:105], v[104:105]
	v_rcp_f32_e32 v248, v248
	v_rcp_f32_e32 v249, v249
	v_pk_mul_f32 v[252:253], v[252:253], s[74:75] op_sel_hi:[1,0]
	v_pk_fma_f32 v[250:251], v[248:249], s[64:65], v[254:255] op_sel_hi:[1,0,0]
	v_exp_f32_e32 v252, v252
	v_exp_f32_e32 v253, v253
	v_pk_fma_f32 v[250:251], v[248:249], v[250:251], s[68:69] op_sel_hi:[1,1,0]
	v_pk_fma_f32 v[250:251], v[248:249], v[250:251], s[70:71] op_sel_hi:[1,1,0]
	v_pk_fma_f32 v[250:251], v[248:249], v[250:251], s[72:73] op_sel_hi:[1,1,0]
	v_pk_mul_f32 v[250:251], v[248:249], v[250:251]
	v_pk_fma_f32 v[250:251], v[250:251], v[252:253], 0.5 op_sel_hi:[1,1,0] neg_lo:[1,0,0] neg_hi:[1,0,0]
	v_pk_mul_f32 v[248:249], v[104:105], 0.5 op_sel_hi:[1,0]
	v_fma_f32 v109, |v104|, v250, v248
	v_fma_f32 v111, |v105|, v251, v249
	v_fma_f32 v248, |v100|, s62, 1.0
	v_fma_f32 v249, |v101|, s62, 1.0
	v_pk_mul_f32 v[252:253], v[100:101], v[100:101]
	v_rcp_f32_e32 v248, v248
	v_rcp_f32_e32 v249, v249
	v_pk_mul_f32 v[252:253], v[252:253], s[74:75] op_sel_hi:[1,0]
	v_pk_fma_f32 v[250:251], v[248:249], s[64:65], v[254:255] op_sel_hi:[1,0,0]
	v_exp_f32_e32 v252, v252
	v_exp_f32_e32 v253, v253
	v_pk_fma_f32 v[250:251], v[248:249], v[250:251], s[68:69] op_sel_hi:[1,1,0]
	v_pk_fma_f32 v[250:251], v[248:249], v[250:251], s[70:71] op_sel_hi:[1,1,0]
	v_pk_fma_f32 v[250:251], v[248:249], v[250:251], s[72:73] op_sel_hi:[1,1,0]
	v_pk_mul_f32 v[250:251], v[248:249], v[250:251]
	v_pk_fma_f32 v[250:251], v[250:251], v[252:253], 0.5 op_sel_hi:[1,1,0] neg_lo:[1,0,0] neg_hi:[1,0,0]
	v_pk_mul_f32 v[248:249], v[100:101], 0.5 op_sel_hi:[1,0]
	v_fma_f32 v134, |v100|, v250, v248
	v_fma_f32 v113, |v101|, v251, v249
	v_fma_f32 v248, |v98|, s62, 1.0
	v_fma_f32 v249, |v99|, s62, 1.0
	v_pk_mul_f32 v[252:253], v[98:99], v[98:99]
	v_rcp_f32_e32 v248, v248
	v_rcp_f32_e32 v249, v249
	v_pk_mul_f32 v[252:253], v[252:253], s[74:75] op_sel_hi:[1,0]
	v_pk_fma_f32 v[250:251], v[248:249], s[64:65], v[254:255] op_sel_hi:[1,0,0]
	v_exp_f32_e32 v252, v252
	v_exp_f32_e32 v253, v253
	v_pk_fma_f32 v[250:251], v[248:249], v[250:251], s[68:69] op_sel_hi:[1,1,0]
	v_pk_fma_f32 v[250:251], v[248:249], v[250:251], s[70:71] op_sel_hi:[1,1,0]
	v_pk_fma_f32 v[250:251], v[248:249], v[250:251], s[72:73] op_sel_hi:[1,1,0]
	v_pk_mul_f32 v[250:251], v[248:249], v[250:251]
	v_pk_fma_f32 v[250:251], v[250:251], v[252:253], 0.5 op_sel_hi:[1,1,0] neg_lo:[1,0,0] neg_hi:[1,0,0]
	v_pk_mul_f32 v[248:249], v[98:99], 0.5 op_sel_hi:[1,0]
	v_fma_f32 v112, |v98|, v250, v248
	v_fma_f32 v136, |v99|, v251, v249
	s_andn2_b64 vcc, exec, s[90:91]
	v_mov_b64_e32 v[138:139], v[132:133]
	s_cbranch_vccnz .LBB0_259
	v_mov_b32_e32 v137, v113
	v_pk_add_f32 v[142:143], v[112:113], v[136:137]
	v_pk_mul_f32 v[144:145], v[112:113], v[136:137]
	v_mov_b32_e32 v138, v112
	v_mov_b32_e32 v143, v145
	v_pk_mul_f32 v[144:145], v[110:111], v[110:111]
	v_mov_b32_e32 v139, v136
	v_pk_fma_f32 v[144:145], v[108:109], v[108:109], v[144:145]
	v_pk_add_f32 v[140:141], v[108:109], v[110:111]
	v_pk_add_f32 v[144:145], v[144:145], v[144:145] op_sel_hi:[0,1]
	v_mul_f32_e32 v144, v138, v138
	v_pk_fma_f32 v[138:139], v[138:139], v[138:139], v[144:145] op_sel_hi:[1,1,0]
	v_mul_f32_e32 v137, v134, v134
	v_pk_add_f32 v[140:141], v[140:141], v[140:141] op_sel:[0,1] op_sel_hi:[1,0]
	v_mov_b32_e32 v135, v145
	v_mov_b32_e32 v138, v113
	v_mov_b32_e32 v141, v137
	v_pk_add_f32 v[138:139], v[134:135], v[138:139]
	v_pk_add_f32 v[140:141], v[140:141], v[142:143]
	s_nop 0
	v_pk_add_f32 v[138:139], v[140:141], v[138:139]
	s_nop 0
	v_pk_add_f32 v[138:139], v[138:139], v[132:133]

; __device__ __forceinline__ f32x2 gelu_pk(f32x2 v) {
;     const f32x2 av = __builtin_elementwise_abs(v), d = av * 0.2316418882f + 1.0f;
;     f32x2 t; t.x = __builtin_amdgcn_rcpf(d.x); t.y = __builtin_amdgcn_rcpf(d.y);
;     f32x2 q = t * 0.5307027145f + (-0.7265760135f); q = q * t + 0.7107068705f; q = q * t + (-0.142248368f); q = q * t + 0.127414796f; q = q * t;
;     const f32x2 s = (v * v) * (-0.72134752044f);
;     f32x2 e; e.x = __builtin_amdgcn_exp2f(s.x); e.y = __builtin_amdgcn_exp2f(s.y);
;     const f32x2 m = v * (q * e), r = v - m;
;     f32x2 o; o.x = v.x < 0.f ? m.x : r.x; o.y = v.y < 0.f ? m.y : r.y; return o;
; }
;     __device__ __forceinline__ void operator()(const f32x4 (&acc)[2][2][4][2], const Unit& u, int wr, int wc, int fr, int fq) const {
;     ...
;                         f32x2 a = gelu_pk((f32x2){v0[0], v0[1]}), b = gelu_pk((f32x2){v0[2], v0[3]}), c = gelu_pk((f32x2){v1[0], v1[1]}), d = gelu_pk((f32x2){v1[2], v1[3]});
;                         v0 = (f32x4){a.x, a.y, b.x, b.y}; v1 = (f32x4){c.x, c.y, d.x, d.y};
;                         if (pn >= 9) { const float t1 = (v0[0] + v0[1]) + (v0[2] + v0[3]) + (v1[0] + v1[1]) + (v1[2] + v1[3]);
;                             const float t2 = (v0[0] * v0[0] + v0[1] * v0[1]) + (v0[2] * v0[2] + v0[3] * v0[3]) + (v1[0] * v1[0] + v1[1] * v1[1]) + (v1[2] * v1[2] + v1[3] * v1[3]);
;                             if (bj == 0) { ps = t1; pss = t2; } else { ps += t1; pss += t2; } }
.LBB0_273:
	s_andn2_b64 vcc, exec, s[20:21]
	s_cbranch_vccnz .LBB0_431
	s_waitcnt vmcnt(4)
	s_waitcnt vmcnt(3)
	s_waitcnt vmcnt(2)
	v_mov_b64_e32 v[254:255], s[66:67]
	v_fma_f32 v248, |v94|, s62, 1.0
	v_fma_f32 v249, |v95|, s62, 1.0
	v_pk_mul_f32 v[252:253], v[94:95], v[94:95]
	v_rcp_f32_e32 v248, v248
	v_rcp_f32_e32 v249, v249
	v_pk_mul_f32 v[252:253], v[252:253], s[74:75] op_sel_hi:[1,0]
	v_pk_fma_f32 v[250:251], v[248:249], s[64:65], v[254:255] op_sel_hi:[1,0,0]
	v_exp_f32_e32 v252, v252
	v_exp_f32_e32 v253, v253
	v_pk_fma_f32 v[250:251], v[248:249], v[250:251], s[68:69] op_sel_hi:[1,1,0]
	v_pk_fma_f32 v[250:251], v[248:249], v[250:251], s[70:71] op_sel_hi:[1,1,0]
	v_pk_fma_f32 v[250:251], v[248:249], v[250:251], s[72:73] op_sel_hi:[1,1,0]
	v_pk_mul_f32 v[250:251], v[248:249], v[250:251]
	v_pk_fma_f32 v[250:251], v[250:251], v[252:253], 0.5 op_sel_hi:[1,1,0] neg_lo:[1,0,0] neg_hi:[1,0,0]
	v_pk_mul_f32 v[248:249], v[94:95], 0.5 op_sel_hi:[1,0]
	v_fma_f32 v118, |v94|, v250, v248
	v_fma_f32 v120, |v95|, v251, v249
	v_fma_f32 v248, |v96|, s62, 1.0
	v_fma_f32 v249, |v97|, s62, 1.0
	v_pk_mul_f32 v[252:253], v[96:97], v[96:97]
	v_rcp_f32_e32 v248, v248
	v_rcp_f32_e32 v249, v249
	v_pk_mul_f32 v[252:253], v[252:253], s[74:75] op_sel_hi:[1,0]
	v_pk_fma_f32 v[250:251], v[248:249], s[64:65], v[254:255] op_sel_hi:[1,0,0]
	v_exp_f32_e32 v252, v252
	v_exp_f32_e32 v253, v253
	v_pk_fma_f32 v[250:251], v[248:249], v[250:251], s[68:69] op_sel_hi:[1,1,0]
	v_pk_fma_f32 v[250:251], v[248:249], v[250:251], s[70:71] op_sel_hi:[1,1,0]
	v_pk_fma_f32 v[250:251], v[248:249], v[250:251], s[72:73] op_sel_hi:[1,1,0]
	v_pk_mul_f32 v[250:251], v[248:249], v[250:251]
	v_pk_fma_f32 v[250:251], v[250:251], v[252:253], 0.5 op_sel_hi:[1,1,0] neg_lo:[1,0,0] neg_hi:[1,0,0]
	v_pk_mul_f32 v[248:249], v[96:97], 0.5 op_sel_hi:[1,0]
	v_fma_f32 v119, |v96|, v250, v248
	v_fma_f32 v121, |v97|, v251, v249
	v_fma_f32 v248, |v92|, s62, 1.0
	v_fma_f32 v249, |v93|, s62, 1.0
	v_pk_mul_f32 v[252:253], v[92:93], v[92:93]
	v_rcp_f32_e32 v248, v248
	v_rcp_f32_e32 v249, v249
	v_pk_mul_f32 v[252:253], v[252:253], s[74:75] op_sel_hi:[1,0]
	v_pk_fma_f32 v[250:251], v[248:249], s[64:65], v[254:255] op_sel_hi:[1,0,0]
	v_exp_f32_e32 v252, v252
	v_exp_f32_e32 v253, v253
	v_pk_fma_f32 v[250:251], v[248:249], v[250:251], s[68:69] op_sel_hi:[1,1,0]
	v_pk_fma_f32 v[250:251], v[248:249], v[250:251], s[70:71] op_sel_hi:[1,1,0]
	v_pk_fma_f32 v[250:251], v[248:249], v[250:251], s[72:73] op_sel_hi:[1,1,0]
	v_pk_mul_f32 v[250:251], v[248:249], v[250:251]
	v_pk_fma_f32 v[250:251], v[250:251], v[252:253], 0.5 op_sel_hi:[1,1,0] neg_lo:[1,0,0] neg_hi:[1,0,0]
	v_pk_mul_f32 v[248:249], v[92:93], 0.5 op_sel_hi:[1,0]
	v_fma_f32 v124, |v92|, v250, v248
	v_fma_f32 v123, |v93|, v251, v249
	v_fma_f32 v248, |v90|, s62, 1.0
	v_fma_f32 v249, |v91|, s62, 1.0
	v_pk_mul_f32 v[252:253], v[90:91], v[90:91]
	v_rcp_f32_e32 v248, v248
	v_rcp_f32_e32 v249, v249
	v_pk_mul_f32 v[252:253], v[252:253], s[74:75] op_sel_hi:[1,0]
	v_pk_fma_f32 v[250:251], v[248:249], s[64:65], v[254:255] op_sel_hi:[1,0,0]
	v_exp_f32_e32 v252, v252
	v_exp_f32_e32 v253, v253
	v_pk_fma_f32 v[250:251], v[248:249], v[250:251], s[68:69] op_sel_hi:[1,1,0]
	v_pk_fma_f32 v[250:251], v[248:249], v[250:251], s[70:71] op_sel_hi:[1,1,0]
	v_pk_fma_f32 v[250:251], v[248:249], v[250:251], s[72:73] op_sel_hi:[1,1,0]
	v_pk_mul_f32 v[250:251], v[248:249], v[250:251]
	v_pk_fma_f32 v[250:251], v[250:251], v[252:253], 0.5 op_sel_hi:[1,1,0] neg_lo:[1,0,0] neg_hi:[1,0,0]
	v_pk_mul_f32 v[248:249], v[90:91], 0.5 op_sel_hi:[1,0]
	v_fma_f32 v122, |v90|, v250, v248
	v_fma_f32 v126, |v91|, v251, v249
	s_andn2_b64 vcc, exec, s[90:91]
	s_cbranch_vccnz .LBB0_431
	v_mov_b32_e32 v127, v123
	v_pk_add_f32 v[130:131], v[122:123], v[126:127]
	v_pk_mul_f32 v[132:133], v[122:123], v[126:127]
	v_mov_b32_e32 v116, v122
	v_mov_b32_e32 v131, v133
	v_pk_mul_f32 v[132:133], v[120:121], v[120:121]
	v_mov_b32_e32 v117, v126
	v_pk_fma_f32 v[132:133], v[118:119], v[118:119], v[132:133]
	v_pk_add_f32 v[128:129], v[118:119], v[120:121]
	v_pk_add_f32 v[132:133], v[132:133], v[132:133] op_sel_hi:[0,1]
	v_mul_f32_e32 v132, v116, v116
	v_pk_fma_f32 v[116:117], v[116:117], v[116:117], v[132:133] op_sel_hi:[1,1,0]
	v_mul_f32_e32 v127, v124, v124
	v_pk_add_f32 v[128:129], v[128:129], v[128:129] op_sel:[0,1] op_sel_hi:[1,0]
	v_mov_b32_e32 v125, v133
	v_mov_b32_e32 v116, v123
	v_mov_b32_e32 v129, v127
	v_pk_add_f32 v[116:117], v[124:125], v[116:117]
	v_pk_add_f32 v[128:129], v[128:129], v[130:131]
	s_nop 0
	v_pk_add_f32 v[116:117], v[128:129], v[116:117]
	s_cbranch_execz .LBB0_277
	s_branch .LBB0_278

; __device__ __forceinline__ f32x2 gelu_pk(f32x2 v) {
;     const f32x2 av = __builtin_elementwise_abs(v), d = av * 0.2316418882f + 1.0f;
;     f32x2 t; t.x = __builtin_amdgcn_rcpf(d.x); t.y = __builtin_amdgcn_rcpf(d.y);
;     f32x2 q = t * 0.5307027145f + (-0.7265760135f); q = q * t + 0.7107068705f; q = q * t + (-0.142248368f); q = q * t + 0.127414796f; q = q * t;
;     const f32x2 s = (v * v) * (-0.72134752044f);
;     f32x2 e; e.x = __builtin_amdgcn_exp2f(s.x); e.y = __builtin_amdgcn_exp2f(s.y);
;     const f32x2 m = v * (q * e), r = v - m;
;     f32x2 o; o.x = v.x < 0.f ? m.x : r.x; o.y = v.y < 0.f ? m.y : r.y; return o;
; }
;     __device__ __forceinline__ void operator()(const f32x4 (&acc)[2][2][4][2], const Unit& u, int wr, int wc, int fr, int fq) const {
;     ...
;                         f32x2 a = gelu_pk((f32x2){v0[0], v0[1]}), b = gelu_pk((f32x2){v0[2], v0[3]}), c = gelu_pk((f32x2){v1[0], v1[1]}), d = gelu_pk((f32x2){v1[2], v1[3]});
;                         v0 = (f32x4){a.x, a.y, b.x, b.y}; v1 = (f32x4){c.x, c.y, d.x, d.y};
;                         if (pn >= 9) { const float t1 = (v0[0] + v0[1]) + (v0[2] + v0[3]) + (v1[0] + v1[1]) + (v1[2] + v1[3]);
;                             const float t2 = (v0[0] * v0[0] + v0[1] * v0[1]) + (v0[2] * v0[2] + v0[3] * v0[3]) + (v1[0] * v1[0] + v1[1] * v1[1]) + (v1[2] * v1[2] + v1[3] * v1[3]);
;                             if (bj == 0) { ps = t1; pss = t2; } else { ps += t1; pss += t2; } }
.LBB0_283:
	s_andn2_b64 vcc, exec, s[20:21]
	v_mov_b64_e32 v[122:123], v[116:117]
	s_cbranch_vccnz .LBB0_286
	v_mov_b64_e32 v[254:255], s[66:67]
	v_fma_f32 v248, |v86|, s62, 1.0
	v_fma_f32 v249, |v87|, s62, 1.0
	v_pk_mul_f32 v[252:253], v[86:87], v[86:87]
	v_rcp_f32_e32 v248, v248
	v_rcp_f32_e32 v249, v249
	v_pk_mul_f32 v[252:253], v[252:253], s[74:75] op_sel_hi:[1,0]
	v_pk_fma_f32 v[250:251], v[248:249], s[64:65], v[254:255] op_sel_hi:[1,0,0]
	v_exp_f32_e32 v252, v252
	v_exp_f32_e32 v253, v253
	v_pk_fma_f32 v[250:251], v[248:249], v[250:251], s[68:69] op_sel_hi:[1,1,0]
	v_pk_fma_f32 v[250:251], v[248:249], v[250:251], s[70:71] op_sel_hi:[1,1,0]
	v_pk_fma_f32 v[250:251], v[248:249], v[250:251], s[72:73] op_sel_hi:[1,1,0]
	v_pk_mul_f32 v[250:251], v[248:249], v[250:251]
	v_pk_fma_f32 v[250:251], v[250:251], v[252:253], 0.5 op_sel_hi:[1,1,0] neg_lo:[1,0,0] neg_hi:[1,0,0]
	v_pk_mul_f32 v[248:249], v[86:87], 0.5 op_sel_hi:[1,0]
	v_fma_f32 v92, |v86|, v250, v248
	v_fma_f32 v94, |v87|, v251, v249
	v_fma_f32 v248, |v88|, s62, 1.0
	v_fma_f32 v249, |v89|, s62, 1.0
	v_pk_mul_f32 v[252:253], v[88:89], v[88:89]
	v_rcp_f32_e32 v248, v248
	v_rcp_f32_e32 v249, v249
	v_pk_mul_f32 v[252:253], v[252:253], s[74:75] op_sel_hi:[1,0]
	v_pk_fma_f32 v[250:251], v[248:249], s[64:65], v[254:255] op_sel_hi:[1,0,0]
	v_exp_f32_e32 v252, v252
	v_exp_f32_e32 v253, v253
	v_pk_fma_f32 v[250:251], v[248:249], v[250:251], s[68:69] op_sel_hi:[1,1,0]
	v_pk_fma_f32 v[250:251], v[248:249], v[250:251], s[70:71] op_sel_hi:[1,1,0]
	v_pk_fma_f32 v[250:251], v[248:249], v[250:251], s[72:73] op_sel_hi:[1,1,0]
	v_pk_mul_f32 v[250:251], v[248:249], v[250:251]
	v_pk_fma_f32 v[250:251], v[250:251], v[252:253], 0.5 op_sel_hi:[1,1,0] neg_lo:[1,0,0] neg_hi:[1,0,0]
	v_pk_mul_f32 v[248:249], v[88:89], 0.5 op_sel_hi:[1,0]
	v_fma_f32 v93, |v88|, v250, v248
	v_fma_f32 v95, |v89|, v251, v249
	v_fma_f32 v248, |v84|, s62, 1.0
	v_fma_f32 v249, |v85|, s62, 1.0
	v_pk_mul_f32 v[252:253], v[84:85], v[84:85]
	v_rcp_f32_e32 v248, v248
	v_rcp_f32_e32 v249, v249
	v_pk_mul_f32 v[252:253], v[252:253], s[74:75] op_sel_hi:[1,0]
	v_pk_fma_f32 v[250:251], v[248:249], s[64:65], v[254:255] op_sel_hi:[1,0,0]
	v_exp_f32_e32 v252, v252
	v_exp_f32_e32 v253, v253
	v_pk_fma_f32 v[250:251], v[248:249], v[250:251], s[68:69] op_sel_hi:[1,1,0]
	v_pk_fma_f32 v[250:251], v[248:249], v[250:251], s[70:71] op_sel_hi:[1,1,0]
	v_pk_fma_f32 v[250:251], v[248:249], v[250:251], s[72:73] op_sel_hi:[1,1,0]
	v_pk_mul_f32 v[250:251], v[248:249], v[250:251]
	v_pk_fma_f32 v[250:251], v[250:251], v[252:253], 0.5 op_sel_hi:[1,1,0] neg_lo:[1,0,0] neg_hi:[1,0,0]
	v_pk_mul_f32 v[248:249], v[84:85], 0.5 op_sel_hi:[1,0]
	v_fma_f32 v118, |v84|, v250, v248
	v_fma_f32 v97, |v85|, v251, v249
	v_fma_f32 v248, |v82|, s62, 1.0
	v_fma_f32 v249, |v83|, s62, 1.0
	v_pk_mul_f32 v[252:253], v[82:83], v[82:83]
	v_rcp_f32_e32 v248, v248
	v_rcp_f32_e32 v249, v249
	v_pk_mul_f32 v[252:253], v[252:253], s[74:75] op_sel_hi:[1,0]
	v_pk_fma_f32 v[250:251], v[248:249], s[64:65], v[254:255] op_sel_hi:[1,0,0]
	v_exp_f32_e32 v252, v252
	v_exp_f32_e32 v253, v253
	v_pk_fma_f32 v[250:251], v[248:249], v[250:251], s[68:69] op_sel_hi:[1,1,0]
	v_pk_fma_f32 v[250:251], v[248:249], v[250:251], s[70:71] op_sel_hi:[1,1,0]
	v_pk_fma_f32 v[250:251], v[248:249], v[250:251], s[72:73] op_sel_hi:[1,1,0]
	v_pk_mul_f32 v[250:251], v[248:249], v[250:251]
	v_pk_fma_f32 v[250:251], v[250:251], v[252:253], 0.5 op_sel_hi:[1,1,0] neg_lo:[1,0,0] neg_hi:[1,0,0]
	v_pk_mul_f32 v[248:249], v[82:83], 0.5 op_sel_hi:[1,0]
	v_fma_f32 v96, |v82|, v250, v248
	v_fma_f32 v120, |v83|, v251, v249
	s_andn2_b64 vcc, exec, s[90:91]
	v_mov_b64_e32 v[122:123], v[116:117]
	s_cbranch_vccnz .LBB0_286
	v_mov_b32_e32 v121, v97
	v_pk_add_f32 v[126:127], v[96:97], v[120:121]
	v_pk_mul_f32 v[128:129], v[96:97], v[120:121]
	v_mov_b32_e32 v122, v96
	v_mov_b32_e32 v127, v129
	v_pk_mul_f32 v[128:129], v[94:95], v[94:95]
	v_mov_b32_e32 v123, v120
	v_pk_fma_f32 v[128:129], v[92:93], v[92:93], v[128:129]
	v_pk_add_f32 v[124:125], v[92:93], v[94:95]
	v_pk_add_f32 v[128:129], v[128:129], v[128:129] op_sel_hi:[0,1]
	v_mul_f32_e32 v128, v122, v122
	v_pk_fma_f32 v[122:123], v[122:123], v[122:123], v[128:129] op_sel_hi:[1,1,0]
	v_mul_f32_e32 v121, v118, v118
	v_pk_add_f32 v[124:125], v[124:125], v[124:125] op_sel:[0,1] op_sel_hi:[1,0]
	v_mov_b32_e32 v119, v129
	v_mov_b32_e32 v122, v97
	v_mov_b32_e32 v125, v121
	v_pk_add_f32 v[122:123], v[118:119], v[122:123]
	v_pk_add_f32 v[124:125], v[124:125], v[126:127]
	s_nop 0
	v_pk_add_f32 v[122:123], v[124:125], v[122:123]
	s_nop 0
	v_pk_add_f32 v[122:123], v[122:123], v[116:117]

; __device__ __forceinline__ f32x2 gelu_pk(f32x2 v) {
;     const f32x2 av = __builtin_elementwise_abs(v), d = av * 0.2316418882f + 1.0f;
;     f32x2 t; t.x = __builtin_amdgcn_rcpf(d.x); t.y = __builtin_amdgcn_rcpf(d.y);
;     f32x2 q = t * 0.5307027145f + (-0.7265760135f); q = q * t + 0.7107068705f; q = q * t + (-0.142248368f); q = q * t + 0.127414796f; q = q * t;
;     const f32x2 s = (v * v) * (-0.72134752044f);
;     f32x2 e; e.x = __builtin_amdgcn_exp2f(s.x); e.y = __builtin_amdgcn_exp2f(s.y);
;     const f32x2 m = v * (q * e), r = v - m;
;     f32x2 o; o.x = v.x < 0.f ? m.x : r.x; o.y = v.y < 0.f ? m.y : r.y; return o;
; }
;     __device__ __forceinline__ void operator()(const f32x4 (&acc)[2][2][4][2], const Unit& u, int wr, int wc, int fr, int fq) const {
;     ...
;                         f32x2 a = gelu_pk((f32x2){v0[0], v0[1]}), b = gelu_pk((f32x2){v0[2], v0[3]}), c = gelu_pk((f32x2){v1[0], v1[1]}), d = gelu_pk((f32x2){v1[2], v1[3]});
;                         v0 = (f32x4){a.x, a.y, b.x, b.y}; v1 = (f32x4){c.x, c.y, d.x, d.y};
;                         if (pn >= 9) { const float t1 = (v0[0] + v0[1]) + (v0[2] + v0[3]) + (v1[0] + v1[1]) + (v1[2] + v1[3]);
;                             const float t2 = (v0[0] * v0[0] + v0[1] * v0[1]) + (v0[2] * v0[2] + v0[3] * v0[3]) + (v1[0] * v1[0] + v1[1] * v1[1]) + (v1[2] * v1[2] + v1[3] * v1[3]);
;                             if (bj == 0) { ps = t1; pss = t2; } else { ps += t1; pss += t2; } }
.LBB0_300:
	s_andn2_b64 vcc, exec, s[20:21]
	s_cbranch_vccnz .LBB0_432
	s_waitcnt vmcnt(3)
	s_waitcnt vmcnt(2)
	v_mov_b64_e32 v[254:255], s[66:67]
	v_fma_f32 v248, |v78|, s62, 1.0
	v_fma_f32 v249, |v79|, s62, 1.0
	v_pk_mul_f32 v[252:253], v[78:79], v[78:79]
	v_rcp_f32_e32 v248, v248
	v_rcp_f32_e32 v249, v249
	v_pk_mul_f32 v[252:253], v[252:253], s[74:75] op_sel_hi:[1,0]
	v_pk_fma_f32 v[250:251], v[248:249], s[64:65], v[254:255] op_sel_hi:[1,0,0]
	v_exp_f32_e32 v252, v252
	v_exp_f32_e32 v253, v253
	v_pk_fma_f32 v[250:251], v[248:249], v[250:251], s[68:69] op_sel_hi:[1,1,0]
	v_pk_fma_f32 v[250:251], v[248:249], v[250:251], s[70:71] op_sel_hi:[1,1,0]
	v_pk_fma_f32 v[250:251], v[248:249], v[250:251], s[72:73] op_sel_hi:[1,1,0]
	v_pk_mul_f32 v[250:251], v[248:249], v[250:251]
	v_pk_fma_f32 v[250:251], v[250:251], v[252:253], 0.5 op_sel_hi:[1,1,0] neg_lo:[1,0,0] neg_hi:[1,0,0]
	v_pk_mul_f32 v[248:249], v[78:79], 0.5 op_sel_hi:[1,0]
	v_fma_f32 v102, |v78|, v250, v248
	v_fma_f32 v104, |v79|, v251, v249
	v_fma_f32 v248, |v80|, s62, 1.0
	v_fma_f32 v249, |v81|, s62, 1.0
	v_pk_mul_f32 v[252:253], v[80:81], v[80:81]
	v_rcp_f32_e32 v248, v248
	v_rcp_f32_e32 v249, v249
	v_pk_mul_f32 v[252:253], v[252:253], s[74:75] op_sel_hi:[1,0]
	v_pk_fma_f32 v[250:251], v[248:249], s[64:65], v[254:255] op_sel_hi:[1,0,0]
	v_exp_f32_e32 v252, v252
	v_exp_f32_e32 v253, v253
	v_pk_fma_f32 v[250:251], v[248:249], v[250:251], s[68:69] op_sel_hi:[1,1,0]
	v_pk_fma_f32 v[250:251], v[248:249], v[250:251], s[70:71] op_sel_hi:[1,1,0]
	v_pk_fma_f32 v[250:251], v[248:249], v[250:251], s[72:73] op_sel_hi:[1,1,0]
	v_pk_mul_f32 v[250:251], v[248:249], v[250:251]
	v_pk_fma_f32 v[250:251], v[250:251], v[252:253], 0.5 op_sel_hi:[1,1,0] neg_lo:[1,0,0] neg_hi:[1,0,0]
	v_pk_mul_f32 v[248:249], v[80:81], 0.5 op_sel_hi:[1,0]
	v_fma_f32 v103, |v80|, v250, v248
	v_fma_f32 v105, |v81|, v251, v249
	v_fma_f32 v248, |v76|, s62, 1.0
	v_fma_f32 v249, |v77|, s62, 1.0
	v_pk_mul_f32 v[252:253], v[76:77], v[76:77]
	v_rcp_f32_e32 v248, v248
	v_rcp_f32_e32 v249, v249
	v_pk_mul_f32 v[252:253], v[252:253], s[74:75] op_sel_hi:[1,0]
	v_pk_fma_f32 v[250:251], v[248:249], s[64:65], v[254:255] op_sel_hi:[1,0,0]
	v_exp_f32_e32 v252, v252
	v_exp_f32_e32 v253, v253
	v_pk_fma_f32 v[250:251], v[248:249], v[250:251], s[68:69] op_sel_hi:[1,1,0]
	v_pk_fma_f32 v[250:251], v[248:249], v[250:251], s[70:71] op_sel_hi:[1,1,0]
	v_pk_fma_f32 v[250:251], v[248:249], v[250:251], s[72:73] op_sel_hi:[1,1,0]
	v_pk_mul_f32 v[250:251], v[248:249], v[250:251]
	v_pk_fma_f32 v[250:251], v[250:251], v[252:253], 0.5 op_sel_hi:[1,1,0] neg_lo:[1,0,0] neg_hi:[1,0,0]
	v_pk_mul_f32 v[248:249], v[76:77], 0.5 op_sel_hi:[1,0]
	v_fma_f32 v108, |v76|, v250, v248
	v_fma_f32 v107, |v77|, v251, v249
	v_fma_f32 v248, |v74|, s62, 1.0
	v_fma_f32 v249, |v75|, s62, 1.0
	v_pk_mul_f32 v[252:253], v[74:75], v[74:75]
	v_rcp_f32_e32 v248, v248
	v_rcp_f32_e32 v249, v249
	v_pk_mul_f32 v[252:253], v[252:253], s[74:75] op_sel_hi:[1,0]
	v_pk_fma_f32 v[250:251], v[248:249], s[64:65], v[254:255] op_sel_hi:[1,0,0]
	v_exp_f32_e32 v252, v252
	v_exp_f32_e32 v253, v253
	v_pk_fma_f32 v[250:251], v[248:249], v[250:251], s[68:69] op_sel_hi:[1,1,0]
	v_pk_fma_f32 v[250:251], v[248:249], v[250:251], s[70:71] op_sel_hi:[1,1,0]
	v_pk_fma_f32 v[250:251], v[248:249], v[250:251], s[72:73] op_sel_hi:[1,1,0]
	v_pk_mul_f32 v[250:251], v[248:249], v[250:251]
	v_pk_fma_f32 v[250:251], v[250:251], v[252:253], 0.5 op_sel_hi:[1,1,0] neg_lo:[1,0,0] neg_hi:[1,0,0]
	v_pk_mul_f32 v[248:249], v[74:75], 0.5 op_sel_hi:[1,0]
	v_fma_f32 v106, |v74|, v250, v248
	v_fma_f32 v110, |v75|, v251, v249
	s_andn2_b64 vcc, exec, s[90:91]
	s_cbranch_vccnz .LBB0_432
	v_mov_b32_e32 v111, v107
	v_pk_add_f32 v[114:115], v[106:107], v[110:111]
	v_pk_mul_f32 v[116:117], v[106:107], v[110:111]
	v_mov_b32_e32 v100, v106
	v_mov_b32_e32 v115, v117
	v_pk_mul_f32 v[116:117], v[104:105], v[104:105]
	v_mov_b32_e32 v101, v110
	v_pk_fma_f32 v[116:117], v[102:103], v[102:103], v[116:117]
	v_pk_add_f32 v[112:113], v[102:103], v[104:105]
	v_pk_add_f32 v[116:117], v[116:117], v[116:117] op_sel_hi:[0,1]
	v_mul_f32_e32 v116, v100, v100
	v_pk_fma_f32 v[100:101], v[100:101], v[100:101], v[116:117] op_sel_hi:[1,1,0]
	v_mul_f32_e32 v111, v108, v108
	v_pk_add_f32 v[112:113], v[112:113], v[112:113] op_sel:[0,1] op_sel_hi:[1,0]
	v_mov_b32_e32 v109, v117
	v_mov_b32_e32 v100, v107
	v_mov_b32_e32 v113, v111
	v_pk_add_f32 v[100:101], v[108:109], v[100:101]
	v_pk_add_f32 v[112:113], v[112:113], v[114:115]
	s_nop 0
	v_pk_add_f32 v[100:101], v[112:113], v[100:101]
	s_cbranch_execz .LBB0_304
	s_branch .LBB0_305

; __device__ __forceinline__ f32x2 gelu_pk(f32x2 v) {
;     const f32x2 av = __builtin_elementwise_abs(v), d = av * 0.2316418882f + 1.0f;
;     f32x2 t; t.x = __builtin_amdgcn_rcpf(d.x); t.y = __builtin_amdgcn_rcpf(d.y);
;     f32x2 q = t * 0.5307027145f + (-0.7265760135f); q = q * t + 0.7107068705f; q = q * t + (-0.142248368f); q = q * t + 0.127414796f; q = q * t;
;     const f32x2 s = (v * v) * (-0.72134752044f);
;     f32x2 e; e.x = __builtin_amdgcn_exp2f(s.x); e.y = __builtin_amdgcn_exp2f(s.y);
;     const f32x2 m = v * (q * e), r = v - m;
;     f32x2 o; o.x = v.x < 0.f ? m.x : r.x; o.y = v.y < 0.f ? m.y : r.y; return o;
; }
;     __device__ __forceinline__ void operator()(const f32x4 (&acc)[2][2][4][2], const Unit& u, int wr, int wc, int fr, int fq) const {
;     ...
;                         f32x2 a = gelu_pk((f32x2){v0[0], v0[1]}), b = gelu_pk((f32x2){v0[2], v0[3]}), c = gelu_pk((f32x2){v1[0], v1[1]}), d = gelu_pk((f32x2){v1[2], v1[3]});
;                         v0 = (f32x4){a.x, a.y, b.x, b.y}; v1 = (f32x4){c.x, c.y, d.x, d.y};
;                         if (pn >= 9) { const float t1 = (v0[0] + v0[1]) + (v0[2] + v0[3]) + (v1[0] + v1[1]) + (v1[2] + v1[3]);
;                             const float t2 = (v0[0] * v0[0] + v0[1] * v0[1]) + (v0[2] * v0[2] + v0[3] * v0[3]) + (v1[0] * v1[0] + v1[1] * v1[1]) + (v1[2] * v1[2] + v1[3] * v1[3]);
;                             if (bj == 0) { ps = t1; pss = t2; } else { ps += t1; pss += t2; } }
.LBB0_310:
	s_andn2_b64 vcc, exec, s[20:21]
	v_mov_b64_e32 v[106:107], v[100:101]
	s_cbranch_vccnz .LBB0_313
	v_mov_b64_e32 v[254:255], s[66:67]
	v_fma_f32 v248, |v70|, s62, 1.0
	v_fma_f32 v249, |v71|, s62, 1.0
	v_pk_mul_f32 v[252:253], v[70:71], v[70:71]
	v_rcp_f32_e32 v248, v248
	v_rcp_f32_e32 v249, v249
	v_pk_mul_f32 v[252:253], v[252:253], s[74:75] op_sel_hi:[1,0]
	v_pk_fma_f32 v[250:251], v[248:249], s[64:65], v[254:255] op_sel_hi:[1,0,0]
	v_exp_f32_e32 v252, v252
	v_exp_f32_e32 v253, v253
	v_pk_fma_f32 v[250:251], v[248:249], v[250:251], s[68:69] op_sel_hi:[1,1,0]
	v_pk_fma_f32 v[250:251], v[248:249], v[250:251], s[70:71] op_sel_hi:[1,1,0]
	v_pk_fma_f32 v[250:251], v[248:249], v[250:251], s[72:73] op_sel_hi:[1,1,0]
	v_pk_mul_f32 v[250:251], v[248:249], v[250:251]
	v_pk_fma_f32 v[250:251], v[250:251], v[252:253], 0.5 op_sel_hi:[1,1,0] neg_lo:[1,0,0] neg_hi:[1,0,0]
	v_pk_mul_f32 v[248:249], v[70:71], 0.5 op_sel_hi:[1,0]
	v_fma_f32 v76, |v70|, v250, v248
	v_fma_f32 v78, |v71|, v251, v249
	v_fma_f32 v248, |v72|, s62, 1.0
	v_fma_f32 v249, |v73|, s62, 1.0
	v_pk_mul_f32 v[252:253], v[72:73], v[72:73]
	v_rcp_f32_e32 v248, v248
	v_rcp_f32_e32 v249, v249
	v_pk_mul_f32 v[252:253], v[252:253], s[74:75] op_sel_hi:[1,0]
	v_pk_fma_f32 v[250:251], v[248:249], s[64:65], v[254:255] op_sel_hi:[1,0,0]
	v_exp_f32_e32 v252, v252
	v_exp_f32_e32 v253, v253
	v_pk_fma_f32 v[250:251], v[248:249], v[250:251], s[68:69] op_sel_hi:[1,1,0]
	v_pk_fma_f32 v[250:251], v[248:249], v[250:251], s[70:71] op_sel_hi:[1,1,0]
	v_pk_fma_f32 v[250:251], v[248:249], v[250:251], s[72:73] op_sel_hi:[1,1,0]
	v_pk_mul_f32 v[250:251], v[248:249], v[250:251]
	v_pk_fma_f32 v[250:251], v[250:251], v[252:253], 0.5 op_sel_hi:[1,1,0] neg_lo:[1,0,0] neg_hi:[1,0,0]
	v_pk_mul_f32 v[248:249], v[72:73], 0.5 op_sel_hi:[1,0]
	v_fma_f32 v77, |v72|, v250, v248
	v_fma_f32 v79, |v73|, v251, v249
	v_fma_f32 v248, |v68|, s62, 1.0
	v_fma_f32 v249, |v69|, s62, 1.0
	v_pk_mul_f32 v[252:253], v[68:69], v[68:69]
	v_rcp_f32_e32 v248, v248
	v_rcp_f32_e32 v249, v249
	v_pk_mul_f32 v[252:253], v[252:253], s[74:75] op_sel_hi:[1,0]
	v_pk_fma_f32 v[250:251], v[248:249], s[64:65], v[254:255] op_sel_hi:[1,0,0]
	v_exp_f32_e32 v252, v252
	v_exp_f32_e32 v253, v253
	v_pk_fma_f32 v[250:251], v[248:249], v[250:251], s[68:69] op_sel_hi:[1,1,0]
	v_pk_fma_f32 v[250:251], v[248:249], v[250:251], s[70:71] op_sel_hi:[1,1,0]
	v_pk_fma_f32 v[250:251], v[248:249], v[250:251], s[72:73] op_sel_hi:[1,1,0]
	v_pk_mul_f32 v[250:251], v[248:249], v[250:251]
	v_pk_fma_f32 v[250:251], v[250:251], v[252:253], 0.5 op_sel_hi:[1,1,0] neg_lo:[1,0,0] neg_hi:[1,0,0]
	v_pk_mul_f32 v[248:249], v[68:69], 0.5 op_sel_hi:[1,0]
	v_fma_f32 v102, |v68|, v250, v248
	v_fma_f32 v81, |v69|, v251, v249
	v_fma_f32 v248, |v66|, s62, 1.0
	v_fma_f32 v249, |v67|, s62, 1.0
	v_pk_mul_f32 v[252:253], v[66:67], v[66:67]
	v_rcp_f32_e32 v248, v248
	v_rcp_f32_e32 v249, v249
	v_pk_mul_f32 v[252:253], v[252:253], s[74:75] op_sel_hi:[1,0]
	v_pk_fma_f32 v[250:251], v[248:249], s[64:65], v[254:255] op_sel_hi:[1,0,0]
	v_exp_f32_e32 v252, v252
	v_exp_f32_e32 v253, v253
	v_pk_fma_f32 v[250:251], v[248:249], v[250:251], s[68:69] op_sel_hi:[1,1,0]
	v_pk_fma_f32 v[250:251], v[248:249], v[250:251], s[70:71] op_sel_hi:[1,1,0]
	v_pk_fma_f32 v[250:251], v[248:249], v[250:251], s[72:73] op_sel_hi:[1,1,0]
	v_pk_mul_f32 v[250:251], v[248:249], v[250:251]
	v_pk_fma_f32 v[250:251], v[250:251], v[252:253], 0.5 op_sel_hi:[1,1,0] neg_lo:[1,0,0] neg_hi:[1,0,0]
	v_pk_mul_f32 v[248:249], v[66:67], 0.5 op_sel_hi:[1,0]
	v_fma_f32 v80, |v66|, v250, v248
	v_fma_f32 v104, |v67|, v251, v249
	s_andn2_b64 vcc, exec, s[90:91]
	v_mov_b64_e32 v[106:107], v[100:101]
	s_cbranch_vccnz .LBB0_313
	v_mov_b32_e32 v105, v81
	v_pk_add_f32 v[110:111], v[80:81], v[104:105]
	v_pk_mul_f32 v[112:113], v[80:81], v[104:105]
	v_mov_b32_e32 v106, v80
	v_mov_b32_e32 v111, v113
	v_pk_mul_f32 v[112:113], v[78:79], v[78:79]
	v_mov_b32_e32 v107, v104
	v_pk_fma_f32 v[112:113], v[76:77], v[76:77], v[112:113]
	v_pk_add_f32 v[108:109], v[76:77], v[78:79]
	v_pk_add_f32 v[112:113], v[112:113], v[112:113] op_sel_hi:[0,1]
	v_mul_f32_e32 v112, v106, v106
	v_pk_fma_f32 v[106:107], v[106:107], v[106:107], v[112:113] op_sel_hi:[1,1,0]
	v_mul_f32_e32 v105, v102, v102
	v_pk_add_f32 v[108:109], v[108:109], v[108:109] op_sel:[0,1] op_sel_hi:[1,0]
	v_mov_b32_e32 v103, v113
	v_mov_b32_e32 v106, v81
	v_mov_b32_e32 v109, v105
	v_pk_add_f32 v[106:107], v[102:103], v[106:107]
	v_pk_add_f32 v[108:109], v[108:109], v[110:111]
	s_nop 0
	v_pk_add_f32 v[106:107], v[108:109], v[106:107]
	s_nop 0
	v_pk_add_f32 v[106:107], v[106:107], v[100:101]

; __device__ __forceinline__ f32x2 gelu_pk(f32x2 v) {
;     const f32x2 av = __builtin_elementwise_abs(v), d = av * 0.2316418882f + 1.0f;
;     f32x2 t; t.x = __builtin_amdgcn_rcpf(d.x); t.y = __builtin_amdgcn_rcpf(d.y);
;     f32x2 q = t * 0.5307027145f + (-0.7265760135f); q = q * t + 0.7107068705f; q = q * t + (-0.142248368f); q = q * t + 0.127414796f; q = q * t;
;     const f32x2 s = (v * v) * (-0.72134752044f);
;     f32x2 e; e.x = __builtin_amdgcn_exp2f(s.x); e.y = __builtin_amdgcn_exp2f(s.y);
;     const f32x2 m = v * (q * e), r = v - m;
;     f32x2 o; o.x = v.x < 0.f ? m.x : r.x; o.y = v.y < 0.f ? m.y : r.y; return o;
; }
;     __device__ __forceinline__ void operator()(const f32x4 (&acc)[2][2][4][2], const Unit& u, int wr, int wc, int fr, int fq) const {
;     ...
;                         f32x2 a = gelu_pk((f32x2){v0[0], v0[1]}), b = gelu_pk((f32x2){v0[2], v0[3]}), c = gelu_pk((f32x2){v1[0], v1[1]}), d = gelu_pk((f32x2){v1[2], v1[3]});
;                         v0 = (f32x4){a.x, a.y, b.x, b.y}; v1 = (f32x4){c.x, c.y, d.x, d.y};
;                         if (pn >= 9) { const float t1 = (v0[0] + v0[1]) + (v0[2] + v0[3]) + (v1[0] + v1[1]) + (v1[2] + v1[3]);
;                             const float t2 = (v0[0] * v0[0] + v0[1] * v0[1]) + (v0[2] * v0[2] + v0[3] * v0[3]) + (v1[0] * v1[0] + v1[1] * v1[1]) + (v1[2] * v1[2] + v1[3] * v1[3]);
;                             if (bj == 0) { ps = t1; pss = t2; } else { ps += t1; pss += t2; } }
.LBB0_327:
	s_andn2_b64 vcc, exec, s[20:21]
	s_cbranch_vccnz .LBB0_433
	s_waitcnt vmcnt(3)
	s_waitcnt vmcnt(2)
	v_mov_b64_e32 v[254:255], s[66:67]
	v_fma_f32 v248, |v62|, s62, 1.0
	v_fma_f32 v249, |v63|, s62, 1.0
	v_pk_mul_f32 v[252:253], v[62:63], v[62:63]
	v_rcp_f32_e32 v248, v248
	v_rcp_f32_e32 v249, v249
	v_pk_mul_f32 v[252:253], v[252:253], s[74:75] op_sel_hi:[1,0]
	v_pk_fma_f32 v[250:251], v[248:249], s[64:65], v[254:255] op_sel_hi:[1,0,0]
	v_exp_f32_e32 v252, v252
	v_exp_f32_e32 v253, v253
	v_pk_fma_f32 v[250:251], v[248:249], v[250:251], s[68:69] op_sel_hi:[1,1,0]
	v_pk_fma_f32 v[250:251], v[248:249], v[250:251], s[70:71] op_sel_hi:[1,1,0]
	v_pk_fma_f32 v[250:251], v[248:249], v[250:251], s[72:73] op_sel_hi:[1,1,0]
	v_pk_mul_f32 v[250:251], v[248:249], v[250:251]
	v_pk_fma_f32 v[250:251], v[250:251], v[252:253], 0.5 op_sel_hi:[1,1,0] neg_lo:[1,0,0] neg_hi:[1,0,0]
	v_pk_mul_f32 v[248:249], v[62:63], 0.5 op_sel_hi:[1,0]
	v_fma_f32 v86, |v62|, v250, v248
	v_fma_f32 v88, |v63|, v251, v249
	v_fma_f32 v248, |v64|, s62, 1.0
	v_fma_f32 v249, |v65|, s62, 1.0
	v_pk_mul_f32 v[252:253], v[64:65], v[64:65]
	v_rcp_f32_e32 v248, v248
	v_rcp_f32_e32 v249, v249
	v_pk_mul_f32 v[252:253], v[252:253], s[74:75] op_sel_hi:[1,0]
	v_pk_fma_f32 v[250:251], v[248:249], s[64:65], v[254:255] op_sel_hi:[1,0,0]
	v_exp_f32_e32 v252, v252
	v_exp_f32_e32 v253, v253
	v_pk_fma_f32 v[250:251], v[248:249], v[250:251], s[68:69] op_sel_hi:[1,1,0]
	v_pk_fma_f32 v[250:251], v[248:249], v[250:251], s[70:71] op_sel_hi:[1,1,0]
	v_pk_fma_f32 v[250:251], v[248:249], v[250:251], s[72:73] op_sel_hi:[1,1,0]
	v_pk_mul_f32 v[250:251], v[248:249], v[250:251]
	v_pk_fma_f32 v[250:251], v[250:251], v[252:253], 0.5 op_sel_hi:[1,1,0] neg_lo:[1,0,0] neg_hi:[1,0,0]
	v_pk_mul_f32 v[248:249], v[64:65], 0.5 op_sel_hi:[1,0]
	v_fma_f32 v87, |v64|, v250, v248
	v_fma_f32 v89, |v65|, v251, v249
	v_fma_f32 v248, |v60|, s62, 1.0
	v_fma_f32 v249, |v61|, s62, 1.0
	v_pk_mul_f32 v[252:253], v[60:61], v[60:61]
	v_rcp_f32_e32 v248, v248
	v_rcp_f32_e32 v249, v249
	v_pk_mul_f32 v[252:253], v[252:253], s[74:75] op_sel_hi:[1,0]
	v_pk_fma_f32 v[250:251], v[248:249], s[64:65], v[254:255] op_sel_hi:[1,0,0]
	v_exp_f32_e32 v252, v252
	v_exp_f32_e32 v253, v253
	v_pk_fma_f32 v[250:251], v[248:249], v[250:251], s[68:69] op_sel_hi:[1,1,0]
	v_pk_fma_f32 v[250:251], v[248:249], v[250:251], s[70:71] op_sel_hi:[1,1,0]
	v_pk_fma_f32 v[250:251], v[248:249], v[250:251], s[72:73] op_sel_hi:[1,1,0]
	v_pk_mul_f32 v[250:251], v[248:249], v[250:251]
	v_pk_fma_f32 v[250:251], v[250:251], v[252:253], 0.5 op_sel_hi:[1,1,0] neg_lo:[1,0,0] neg_hi:[1,0,0]
	v_pk_mul_f32 v[248:249], v[60:61], 0.5 op_sel_hi:[1,0]
	v_fma_f32 v92, |v60|, v250, v248
	v_fma_f32 v91, |v61|, v251, v249
	v_fma_f32 v248, |v58|, s62, 1.0
	v_fma_f32 v249, |v59|, s62, 1.0
	v_pk_mul_f32 v[252:253], v[58:59], v[58:59]
	v_rcp_f32_e32 v248, v248
	v_rcp_f32_e32 v249, v249
	v_pk_mul_f32 v[252:253], v[252:253], s[74:75] op_sel_hi:[1,0]
	v_pk_fma_f32 v[250:251], v[248:249], s[64:65], v[254:255] op_sel_hi:[1,0,0]
	v_exp_f32_e32 v252, v252
	v_exp_f32_e32 v253, v253
	v_pk_fma_f32 v[250:251], v[248:249], v[250:251], s[68:69] op_sel_hi:[1,1,0]
	v_pk_fma_f32 v[250:251], v[248:249], v[250:251], s[70:71] op_sel_hi:[1,1,0]
	v_pk_fma_f32 v[250:251], v[248:249], v[250:251], s[72:73] op_sel_hi:[1,1,0]
	v_pk_mul_f32 v[250:251], v[248:249], v[250:251]
	v_pk_fma_f32 v[250:251], v[250:251], v[252:253], 0.5 op_sel_hi:[1,1,0] neg_lo:[1,0,0] neg_hi:[1,0,0]
	v_pk_mul_f32 v[248:249], v[58:59], 0.5 op_sel_hi:[1,0]
	v_fma_f32 v90, |v58|, v250, v248
	v_fma_f32 v94, |v59|, v251, v249
	s_andn2_b64 vcc, exec, s[90:91]
	s_cbranch_vccnz .LBB0_433
	v_mov_b32_e32 v95, v91
	v_pk_add_f32 v[98:99], v[90:91], v[94:95]
	v_pk_mul_f32 v[100:101], v[90:91], v[94:95]
	v_mov_b32_e32 v84, v90
	v_mov_b32_e32 v99, v101
	v_pk_mul_f32 v[100:101], v[88:89], v[88:89]
	v_mov_b32_e32 v85, v94
	v_pk_fma_f32 v[100:101], v[86:87], v[86:87], v[100:101]
	v_pk_add_f32 v[96:97], v[86:87], v[88:89]
	v_pk_add_f32 v[100:101], v[100:101], v[100:101] op_sel_hi:[0,1]
	v_mul_f32_e32 v100, v84, v84
	v_pk_fma_f32 v[84:85], v[84:85], v[84:85], v[100:101] op_sel_hi:[1,1,0]
	v_mul_f32_e32 v95, v92, v92
	v_pk_add_f32 v[96:97], v[96:97], v[96:97] op_sel:[0,1] op_sel_hi:[1,0]
	v_mov_b32_e32 v93, v101
	v_mov_b32_e32 v84, v91
	v_mov_b32_e32 v97, v95
	v_pk_add_f32 v[84:85], v[92:93], v[84:85]
	v_pk_add_f32 v[96:97], v[96:97], v[98:99]
	s_nop 0
	v_pk_add_f32 v[84:85], v[96:97], v[84:85]
	s_cbranch_execz .LBB0_331
	s_branch .LBB0_332

; __device__ __forceinline__ f32x2 gelu_pk(f32x2 v) {
;     const f32x2 av = __builtin_elementwise_abs(v), d = av * 0.2316418882f + 1.0f;
;     f32x2 t; t.x = __builtin_amdgcn_rcpf(d.x); t.y = __builtin_amdgcn_rcpf(d.y);
;     f32x2 q = t * 0.5307027145f + (-0.7265760135f); q = q * t + 0.7107068705f; q = q * t + (-0.142248368f); q = q * t + 0.127414796f; q = q * t;
;     const f32x2 s = (v * v) * (-0.72134752044f);
;     f32x2 e; e.x = __builtin_amdgcn_exp2f(s.x); e.y = __builtin_amdgcn_exp2f(s.y);
;     const f32x2 m = v * (q * e), r = v - m;
;     f32x2 o; o.x = v.x < 0.f ? m.x : r.x; o.y = v.y < 0.f ? m.y : r.y; return o;
; }
;     __device__ __forceinline__ void operator()(const f32x4 (&acc)[2][2][4][2], const Unit& u, int wr, int wc, int fr, int fq) const {
;     ...
;                         f32x2 a = gelu_pk((f32x2){v0[0], v0[1]}), b = gelu_pk((f32x2){v0[2], v0[3]}), c = gelu_pk((f32x2){v1[0], v1[1]}), d = gelu_pk((f32x2){v1[2], v1[3]});
;                         v0 = (f32x4){a.x, a.y, b.x, b.y}; v1 = (f32x4){c.x, c.y, d.x, d.y};
;                         if (pn >= 9) { const float t1 = (v0[0] + v0[1]) + (v0[2] + v0[3]) + (v1[0] + v1[1]) + (v1[2] + v1[3]);
;                             const float t2 = (v0[0] * v0[0] + v0[1] * v0[1]) + (v0[2] * v0[2] + v0[3] * v0[3]) + (v1[0] * v1[0] + v1[1] * v1[1]) + (v1[2] * v1[2] + v1[3] * v1[3]);
;                             if (bj == 0) { ps = t1; pss = t2; } else { ps += t1; pss += t2; } }
.LBB0_337:
	s_andn2_b64 vcc, exec, s[20:21]
	v_mov_b64_e32 v[90:91], v[84:85]
	s_cbranch_vccnz .LBB0_340
	v_mov_b64_e32 v[254:255], s[66:67]
	v_fma_f32 v248, |v54|, s62, 1.0
	v_fma_f32 v249, |v55|, s62, 1.0
	v_pk_mul_f32 v[252:253], v[54:55], v[54:55]
	v_rcp_f32_e32 v248, v248
	v_rcp_f32_e32 v249, v249
	v_pk_mul_f32 v[252:253], v[252:253], s[74:75] op_sel_hi:[1,0]
	v_pk_fma_f32 v[250:251], v[248:249], s[64:65], v[254:255] op_sel_hi:[1,0,0]
	v_exp_f32_e32 v252, v252
	v_exp_f32_e32 v253, v253
	v_pk_fma_f32 v[250:251], v[248:249], v[250:251], s[68:69] op_sel_hi:[1,1,0]
	v_pk_fma_f32 v[250:251], v[248:249], v[250:251], s[70:71] op_sel_hi:[1,1,0]
	v_pk_fma_f32 v[250:251], v[248:249], v[250:251], s[72:73] op_sel_hi:[1,1,0]
	v_pk_mul_f32 v[250:251], v[248:249], v[250:251]
	v_pk_fma_f32 v[250:251], v[250:251], v[252:253], 0.5 op_sel_hi:[1,1,0] neg_lo:[1,0,0] neg_hi:[1,0,0]
	v_pk_mul_f32 v[248:249], v[54:55], 0.5 op_sel_hi:[1,0]
	v_fma_f32 v60, |v54|, v250, v248
	v_fma_f32 v62, |v55|, v251, v249
	v_fma_f32 v248, |v56|, s62, 1.0
	v_fma_f32 v249, |v57|, s62, 1.0
	v_pk_mul_f32 v[252:253], v[56:57], v[56:57]
	v_rcp_f32_e32 v248, v248
	v_rcp_f32_e32 v249, v249
	v_pk_mul_f32 v[252:253], v[252:253], s[74:75] op_sel_hi:[1,0]
	v_pk_fma_f32 v[250:251], v[248:249], s[64:65], v[254:255] op_sel_hi:[1,0,0]
	v_exp_f32_e32 v252, v252
	v_exp_f32_e32 v253, v253
	v_pk_fma_f32 v[250:251], v[248:249], v[250:251], s[68:69] op_sel_hi:[1,1,0]
	v_pk_fma_f32 v[250:251], v[248:249], v[250:251], s[70:71] op_sel_hi:[1,1,0]
	v_pk_fma_f32 v[250:251], v[248:249], v[250:251], s[72:73] op_sel_hi:[1,1,0]
	v_pk_mul_f32 v[250:251], v[248:249], v[250:251]
	v_pk_fma_f32 v[250:251], v[250:251], v[252:253], 0.5 op_sel_hi:[1,1,0] neg_lo:[1,0,0] neg_hi:[1,0,0]
	v_pk_mul_f32 v[248:249], v[56:57], 0.5 op_sel_hi:[1,0]
	v_fma_f32 v61, |v56|, v250, v248
	v_fma_f32 v63, |v57|, v251, v249
	v_fma_f32 v248, |v52|, s62, 1.0
	v_fma_f32 v249, |v53|, s62, 1.0
	v_pk_mul_f32 v[252:253], v[52:53], v[52:53]
	v_rcp_f32_e32 v248, v248
	v_rcp_f32_e32 v249, v249
	v_pk_mul_f32 v[252:253], v[252:253], s[74:75] op_sel_hi:[1,0]
	v_pk_fma_f32 v[250:251], v[248:249], s[64:65], v[254:255] op_sel_hi:[1,0,0]
	v_exp_f32_e32 v252, v252
	v_exp_f32_e32 v253, v253
	v_pk_fma_f32 v[250:251], v[248:249], v[250:251], s[68:69] op_sel_hi:[1,1,0]
	v_pk_fma_f32 v[250:251], v[248:249], v[250:251], s[70:71] op_sel_hi:[1,1,0]
	v_pk_fma_f32 v[250:251], v[248:249], v[250:251], s[72:73] op_sel_hi:[1,1,0]
	v_pk_mul_f32 v[250:251], v[248:249], v[250:251]
	v_pk_fma_f32 v[250:251], v[250:251], v[252:253], 0.5 op_sel_hi:[1,1,0] neg_lo:[1,0,0] neg_hi:[1,0,0]
	v_pk_mul_f32 v[248:249], v[52:53], 0.5 op_sel_hi:[1,0]
	v_fma_f32 v86, |v52|, v250, v248
	v_fma_f32 v65, |v53|, v251, v249
	v_fma_f32 v248, |v50|, s62, 1.0
	v_fma_f32 v249, |v51|, s62, 1.0
	v_pk_mul_f32 v[252:253], v[50:51], v[50:51]
	v_rcp_f32_e32 v248, v248
	v_rcp_f32_e32 v249, v249
	v_pk_mul_f32 v[252:253], v[252:253], s[74:75] op_sel_hi:[1,0]
	v_pk_fma_f32 v[250:251], v[248:249], s[64:65], v[254:255] op_sel_hi:[1,0,0]
	v_exp_f32_e32 v252, v252
	v_exp_f32_e32 v253, v253
	v_pk_fma_f32 v[250:251], v[248:249], v[250:251], s[68:69] op_sel_hi:[1,1,0]
	v_pk_fma_f32 v[250:251], v[248:249], v[250:251], s[70:71] op_sel_hi:[1,1,0]
	v_pk_fma_f32 v[250:251], v[248:249], v[250:251], s[72:73] op_sel_hi:[1,1,0]
	v_pk_mul_f32 v[250:251], v[248:249], v[250:251]
	v_pk_fma_f32 v[250:251], v[250:251], v[252:253], 0.5 op_sel_hi:[1,1,0] neg_lo:[1,0,0] neg_hi:[1,0,0]
	v_pk_mul_f32 v[248:249], v[50:51], 0.5 op_sel_hi:[1,0]
	v_fma_f32 v64, |v50|, v250, v248
	v_fma_f32 v88, |v51|, v251, v249
	s_andn2_b64 vcc, exec, s[90:91]
	v_mov_b64_e32 v[90:91], v[84:85]
	s_cbranch_vccnz .LBB0_340
	v_mov_b32_e32 v89, v65
	v_pk_add_f32 v[94:95], v[64:65], v[88:89]
	v_pk_mul_f32 v[96:97], v[64:65], v[88:89]
	v_mov_b32_e32 v90, v64
	v_mov_b32_e32 v95, v97
	v_pk_mul_f32 v[96:97], v[62:63], v[62:63]
	v_mov_b32_e32 v91, v88
	v_pk_fma_f32 v[96:97], v[60:61], v[60:61], v[96:97]
	v_pk_add_f32 v[92:93], v[60:61], v[62:63]
	v_pk_add_f32 v[96:97], v[96:97], v[96:97] op_sel_hi:[0,1]
	v_mul_f32_e32 v96, v90, v90
	v_pk_fma_f32 v[90:91], v[90:91], v[90:91], v[96:97] op_sel_hi:[1,1,0]
	v_mul_f32_e32 v89, v86, v86
	v_pk_add_f32 v[92:93], v[92:93], v[92:93] op_sel:[0,1] op_sel_hi:[1,0]
	v_mov_b32_e32 v87, v97
	v_mov_b32_e32 v90, v65
	v_mov_b32_e32 v93, v89
	v_pk_add_f32 v[90:91], v[86:87], v[90:91]
	v_pk_add_f32 v[92:93], v[92:93], v[94:95]
	s_nop 0
	v_pk_add_f32 v[90:91], v[92:93], v[90:91]
	s_nop 0
	v_pk_add_f32 v[90:91], v[90:91], v[84:85]

; __device__ __forceinline__ f32x2 gelu_pk(f32x2 v) {
;     const f32x2 av = __builtin_elementwise_abs(v), d = av * 0.2316418882f + 1.0f;
;     f32x2 t; t.x = __builtin_amdgcn_rcpf(d.x); t.y = __builtin_amdgcn_rcpf(d.y);
;     f32x2 q = t * 0.5307027145f + (-0.7265760135f); q = q * t + 0.7107068705f; q = q * t + (-0.142248368f); q = q * t + 0.127414796f; q = q * t;
;     const f32x2 s = (v * v) * (-0.72134752044f);
;     f32x2 e; e.x = __builtin_amdgcn_exp2f(s.x); e.y = __builtin_amdgcn_exp2f(s.y);
;     const f32x2 m = v * (q * e), r = v - m;
;     f32x2 o; o.x = v.x < 0.f ? m.x : r.x; o.y = v.y < 0.f ? m.y : r.y; return o;
; }
;     __device__ __forceinline__ void operator()(const f32x4 (&acc)[2][2][4][2], const Unit& u, int wr, int wc, int fr, int fq) const {
;     ...
;                         f32x2 a = gelu_pk((f32x2){v0[0], v0[1]}), b = gelu_pk((f32x2){v0[2], v0[3]}), c = gelu_pk((f32x2){v1[0], v1[1]}), d = gelu_pk((f32x2){v1[2], v1[3]});
;                         v0 = (f32x4){a.x, a.y, b.x, b.y}; v1 = (f32x4){c.x, c.y, d.x, d.y};
;                         if (pn >= 9) { const float t1 = (v0[0] + v0[1]) + (v0[2] + v0[3]) + (v1[0] + v1[1]) + (v1[2] + v1[3]);
;                             const float t2 = (v0[0] * v0[0] + v0[1] * v0[1]) + (v0[2] * v0[2] + v0[3] * v0[3]) + (v1[0] * v1[0] + v1[1] * v1[1]) + (v1[2] * v1[2] + v1[3] * v1[3]);
;                             if (bj == 0) { ps = t1; pss = t2; } else { ps += t1; pss += t2; } }
.LBB0_354:
	s_andn2_b64 vcc, exec, s[20:21]
	s_cbranch_vccnz .LBB0_434
	s_waitcnt vmcnt(3)
	s_waitcnt vmcnt(2)
	v_mov_b64_e32 v[254:255], s[66:67]
	v_fma_f32 v248, |v46|, s62, 1.0
	v_fma_f32 v249, |v47|, s62, 1.0
	v_pk_mul_f32 v[252:253], v[46:47], v[46:47]
	v_rcp_f32_e32 v248, v248
	v_rcp_f32_e32 v249, v249
	v_pk_mul_f32 v[252:253], v[252:253], s[74:75] op_sel_hi:[1,0]
	v_pk_fma_f32 v[250:251], v[248:249], s[64:65], v[254:255] op_sel_hi:[1,0,0]
	v_exp_f32_e32 v252, v252
	v_exp_f32_e32 v253, v253
	v_pk_fma_f32 v[250:251], v[248:249], v[250:251], s[68:69] op_sel_hi:[1,1,0]
	v_pk_fma_f32 v[250:251], v[248:249], v[250:251], s[70:71] op_sel_hi:[1,1,0]
	v_pk_fma_f32 v[250:251], v[248:249], v[250:251], s[72:73] op_sel_hi:[1,1,0]
	v_pk_mul_f32 v[250:251], v[248:249], v[250:251]
	v_pk_fma_f32 v[250:251], v[250:251], v[252:253], 0.5 op_sel_hi:[1,1,0] neg_lo:[1,0,0] neg_hi:[1,0,0]
	v_pk_mul_f32 v[248:249], v[46:47], 0.5 op_sel_hi:[1,0]
	v_fma_f32 v70, |v46|, v250, v248
	v_fma_f32 v72, |v47|, v251, v249
	v_fma_f32 v248, |v48|, s62, 1.0
	v_fma_f32 v249, |v49|, s62, 1.0
	v_pk_mul_f32 v[252:253], v[48:49], v[48:49]
	v_rcp_f32_e32 v248, v248
	v_rcp_f32_e32 v249, v249
	v_pk_mul_f32 v[252:253], v[252:253], s[74:75] op_sel_hi:[1,0]
	v_pk_fma_f32 v[250:251], v[248:249], s[64:65], v[254:255] op_sel_hi:[1,0,0]
	v_exp_f32_e32 v252, v252
	v_exp_f32_e32 v253, v253
	v_pk_fma_f32 v[250:251], v[248:249], v[250:251], s[68:69] op_sel_hi:[1,1,0]
	v_pk_fma_f32 v[250:251], v[248:249], v[250:251], s[70:71] op_sel_hi:[1,1,0]
	v_pk_fma_f32 v[250:251], v[248:249], v[250:251], s[72:73] op_sel_hi:[1,1,0]
	v_pk_mul_f32 v[250:251], v[248:249], v[250:251]
	v_pk_fma_f32 v[250:251], v[250:251], v[252:253], 0.5 op_sel_hi:[1,1,0] neg_lo:[1,0,0] neg_hi:[1,0,0]
	v_pk_mul_f32 v[248:249], v[48:49], 0.5 op_sel_hi:[1,0]
	v_fma_f32 v71, |v48|, v250, v248
	v_fma_f32 v73, |v49|, v251, v249
	v_fma_f32 v248, |v44|, s62, 1.0
	v_fma_f32 v249, |v45|, s62, 1.0
	v_pk_mul_f32 v[252:253], v[44:45], v[44:45]
	v_rcp_f32_e32 v248, v248
	v_rcp_f32_e32 v249, v249
	v_pk_mul_f32 v[252:253], v[252:253], s[74:75] op_sel_hi:[1,0]
	v_pk_fma_f32 v[250:251], v[248:249], s[64:65], v[254:255] op_sel_hi:[1,0,0]
	v_exp_f32_e32 v252, v252
	v_exp_f32_e32 v253, v253
	v_pk_fma_f32 v[250:251], v[248:249], v[250:251], s[68:69] op_sel_hi:[1,1,0]
	v_pk_fma_f32 v[250:251], v[248:249], v[250:251], s[70:71] op_sel_hi:[1,1,0]
	v_pk_fma_f32 v[250:251], v[248:249], v[250:251], s[72:73] op_sel_hi:[1,1,0]
	v_pk_mul_f32 v[250:251], v[248:249], v[250:251]
	v_pk_fma_f32 v[250:251], v[250:251], v[252:253], 0.5 op_sel_hi:[1,1,0] neg_lo:[1,0,0] neg_hi:[1,0,0]
	v_pk_mul_f32 v[248:249], v[44:45], 0.5 op_sel_hi:[1,0]
	v_fma_f32 v76, |v44|, v250, v248
	v_fma_f32 v75, |v45|, v251, v249
	v_fma_f32 v248, |v42|, s62, 1.0
	v_fma_f32 v249, |v43|, s62, 1.0
	v_pk_mul_f32 v[252:253], v[42:43], v[42:43]
	v_rcp_f32_e32 v248, v248
	v_rcp_f32_e32 v249, v249
	v_pk_mul_f32 v[252:253], v[252:253], s[74:75] op_sel_hi:[1,0]
	v_pk_fma_f32 v[250:251], v[248:249], s[64:65], v[254:255] op_sel_hi:[1,0,0]
	v_exp_f32_e32 v252, v252
	v_exp_f32_e32 v253, v253
	v_pk_fma_f32 v[250:251], v[248:249], v[250:251], s[68:69] op_sel_hi:[1,1,0]
	v_pk_fma_f32 v[250:251], v[248:249], v[250:251], s[70:71] op_sel_hi:[1,1,0]
	v_pk_fma_f32 v[250:251], v[248:249], v[250:251], s[72:73] op_sel_hi:[1,1,0]
	v_pk_mul_f32 v[250:251], v[248:249], v[250:251]
	v_pk_fma_f32 v[250:251], v[250:251], v[252:253], 0.5 op_sel_hi:[1,1,0] neg_lo:[1,0,0] neg_hi:[1,0,0]
	v_pk_mul_f32 v[248:249], v[42:43], 0.5 op_sel_hi:[1,0]
	v_fma_f32 v74, |v42|, v250, v248
	v_fma_f32 v78, |v43|, v251, v249
	s_andn2_b64 vcc, exec, s[90:91]
	s_cbranch_vccnz .LBB0_434
	v_mov_b32_e32 v79, v75
	v_pk_add_f32 v[82:83], v[74:75], v[78:79]
	v_pk_mul_f32 v[84:85], v[74:75], v[78:79]
	v_mov_b32_e32 v68, v74
	v_mov_b32_e32 v83, v85
	v_pk_mul_f32 v[84:85], v[72:73], v[72:73]
	v_mov_b32_e32 v69, v78
	v_pk_fma_f32 v[84:85], v[70:71], v[70:71], v[84:85]
	v_pk_add_f32 v[80:81], v[70:71], v[72:73]
	v_pk_add_f32 v[84:85], v[84:85], v[84:85] op_sel_hi:[0,1]
	v_mul_f32_e32 v84, v68, v68
	v_pk_fma_f32 v[68:69], v[68:69], v[68:69], v[84:85] op_sel_hi:[1,1,0]
	v_mul_f32_e32 v79, v76, v76
	v_pk_add_f32 v[80:81], v[80:81], v[80:81] op_sel:[0,1] op_sel_hi:[1,0]
	v_mov_b32_e32 v77, v85
	v_mov_b32_e32 v68, v75
	v_mov_b32_e32 v81, v79
	v_pk_add_f32 v[68:69], v[76:77], v[68:69]
	v_pk_add_f32 v[80:81], v[80:81], v[82:83]
	s_nop 0
	v_pk_add_f32 v[68:69], v[80:81], v[68:69]
	s_cbranch_execz .LBB0_358
	s_branch .LBB0_359

; __device__ __forceinline__ f32x2 gelu_pk(f32x2 v) {
;     const f32x2 av = __builtin_elementwise_abs(v), d = av * 0.2316418882f + 1.0f;
;     f32x2 t; t.x = __builtin_amdgcn_rcpf(d.x); t.y = __builtin_amdgcn_rcpf(d.y);
;     f32x2 q = t * 0.5307027145f + (-0.7265760135f); q = q * t + 0.7107068705f; q = q * t + (-0.142248368f); q = q * t + 0.127414796f; q = q * t;
;     const f32x2 s = (v * v) * (-0.72134752044f);
;     f32x2 e; e.x = __builtin_amdgcn_exp2f(s.x); e.y = __builtin_amdgcn_exp2f(s.y);
;     const f32x2 m = v * (q * e), r = v - m;
;     f32x2 o; o.x = v.x < 0.f ? m.x : r.x; o.y = v.y < 0.f ? m.y : r.y; return o;
; }
;     __device__ __forceinline__ void operator()(const f32x4 (&acc)[2][2][4][2], const Unit& u, int wr, int wc, int fr, int fq) const {
;     ...
;                         f32x2 a = gelu_pk((f32x2){v0[0], v0[1]}), b = gelu_pk((f32x2){v0[2], v0[3]}), c = gelu_pk((f32x2){v1[0], v1[1]}), d = gelu_pk((f32x2){v1[2], v1[3]});
;                         v0 = (f32x4){a.x, a.y, b.x, b.y}; v1 = (f32x4){c.x, c.y, d.x, d.y};
;                         if (pn >= 9) { const float t1 = (v0[0] + v0[1]) + (v0[2] + v0[3]) + (v1[0] + v1[1]) + (v1[2] + v1[3]);
;                             const float t2 = (v0[0] * v0[0] + v0[1] * v0[1]) + (v0[2] * v0[2] + v0[3] * v0[3]) + (v1[0] * v1[0] + v1[1] * v1[1]) + (v1[2] * v1[2] + v1[3] * v1[3]);
;                             if (bj == 0) { ps = t1; pss = t2; } else { ps += t1; pss += t2; } }
.LBB0_364:
	s_andn2_b64 vcc, exec, s[20:21]
	v_mov_b64_e32 v[74:75], v[68:69]
	s_cbranch_vccnz .LBB0_367
	v_mov_b64_e32 v[254:255], s[66:67]
	v_fma_f32 v248, |v38|, s62, 1.0
	v_fma_f32 v249, |v39|, s62, 1.0
	v_pk_mul_f32 v[252:253], v[38:39], v[38:39]
	v_rcp_f32_e32 v248, v248
	v_rcp_f32_e32 v249, v249
	v_pk_mul_f32 v[252:253], v[252:253], s[74:75] op_sel_hi:[1,0]
	v_pk_fma_f32 v[250:251], v[248:249], s[64:65], v[254:255] op_sel_hi:[1,0,0]
	v_exp_f32_e32 v252, v252
	v_exp_f32_e32 v253, v253
	v_pk_fma_f32 v[250:251], v[248:249], v[250:251], s[68:69] op_sel_hi:[1,1,0]
	v_pk_fma_f32 v[250:251], v[248:249], v[250:251], s[70:71] op_sel_hi:[1,1,0]
	v_pk_fma_f32 v[250:251], v[248:249], v[250:251], s[72:73] op_sel_hi:[1,1,0]
	v_pk_mul_f32 v[250:251], v[248:249], v[250:251]
	v_pk_fma_f32 v[250:251], v[250:251], v[252:253], 0.5 op_sel_hi:[1,1,0] neg_lo:[1,0,0] neg_hi:[1,0,0]
	v_pk_mul_f32 v[248:249], v[38:39], 0.5 op_sel_hi:[1,0]
	v_fma_f32 v44, |v38|, v250, v248
	v_fma_f32 v46, |v39|, v251, v249
	v_fma_f32 v248, |v40|, s62, 1.0
	v_fma_f32 v249, |v41|, s62, 1.0
	v_pk_mul_f32 v[252:253], v[40:41], v[40:41]
	v_rcp_f32_e32 v248, v248
	v_rcp_f32_e32 v249, v249
	v_pk_mul_f32 v[252:253], v[252:253], s[74:75] op_sel_hi:[1,0]
	v_pk_fma_f32 v[250:251], v[248:249], s[64:65], v[254:255] op_sel_hi:[1,0,0]
	v_exp_f32_e32 v252, v252
	v_exp_f32_e32 v253, v253
	v_pk_fma_f32 v[250:251], v[248:249], v[250:251], s[68:69] op_sel_hi:[1,1,0]
	v_pk_fma_f32 v[250:251], v[248:249], v[250:251], s[70:71] op_sel_hi:[1,1,0]
	v_pk_fma_f32 v[250:251], v[248:249], v[250:251], s[72:73] op_sel_hi:[1,1,0]
	v_pk_mul_f32 v[250:251], v[248:249], v[250:251]
	v_pk_fma_f32 v[250:251], v[250:251], v[252:253], 0.5 op_sel_hi:[1,1,0] neg_lo:[1,0,0] neg_hi:[1,0,0]
	v_pk_mul_f32 v[248:249], v[40:41], 0.5 op_sel_hi:[1,0]
	v_fma_f32 v45, |v40|, v250, v248
	v_fma_f32 v47, |v41|, v251, v249
	v_fma_f32 v248, |v36|, s62, 1.0
	v_fma_f32 v249, |v37|, s62, 1.0
	v_pk_mul_f32 v[252:253], v[36:37], v[36:37]
	v_rcp_f32_e32 v248, v248
	v_rcp_f32_e32 v249, v249
	v_pk_mul_f32 v[252:253], v[252:253], s[74:75] op_sel_hi:[1,0]
	v_pk_fma_f32 v[250:251], v[248:249], s[64:65], v[254:255] op_sel_hi:[1,0,0]
	v_exp_f32_e32 v252, v252
	v_exp_f32_e32 v253, v253
	v_pk_fma_f32 v[250:251], v[248:249], v[250:251], s[68:69] op_sel_hi:[1,1,0]
	v_pk_fma_f32 v[250:251], v[248:249], v[250:251], s[70:71] op_sel_hi:[1,1,0]
	v_pk_fma_f32 v[250:251], v[248:249], v[250:251], s[72:73] op_sel_hi:[1,1,0]
	v_pk_mul_f32 v[250:251], v[248:249], v[250:251]
	v_pk_fma_f32 v[250:251], v[250:251], v[252:253], 0.5 op_sel_hi:[1,1,0] neg_lo:[1,0,0] neg_hi:[1,0,0]
	v_pk_mul_f32 v[248:249], v[36:37], 0.5 op_sel_hi:[1,0]
	v_fma_f32 v70, |v36|, v250, v248
	v_fma_f32 v49, |v37|, v251, v249
	v_fma_f32 v248, |v34|, s62, 1.0
	v_fma_f32 v249, |v35|, s62, 1.0
	v_pk_mul_f32 v[252:253], v[34:35], v[34:35]
	v_rcp_f32_e32 v248, v248
	v_rcp_f32_e32 v249, v249
	v_pk_mul_f32 v[252:253], v[252:253], s[74:75] op_sel_hi:[1,0]
	v_pk_fma_f32 v[250:251], v[248:249], s[64:65], v[254:255] op_sel_hi:[1,0,0]
	v_exp_f32_e32 v252, v252
	v_exp_f32_e32 v253, v253
	v_pk_fma_f32 v[250:251], v[248:249], v[250:251], s[68:69] op_sel_hi:[1,1,0]
	v_pk_fma_f32 v[250:251], v[248:249], v[250:251], s[70:71] op_sel_hi:[1,1,0]
	v_pk_fma_f32 v[250:251], v[248:249], v[250:251], s[72:73] op_sel_hi:[1,1,0]
	v_pk_mul_f32 v[250:251], v[248:249], v[250:251]
	v_pk_fma_f32 v[250:251], v[250:251], v[252:253], 0.5 op_sel_hi:[1,1,0] neg_lo:[1,0,0] neg_hi:[1,0,0]
	v_pk_mul_f32 v[248:249], v[34:35], 0.5 op_sel_hi:[1,0]
	v_fma_f32 v48, |v34|, v250, v248
	v_fma_f32 v72, |v35|, v251, v249
	s_andn2_b64 vcc, exec, s[90:91]
	v_mov_b64_e32 v[74:75], v[68:69]
	s_cbranch_vccnz .LBB0_367
	v_mov_b32_e32 v73, v49
	v_pk_add_f32 v[78:79], v[48:49], v[72:73]
	v_pk_mul_f32 v[80:81], v[48:49], v[72:73]
	v_mov_b32_e32 v74, v48
	v_mov_b32_e32 v79, v81
	v_pk_mul_f32 v[80:81], v[46:47], v[46:47]
	v_mov_b32_e32 v75, v72
	v_pk_fma_f32 v[80:81], v[44:45], v[44:45], v[80:81]
	v_pk_add_f32 v[76:77], v[44:45], v[46:47]
	v_pk_add_f32 v[80:81], v[80:81], v[80:81] op_sel_hi:[0,1]
	v_mul_f32_e32 v80, v74, v74
	v_pk_fma_f32 v[74:75], v[74:75], v[74:75], v[80:81] op_sel_hi:[1,1,0]
	v_mul_f32_e32 v73, v70, v70
	v_pk_add_f32 v[76:77], v[76:77], v[76:77] op_sel:[0,1] op_sel_hi:[1,0]
	v_mov_b32_e32 v71, v81
	v_mov_b32_e32 v74, v49
	v_mov_b32_e32 v77, v73
	v_pk_add_f32 v[74:75], v[70:71], v[74:75]
	v_pk_add_f32 v[76:77], v[76:77], v[78:79]
	s_nop 0
	v_pk_add_f32 v[74:75], v[76:77], v[74:75]
	s_nop 0
	v_pk_add_f32 v[74:75], v[74:75], v[68:69]

; __device__ __forceinline__ f32x2 gelu_pk(f32x2 v) {
;     const f32x2 av = __builtin_elementwise_abs(v), d = av * 0.2316418882f + 1.0f;
;     f32x2 t; t.x = __builtin_amdgcn_rcpf(d.x); t.y = __builtin_amdgcn_rcpf(d.y);
;     f32x2 q = t * 0.5307027145f + (-0.7265760135f); q = q * t + 0.7107068705f; q = q * t + (-0.142248368f); q = q * t + 0.127414796f; q = q * t;
;     const f32x2 s = (v * v) * (-0.72134752044f);
;     f32x2 e; e.x = __builtin_amdgcn_exp2f(s.x); e.y = __builtin_amdgcn_exp2f(s.y);
;     const f32x2 m = v * (q * e), r = v - m;
;     f32x2 o; o.x = v.x < 0.f ? m.x : r.x; o.y = v.y < 0.f ? m.y : r.y; return o;
; }
;     __device__ __forceinline__ void operator()(const f32x4 (&acc)[2][2][4][2], const Unit& u, int wr, int wc, int fr, int fq) const {
;     ...
;                         f32x2 a = gelu_pk((f32x2){v0[0], v0[1]}), b = gelu_pk((f32x2){v0[2], v0[3]}), c = gelu_pk((f32x2){v1[0], v1[1]}), d = gelu_pk((f32x2){v1[2], v1[3]});
;                         v0 = (f32x4){a.x, a.y, b.x, b.y}; v1 = (f32x4){c.x, c.y, d.x, d.y};
;                         if (pn >= 9) { const float t1 = (v0[0] + v0[1]) + (v0[2] + v0[3]) + (v1[0] + v1[1]) + (v1[2] + v1[3]);
;                             const float t2 = (v0[0] * v0[0] + v0[1] * v0[1]) + (v0[2] * v0[2] + v0[3] * v0[3]) + (v1[0] * v1[0] + v1[1] * v1[1]) + (v1[2] * v1[2] + v1[3] * v1[3]);
;                             if (bj == 0) { ps = t1; pss = t2; } else { ps += t1; pss += t2; } }
.LBB0_381:
	s_andn2_b64 vcc, exec, s[20:21]
	s_cbranch_vccnz .LBB0_435
	s_waitcnt vmcnt(3)
	s_waitcnt vmcnt(2)
	v_mov_b64_e32 v[254:255], s[66:67]
	v_fma_f32 v248, |v30|, s62, 1.0
	v_fma_f32 v249, |v31|, s62, 1.0
	v_pk_mul_f32 v[252:253], v[30:31], v[30:31]
	v_rcp_f32_e32 v248, v248
	v_rcp_f32_e32 v249, v249
	v_pk_mul_f32 v[252:253], v[252:253], s[74:75] op_sel_hi:[1,0]
	v_pk_fma_f32 v[250:251], v[248:249], s[64:65], v[254:255] op_sel_hi:[1,0,0]
	v_exp_f32_e32 v252, v252
	v_exp_f32_e32 v253, v253
	v_pk_fma_f32 v[250:251], v[248:249], v[250:251], s[68:69] op_sel_hi:[1,1,0]
	v_pk_fma_f32 v[250:251], v[248:249], v[250:251], s[70:71] op_sel_hi:[1,1,0]
	v_pk_fma_f32 v[250:251], v[248:249], v[250:251], s[72:73] op_sel_hi:[1,1,0]
	v_pk_mul_f32 v[250:251], v[248:249], v[250:251]
	v_pk_fma_f32 v[250:251], v[250:251], v[252:253], 0.5 op_sel_hi:[1,1,0] neg_lo:[1,0,0] neg_hi:[1,0,0]
	v_pk_mul_f32 v[248:249], v[30:31], 0.5 op_sel_hi:[1,0]
	v_fma_f32 v54, |v30|, v250, v248
	v_fma_f32 v56, |v31|, v251, v249
	v_fma_f32 v248, |v32|, s62, 1.0
	v_fma_f32 v249, |v33|, s62, 1.0
	v_pk_mul_f32 v[252:253], v[32:33], v[32:33]
	v_rcp_f32_e32 v248, v248
	v_rcp_f32_e32 v249, v249
	v_pk_mul_f32 v[252:253], v[252:253], s[74:75] op_sel_hi:[1,0]
	v_pk_fma_f32 v[250:251], v[248:249], s[64:65], v[254:255] op_sel_hi:[1,0,0]
	v_exp_f32_e32 v252, v252
	v_exp_f32_e32 v253, v253
	v_pk_fma_f32 v[250:251], v[248:249], v[250:251], s[68:69] op_sel_hi:[1,1,0]
	v_pk_fma_f32 v[250:251], v[248:249], v[250:251], s[70:71] op_sel_hi:[1,1,0]
	v_pk_fma_f32 v[250:251], v[248:249], v[250:251], s[72:73] op_sel_hi:[1,1,0]
	v_pk_mul_f32 v[250:251], v[248:249], v[250:251]
	v_pk_fma_f32 v[250:251], v[250:251], v[252:253], 0.5 op_sel_hi:[1,1,0] neg_lo:[1,0,0] neg_hi:[1,0,0]
	v_pk_mul_f32 v[248:249], v[32:33], 0.5 op_sel_hi:[1,0]
	v_fma_f32 v55, |v32|, v250, v248
	v_fma_f32 v57, |v33|, v251, v249
	v_fma_f32 v248, |v28|, s62, 1.0
	v_fma_f32 v249, |v29|, s62, 1.0
	v_pk_mul_f32 v[252:253], v[28:29], v[28:29]
	v_rcp_f32_e32 v248, v248
	v_rcp_f32_e32 v249, v249
	v_pk_mul_f32 v[252:253], v[252:253], s[74:75] op_sel_hi:[1,0]
	v_pk_fma_f32 v[250:251], v[248:249], s[64:65], v[254:255] op_sel_hi:[1,0,0]
	v_exp_f32_e32 v252, v252
	v_exp_f32_e32 v253, v253
	v_pk_fma_f32 v[250:251], v[248:249], v[250:251], s[68:69] op_sel_hi:[1,1,0]
	v_pk_fma_f32 v[250:251], v[248:249], v[250:251], s[70:71] op_sel_hi:[1,1,0]
	v_pk_fma_f32 v[250:251], v[248:249], v[250:251], s[72:73] op_sel_hi:[1,1,0]
	v_pk_mul_f32 v[250:251], v[248:249], v[250:251]
	v_pk_fma_f32 v[250:251], v[250:251], v[252:253], 0.5 op_sel_hi:[1,1,0] neg_lo:[1,0,0] neg_hi:[1,0,0]
	v_pk_mul_f32 v[248:249], v[28:29], 0.5 op_sel_hi:[1,0]
	v_fma_f32 v60, |v28|, v250, v248
	v_fma_f32 v59, |v29|, v251, v249
	v_fma_f32 v248, |v26|, s62, 1.0
	v_fma_f32 v249, |v27|, s62, 1.0
	v_pk_mul_f32 v[252:253], v[26:27], v[26:27]
	v_rcp_f32_e32 v248, v248
	v_rcp_f32_e32 v249, v249
	v_pk_mul_f32 v[252:253], v[252:253], s[74:75] op_sel_hi:[1,0]
	v_pk_fma_f32 v[250:251], v[248:249], s[64:65], v[254:255] op_sel_hi:[1,0,0]
	v_exp_f32_e32 v252, v252
	v_exp_f32_e32 v253, v253
	v_pk_fma_f32 v[250:251], v[248:249], v[250:251], s[68:69] op_sel_hi:[1,1,0]
	v_pk_fma_f32 v[250:251], v[248:249], v[250:251], s[70:71] op_sel_hi:[1,1,0]
	v_pk_fma_f32 v[250:251], v[248:249], v[250:251], s[72:73] op_sel_hi:[1,1,0]
	v_pk_mul_f32 v[250:251], v[248:249], v[250:251]
	v_pk_fma_f32 v[250:251], v[250:251], v[252:253], 0.5 op_sel_hi:[1,1,0] neg_lo:[1,0,0] neg_hi:[1,0,0]
	v_pk_mul_f32 v[248:249], v[26:27], 0.5 op_sel_hi:[1,0]
	v_fma_f32 v58, |v26|, v250, v248
	v_fma_f32 v62, |v27|, v251, v249
	s_andn2_b64 vcc, exec, s[90:91]
	s_cbranch_vccnz .LBB0_435
	v_mov_b32_e32 v63, v59
	v_pk_add_f32 v[66:67], v[58:59], v[62:63]
	v_pk_mul_f32 v[68:69], v[58:59], v[62:63]
	v_mov_b32_e32 v52, v58
	v_mov_b32_e32 v67, v69
	v_pk_mul_f32 v[68:69], v[56:57], v[56:57]
	v_mov_b32_e32 v53, v62
	v_pk_fma_f32 v[68:69], v[54:55], v[54:55], v[68:69]
	v_pk_add_f32 v[64:65], v[54:55], v[56:57]
	v_pk_add_f32 v[68:69], v[68:69], v[68:69] op_sel_hi:[0,1]
	v_mul_f32_e32 v68, v52, v52
	v_pk_fma_f32 v[52:53], v[52:53], v[52:53], v[68:69] op_sel_hi:[1,1,0]
	v_mul_f32_e32 v63, v60, v60
	v_pk_add_f32 v[64:65], v[64:65], v[64:65] op_sel:[0,1] op_sel_hi:[1,0]
	v_mov_b32_e32 v61, v69
	v_mov_b32_e32 v52, v59
	v_mov_b32_e32 v65, v63
	v_pk_add_f32 v[52:53], v[60:61], v[52:53]
	v_pk_add_f32 v[64:65], v[64:65], v[66:67]
	s_nop 0
	v_pk_add_f32 v[52:53], v[64:65], v[52:53]
	s_cbranch_execz .LBB0_385
	s_branch .LBB0_386

; __device__ __forceinline__ f32x2 gelu_pk(f32x2 v) {
;     const f32x2 av = __builtin_elementwise_abs(v), d = av * 0.2316418882f + 1.0f;
;     f32x2 t; t.x = __builtin_amdgcn_rcpf(d.x); t.y = __builtin_amdgcn_rcpf(d.y);
;     f32x2 q = t * 0.5307027145f + (-0.7265760135f); q = q * t + 0.7107068705f; q = q * t + (-0.142248368f); q = q * t + 0.127414796f; q = q * t;
;     const f32x2 s = (v * v) * (-0.72134752044f);
;     f32x2 e; e.x = __builtin_amdgcn_exp2f(s.x); e.y = __builtin_amdgcn_exp2f(s.y);
;     const f32x2 m = v * (q * e), r = v - m;
;     f32x2 o; o.x = v.x < 0.f ? m.x : r.x; o.y = v.y < 0.f ? m.y : r.y; return o;
; }
;     __device__ __forceinline__ void operator()(const f32x4 (&acc)[2][2][4][2], const Unit& u, int wr, int wc, int fr, int fq) const {
;     ...
;                         f32x2 a = gelu_pk((f32x2){v0[0], v0[1]}), b = gelu_pk((f32x2){v0[2], v0[3]}), c = gelu_pk((f32x2){v1[0], v1[1]}), d = gelu_pk((f32x2){v1[2], v1[3]});
;                         v0 = (f32x4){a.x, a.y, b.x, b.y}; v1 = (f32x4){c.x, c.y, d.x, d.y};
;                         if (pn >= 9) { const float t1 = (v0[0] + v0[1]) + (v0[2] + v0[3]) + (v1[0] + v1[1]) + (v1[2] + v1[3]);
;                             const float t2 = (v0[0] * v0[0] + v0[1] * v0[1]) + (v0[2] * v0[2] + v0[3] * v0[3]) + (v1[0] * v1[0] + v1[1] * v1[1]) + (v1[2] * v1[2] + v1[3] * v1[3]);
;                             if (bj == 0) { ps = t1; pss = t2; } else { ps += t1; pss += t2; } }
.LBB0_391:
	s_andn2_b64 vcc, exec, s[20:21]
	v_mov_b64_e32 v[58:59], v[52:53]
	s_cbranch_vccnz .LBB0_394
	v_mov_b64_e32 v[254:255], s[66:67]
	v_fma_f32 v248, |v22|, s62, 1.0
	v_fma_f32 v249, |v23|, s62, 1.0
	v_pk_mul_f32 v[252:253], v[22:23], v[22:23]
	v_rcp_f32_e32 v248, v248
	v_rcp_f32_e32 v249, v249
	v_pk_mul_f32 v[252:253], v[252:253], s[74:75] op_sel_hi:[1,0]
	v_pk_fma_f32 v[250:251], v[248:249], s[64:65], v[254:255] op_sel_hi:[1,0,0]
	v_exp_f32_e32 v252, v252
	v_exp_f32_e32 v253, v253
	v_pk_fma_f32 v[250:251], v[248:249], v[250:251], s[68:69] op_sel_hi:[1,1,0]
	v_pk_fma_f32 v[250:251], v[248:249], v[250:251], s[70:71] op_sel_hi:[1,1,0]
	v_pk_fma_f32 v[250:251], v[248:249], v[250:251], s[72:73] op_sel_hi:[1,1,0]
	v_pk_mul_f32 v[250:251], v[248:249], v[250:251]
	v_pk_fma_f32 v[250:251], v[250:251], v[252:253], 0.5 op_sel_hi:[1,1,0] neg_lo:[1,0,0] neg_hi:[1,0,0]
	v_pk_mul_f32 v[248:249], v[22:23], 0.5 op_sel_hi:[1,0]
	v_fma_f32 v28, |v22|, v250, v248
	v_fma_f32 v30, |v23|, v251, v249
	v_fma_f32 v248, |v24|, s62, 1.0
	v_fma_f32 v249, |v25|, s62, 1.0
	v_pk_mul_f32 v[252:253], v[24:25], v[24:25]
	v_rcp_f32_e32 v248, v248
	v_rcp_f32_e32 v249, v249
	v_pk_mul_f32 v[252:253], v[252:253], s[74:75] op_sel_hi:[1,0]
	v_pk_fma_f32 v[250:251], v[248:249], s[64:65], v[254:255] op_sel_hi:[1,0,0]
	v_exp_f32_e32 v252, v252
	v_exp_f32_e32 v253, v253
	v_pk_fma_f32 v[250:251], v[248:249], v[250:251], s[68:69] op_sel_hi:[1,1,0]
	v_pk_fma_f32 v[250:251], v[248:249], v[250:251], s[70:71] op_sel_hi:[1,1,0]
	v_pk_fma_f32 v[250:251], v[248:249], v[250:251], s[72:73] op_sel_hi:[1,1,0]
	v_pk_mul_f32 v[250:251], v[248:249], v[250:251]
	v_pk_fma_f32 v[250:251], v[250:251], v[252:253], 0.5 op_sel_hi:[1,1,0] neg_lo:[1,0,0] neg_hi:[1,0,0]
	v_pk_mul_f32 v[248:249], v[24:25], 0.5 op_sel_hi:[1,0]
	v_fma_f32 v29, |v24|, v250, v248
	v_fma_f32 v31, |v25|, v251, v249
	v_fma_f32 v248, |v20|, s62, 1.0
	v_fma_f32 v249, |v21|, s62, 1.0
	v_pk_mul_f32 v[252:253], v[20:21], v[20:21]
	v_rcp_f32_e32 v248, v248
	v_rcp_f32_e32 v249, v249
	v_pk_mul_f32 v[252:253], v[252:253], s[74:75] op_sel_hi:[1,0]
	v_pk_fma_f32 v[250:251], v[248:249], s[64:65], v[254:255] op_sel_hi:[1,0,0]
	v_exp_f32_e32 v252, v252
	v_exp_f32_e32 v253, v253
	v_pk_fma_f32 v[250:251], v[248:249], v[250:251], s[68:69] op_sel_hi:[1,1,0]
	v_pk_fma_f32 v[250:251], v[248:249], v[250:251], s[70:71] op_sel_hi:[1,1,0]
	v_pk_fma_f32 v[250:251], v[248:249], v[250:251], s[72:73] op_sel_hi:[1,1,0]
	v_pk_mul_f32 v[250:251], v[248:249], v[250:251]
	v_pk_fma_f32 v[250:251], v[250:251], v[252:253], 0.5 op_sel_hi:[1,1,0] neg_lo:[1,0,0] neg_hi:[1,0,0]
	v_pk_mul_f32 v[248:249], v[20:21], 0.5 op_sel_hi:[1,0]
	v_fma_f32 v54, |v20|, v250, v248
	v_fma_f32 v33, |v21|, v251, v249
	v_fma_f32 v248, |v18|, s62, 1.0
	v_fma_f32 v249, |v19|, s62, 1.0
	v_pk_mul_f32 v[252:253], v[18:19], v[18:19]
	v_rcp_f32_e32 v248, v248
	v_rcp_f32_e32 v249, v249
	v_pk_mul_f32 v[252:253], v[252:253], s[74:75] op_sel_hi:[1,0]
	v_pk_fma_f32 v[250:251], v[248:249], s[64:65], v[254:255] op_sel_hi:[1,0,0]
	v_exp_f32_e32 v252, v252
	v_exp_f32_e32 v253, v253
	v_pk_fma_f32 v[250:251], v[248:249], v[250:251], s[68:69] op_sel_hi:[1,1,0]
	v_pk_fma_f32 v[250:251], v[248:249], v[250:251], s[70:71] op_sel_hi:[1,1,0]
	v_pk_fma_f32 v[250:251], v[248:249], v[250:251], s[72:73] op_sel_hi:[1,1,0]
	v_pk_mul_f32 v[250:251], v[248:249], v[250:251]
	v_pk_fma_f32 v[250:251], v[250:251], v[252:253], 0.5 op_sel_hi:[1,1,0] neg_lo:[1,0,0] neg_hi:[1,0,0]
	v_pk_mul_f32 v[248:249], v[18:19], 0.5 op_sel_hi:[1,0]
	v_fma_f32 v32, |v18|, v250, v248
	v_fma_f32 v56, |v19|, v251, v249
	s_andn2_b64 vcc, exec, s[90:91]
	v_mov_b64_e32 v[58:59], v[52:53]
	s_cbranch_vccnz .LBB0_394
	v_mov_b32_e32 v57, v33
	v_pk_add_f32 v[62:63], v[32:33], v[56:57]
	v_pk_mul_f32 v[64:65], v[32:33], v[56:57]
	v_mov_b32_e32 v58, v32
	v_mov_b32_e32 v63, v65
	v_pk_mul_f32 v[64:65], v[30:31], v[30:31]
	v_mov_b32_e32 v59, v56
	v_pk_fma_f32 v[64:65], v[28:29], v[28:29], v[64:65]
	v_pk_add_f32 v[60:61], v[28:29], v[30:31]
	v_pk_add_f32 v[64:65], v[64:65], v[64:65] op_sel_hi:[0,1]
	v_mul_f32_e32 v64, v58, v58
	v_pk_fma_f32 v[58:59], v[58:59], v[58:59], v[64:65] op_sel_hi:[1,1,0]
	v_mul_f32_e32 v57, v54, v54
	v_pk_add_f32 v[60:61], v[60:61], v[60:61] op_sel:[0,1] op_sel_hi:[1,0]
	v_mov_b32_e32 v55, v65
	v_mov_b32_e32 v58, v33
	v_mov_b32_e32 v61, v57
	v_pk_add_f32 v[58:59], v[54:55], v[58:59]
	v_pk_add_f32 v[60:61], v[60:61], v[62:63]
	s_nop 0
	v_pk_add_f32 v[58:59], v[60:61], v[58:59]
	s_nop 0
	v_pk_add_f32 v[58:59], v[58:59], v[52:53]

; __device__ __forceinline__ f32x2 gelu_pk(f32x2 v) {
;     const f32x2 av = __builtin_elementwise_abs(v), d = av * 0.2316418882f + 1.0f;
;     f32x2 t; t.x = __builtin_amdgcn_rcpf(d.x); t.y = __builtin_amdgcn_rcpf(d.y);
;     f32x2 q = t * 0.5307027145f + (-0.7265760135f); q = q * t + 0.7107068705f; q = q * t + (-0.142248368f); q = q * t + 0.127414796f; q = q * t;
;     const f32x2 s = (v * v) * (-0.72134752044f);
;     f32x2 e; e.x = __builtin_amdgcn_exp2f(s.x); e.y = __builtin_amdgcn_exp2f(s.y);
;     const f32x2 m = v * (q * e), r = v - m;
;     f32x2 o; o.x = v.x < 0.f ? m.x : r.x; o.y = v.y < 0.f ? m.y : r.y; return o;
; }
;     __device__ __forceinline__ void operator()(const f32x4 (&acc)[2][2][4][2], const Unit& u, int wr, int wc, int fr, int fq) const {
;     ...
;                         f32x2 a = gelu_pk((f32x2){v0[0], v0[1]}), b = gelu_pk((f32x2){v0[2], v0[3]}), c = gelu_pk((f32x2){v1[0], v1[1]}), d = gelu_pk((f32x2){v1[2], v1[3]});
;                         v0 = (f32x4){a.x, a.y, b.x, b.y}; v1 = (f32x4){c.x, c.y, d.x, d.y};
;                         if (pn >= 9) { const float t1 = (v0[0] + v0[1]) + (v0[2] + v0[3]) + (v1[0] + v1[1]) + (v1[2] + v1[3]);
;                             const float t2 = (v0[0] * v0[0] + v0[1] * v0[1]) + (v0[2] * v0[2] + v0[3] * v0[3]) + (v1[0] * v1[0] + v1[1] * v1[1]) + (v1[2] * v1[2] + v1[3] * v1[3]);
;                             if (bj == 0) { ps = t1; pss = t2; } else { ps += t1; pss += t2; } }
.LBB0_408:
	s_andn2_b64 vcc, exec, s[18:19]
	s_cbranch_vccnz .LBB0_436
	s_waitcnt vmcnt(3)
	s_waitcnt vmcnt(2)
	v_mov_b64_e32 v[254:255], s[66:67]
	v_fma_f32 v248, |v14|, s62, 1.0
	v_fma_f32 v249, |v15|, s62, 1.0
	v_pk_mul_f32 v[252:253], v[14:15], v[14:15]
	v_rcp_f32_e32 v248, v248
	v_rcp_f32_e32 v249, v249
	v_pk_mul_f32 v[252:253], v[252:253], s[74:75] op_sel_hi:[1,0]
	v_pk_fma_f32 v[250:251], v[248:249], s[64:65], v[254:255] op_sel_hi:[1,0,0]
	v_exp_f32_e32 v252, v252
	v_exp_f32_e32 v253, v253
	v_pk_fma_f32 v[250:251], v[248:249], v[250:251], s[68:69] op_sel_hi:[1,1,0]
	v_pk_fma_f32 v[250:251], v[248:249], v[250:251], s[70:71] op_sel_hi:[1,1,0]
	v_pk_fma_f32 v[250:251], v[248:249], v[250:251], s[72:73] op_sel_hi:[1,1,0]
	v_pk_mul_f32 v[250:251], v[248:249], v[250:251]
	v_pk_fma_f32 v[250:251], v[250:251], v[252:253], 0.5 op_sel_hi:[1,1,0] neg_lo:[1,0,0] neg_hi:[1,0,0]
	v_pk_mul_f32 v[248:249], v[14:15], 0.5 op_sel_hi:[1,0]
	v_fma_f32 v38, |v14|, v250, v248
	v_fma_f32 v40, |v15|, v251, v249
	v_fma_f32 v248, |v16|, s62, 1.0
	v_fma_f32 v249, |v17|, s62, 1.0
	v_pk_mul_f32 v[252:253], v[16:17], v[16:17]
	v_rcp_f32_e32 v248, v248
	v_rcp_f32_e32 v249, v249
	v_pk_mul_f32 v[252:253], v[252:253], s[74:75] op_sel_hi:[1,0]
	v_pk_fma_f32 v[250:251], v[248:249], s[64:65], v[254:255] op_sel_hi:[1,0,0]
	v_exp_f32_e32 v252, v252
	v_exp_f32_e32 v253, v253
	v_pk_fma_f32 v[250:251], v[248:249], v[250:251], s[68:69] op_sel_hi:[1,1,0]
	v_pk_fma_f32 v[250:251], v[248:249], v[250:251], s[70:71] op_sel_hi:[1,1,0]
	v_pk_fma_f32 v[250:251], v[248:249], v[250:251], s[72:73] op_sel_hi:[1,1,0]
	v_pk_mul_f32 v[250:251], v[248:249], v[250:251]
	v_pk_fma_f32 v[250:251], v[250:251], v[252:253], 0.5 op_sel_hi:[1,1,0] neg_lo:[1,0,0] neg_hi:[1,0,0]
	v_pk_mul_f32 v[248:249], v[16:17], 0.5 op_sel_hi:[1,0]
	v_fma_f32 v39, |v16|, v250, v248
	v_fma_f32 v41, |v17|, v251, v249
	v_fma_f32 v248, |v12|, s62, 1.0
	v_fma_f32 v249, |v13|, s62, 1.0
	v_pk_mul_f32 v[252:253], v[12:13], v[12:13]
	v_rcp_f32_e32 v248, v248
	v_rcp_f32_e32 v249, v249
	v_pk_mul_f32 v[252:253], v[252:253], s[74:75] op_sel_hi:[1,0]
	v_pk_fma_f32 v[250:251], v[248:249], s[64:65], v[254:255] op_sel_hi:[1,0,0]
	v_exp_f32_e32 v252, v252
	v_exp_f32_e32 v253, v253
	v_pk_fma_f32 v[250:251], v[248:249], v[250:251], s[68:69] op_sel_hi:[1,1,0]
	v_pk_fma_f32 v[250:251], v[248:249], v[250:251], s[70:71] op_sel_hi:[1,1,0]
	v_pk_fma_f32 v[250:251], v[248:249], v[250:251], s[72:73] op_sel_hi:[1,1,0]
	v_pk_mul_f32 v[250:251], v[248:249], v[250:251]
	v_pk_fma_f32 v[250:251], v[250:251], v[252:253], 0.5 op_sel_hi:[1,1,0] neg_lo:[1,0,0] neg_hi:[1,0,0]
	v_pk_mul_f32 v[248:249], v[12:13], 0.5 op_sel_hi:[1,0]
	v_fma_f32 v44, |v12|, v250, v248
	v_fma_f32 v43, |v13|, v251, v249
	v_fma_f32 v248, |v10|, s62, 1.0
	v_fma_f32 v249, |v11|, s62, 1.0
	v_pk_mul_f32 v[252:253], v[10:11], v[10:11]
	v_rcp_f32_e32 v248, v248
	v_rcp_f32_e32 v249, v249
	v_pk_mul_f32 v[252:253], v[252:253], s[74:75] op_sel_hi:[1,0]
	v_pk_fma_f32 v[250:251], v[248:249], s[64:65], v[254:255] op_sel_hi:[1,0,0]
	v_exp_f32_e32 v252, v252
	v_exp_f32_e32 v253, v253
	v_pk_fma_f32 v[250:251], v[248:249], v[250:251], s[68:69] op_sel_hi:[1,1,0]
	v_pk_fma_f32 v[250:251], v[248:249], v[250:251], s[70:71] op_sel_hi:[1,1,0]
	v_pk_fma_f32 v[250:251], v[248:249], v[250:251], s[72:73] op_sel_hi:[1,1,0]
	v_pk_mul_f32 v[250:251], v[248:249], v[250:251]
	v_pk_fma_f32 v[250:251], v[250:251], v[252:253], 0.5 op_sel_hi:[1,1,0] neg_lo:[1,0,0] neg_hi:[1,0,0]
	v_pk_mul_f32 v[248:249], v[10:11], 0.5 op_sel_hi:[1,0]
	v_fma_f32 v42, |v10|, v250, v248
	v_fma_f32 v46, |v11|, v251, v249
	s_andn2_b64 vcc, exec, s[90:91]
	s_cbranch_vccnz .LBB0_436
	v_mov_b32_e32 v47, v43
	v_pk_add_f32 v[50:51], v[42:43], v[46:47]
	v_pk_mul_f32 v[52:53], v[42:43], v[46:47]
	v_mov_b32_e32 v36, v42
	v_mov_b32_e32 v51, v53
	v_pk_mul_f32 v[52:53], v[40:41], v[40:41]
	v_mov_b32_e32 v37, v46
	v_pk_fma_f32 v[52:53], v[38:39], v[38:39], v[52:53]
	v_pk_add_f32 v[48:49], v[38:39], v[40:41]
	v_pk_add_f32 v[52:53], v[52:53], v[52:53] op_sel_hi:[0,1]
	v_mul_f32_e32 v52, v36, v36
	v_pk_fma_f32 v[36:37], v[36:37], v[36:37], v[52:53] op_sel_hi:[1,1,0]
	v_mul_f32_e32 v47, v44, v44
	v_pk_add_f32 v[48:49], v[48:49], v[48:49] op_sel:[0,1] op_sel_hi:[1,0]
	v_mov_b32_e32 v45, v53
	v_mov_b32_e32 v36, v43
	v_mov_b32_e32 v49, v47
	v_pk_add_f32 v[36:37], v[44:45], v[36:37]
	v_pk_add_f32 v[48:49], v[48:49], v[50:51]
	s_nop 0
	v_pk_add_f32 v[36:37], v[48:49], v[36:37]
	s_cbranch_execz .LBB0_412
	s_branch .LBB0_413

; __device__ __forceinline__ f32x2 gelu_pk(f32x2 v) {
;     const f32x2 av = __builtin_elementwise_abs(v), d = av * 0.2316418882f + 1.0f;
;     f32x2 t; t.x = __builtin_amdgcn_rcpf(d.x); t.y = __builtin_amdgcn_rcpf(d.y);
;     f32x2 q = t * 0.5307027145f + (-0.7265760135f); q = q * t + 0.7107068705f; q = q * t + (-0.142248368f); q = q * t + 0.127414796f; q = q * t;
;     const f32x2 s = (v * v) * (-0.72134752044f);
;     f32x2 e; e.x = __builtin_amdgcn_exp2f(s.x); e.y = __builtin_amdgcn_exp2f(s.y);
;     const f32x2 m = v * (q * e), r = v - m;
;     f32x2 o; o.x = v.x < 0.f ? m.x : r.x; o.y = v.y < 0.f ? m.y : r.y; return o;
; }
;     __device__ __forceinline__ void operator()(const f32x4 (&acc)[2][2][4][2], const Unit& u, int wr, int wc, int fr, int fq) const {
;     ...
;                         f32x2 a = gelu_pk((f32x2){v0[0], v0[1]}), b = gelu_pk((f32x2){v0[2], v0[3]}), c = gelu_pk((f32x2){v1[0], v1[1]}), d = gelu_pk((f32x2){v1[2], v1[3]});
;                         v0 = (f32x4){a.x, a.y, b.x, b.y}; v1 = (f32x4){c.x, c.y, d.x, d.y};
;                         if (pn >= 9) { const float t1 = (v0[0] + v0[1]) + (v0[2] + v0[3]) + (v1[0] + v1[1]) + (v1[2] + v1[3]);
;                             const float t2 = (v0[0] * v0[0] + v0[1] * v0[1]) + (v0[2] * v0[2] + v0[3] * v0[3]) + (v1[0] * v1[0] + v1[1] * v1[1]) + (v1[2] * v1[2] + v1[3] * v1[3]);
;                             if (bj == 0) { ps = t1; pss = t2; } else { ps += t1; pss += t2; } }
.LBB0_418:
	s_andn2_b64 vcc, exec, s[10:11]
	v_mov_b64_e32 v[42:43], v[36:37]
	s_cbranch_vccnz .LBB0_421
	v_mov_b64_e32 v[254:255], s[66:67]
	v_fma_f32 v248, |v6|, s62, 1.0
	v_fma_f32 v249, |v7|, s62, 1.0
	v_pk_mul_f32 v[252:253], v[6:7], v[6:7]
	v_rcp_f32_e32 v248, v248
	v_rcp_f32_e32 v249, v249
	v_pk_mul_f32 v[252:253], v[252:253], s[74:75] op_sel_hi:[1,0]
	v_pk_fma_f32 v[250:251], v[248:249], s[64:65], v[254:255] op_sel_hi:[1,0,0]
	v_exp_f32_e32 v252, v252
	v_exp_f32_e32 v253, v253
	v_pk_fma_f32 v[250:251], v[248:249], v[250:251], s[68:69] op_sel_hi:[1,1,0]
	v_pk_fma_f32 v[250:251], v[248:249], v[250:251], s[70:71] op_sel_hi:[1,1,0]
	v_pk_fma_f32 v[250:251], v[248:249], v[250:251], s[72:73] op_sel_hi:[1,1,0]
	v_pk_mul_f32 v[250:251], v[248:249], v[250:251]
	v_pk_fma_f32 v[250:251], v[250:251], v[252:253], 0.5 op_sel_hi:[1,1,0] neg_lo:[1,0,0] neg_hi:[1,0,0]
	v_pk_mul_f32 v[248:249], v[6:7], 0.5 op_sel_hi:[1,0]
	v_fma_f32 v12, |v6|, v250, v248
	v_fma_f32 v14, |v7|, v251, v249
	v_fma_f32 v248, |v8|, s62, 1.0
	v_fma_f32 v249, |v9|, s62, 1.0
	v_pk_mul_f32 v[252:253], v[8:9], v[8:9]
	v_rcp_f32_e32 v248, v248
	v_rcp_f32_e32 v249, v249
	v_pk_mul_f32 v[252:253], v[252:253], s[74:75] op_sel_hi:[1,0]
	v_pk_fma_f32 v[250:251], v[248:249], s[64:65], v[254:255] op_sel_hi:[1,0,0]
	v_exp_f32_e32 v252, v252
	v_exp_f32_e32 v253, v253
	v_pk_fma_f32 v[250:251], v[248:249], v[250:251], s[68:69] op_sel_hi:[1,1,0]
	v_pk_fma_f32 v[250:251], v[248:249], v[250:251], s[70:71] op_sel_hi:[1,1,0]
	v_pk_fma_f32 v[250:251], v[248:249], v[250:251], s[72:73] op_sel_hi:[1,1,0]
	v_pk_mul_f32 v[250:251], v[248:249], v[250:251]
	v_pk_fma_f32 v[250:251], v[250:251], v[252:253], 0.5 op_sel_hi:[1,1,0] neg_lo:[1,0,0] neg_hi:[1,0,0]
	v_pk_mul_f32 v[248:249], v[8:9], 0.5 op_sel_hi:[1,0]
	v_fma_f32 v13, |v8|, v250, v248
	v_fma_f32 v15, |v9|, v251, v249
	v_fma_f32 v248, |v4|, s62, 1.0
	v_fma_f32 v249, |v5|, s62, 1.0
	v_pk_mul_f32 v[252:253], v[4:5], v[4:5]
	v_rcp_f32_e32 v248, v248
	v_rcp_f32_e32 v249, v249
	v_pk_mul_f32 v[252:253], v[252:253], s[74:75] op_sel_hi:[1,0]
	v_pk_fma_f32 v[250:251], v[248:249], s[64:65], v[254:255] op_sel_hi:[1,0,0]
	v_exp_f32_e32 v252, v252
	v_exp_f32_e32 v253, v253
	v_pk_fma_f32 v[250:251], v[248:249], v[250:251], s[68:69] op_sel_hi:[1,1,0]
	v_pk_fma_f32 v[250:251], v[248:249], v[250:251], s[70:71] op_sel_hi:[1,1,0]
	v_pk_fma_f32 v[250:251], v[248:249], v[250:251], s[72:73] op_sel_hi:[1,1,0]
	v_pk_mul_f32 v[250:251], v[248:249], v[250:251]
	v_pk_fma_f32 v[250:251], v[250:251], v[252:253], 0.5 op_sel_hi:[1,1,0] neg_lo:[1,0,0] neg_hi:[1,0,0]
	v_pk_mul_f32 v[248:249], v[4:5], 0.5 op_sel_hi:[1,0]
	v_fma_f32 v38, |v4|, v250, v248
	v_fma_f32 v17, |v5|, v251, v249
	v_fma_f32 v248, |v2|, s62, 1.0
	v_fma_f32 v249, |v3|, s62, 1.0
	v_pk_mul_f32 v[252:253], v[2:3], v[2:3]
	v_rcp_f32_e32 v248, v248
	v_rcp_f32_e32 v249, v249
	v_pk_mul_f32 v[252:253], v[252:253], s[74:75] op_sel_hi:[1,0]
	v_pk_fma_f32 v[250:251], v[248:249], s[64:65], v[254:255] op_sel_hi:[1,0,0]
	v_exp_f32_e32 v252, v252
	v_exp_f32_e32 v253, v253
	v_pk_fma_f32 v[250:251], v[248:249], v[250:251], s[68:69] op_sel_hi:[1,1,0]
	v_pk_fma_f32 v[250:251], v[248:249], v[250:251], s[70:71] op_sel_hi:[1,1,0]
	v_pk_fma_f32 v[250:251], v[248:249], v[250:251], s[72:73] op_sel_hi:[1,1,0]
	v_pk_mul_f32 v[250:251], v[248:249], v[250:251]
	v_pk_fma_f32 v[250:251], v[250:251], v[252:253], 0.5 op_sel_hi:[1,1,0] neg_lo:[1,0,0] neg_hi:[1,0,0]
	v_pk_mul_f32 v[248:249], v[2:3], 0.5 op_sel_hi:[1,0]
	v_fma_f32 v16, |v2|, v250, v248
	v_fma_f32 v40, |v3|, v251, v249
	s_andn2_b64 vcc, exec, s[90:91]
	v_mov_b64_e32 v[42:43], v[36:37]
	s_cbranch_vccnz .LBB0_421
	v_mov_b32_e32 v41, v17
	v_pk_add_f32 v[46:47], v[16:17], v[40:41]
	v_pk_mul_f32 v[48:49], v[16:17], v[40:41]
	v_mov_b32_e32 v42, v16
	v_mov_b32_e32 v47, v49
	v_pk_mul_f32 v[48:49], v[14:15], v[14:15]
	v_mov_b32_e32 v43, v40
	v_pk_fma_f32 v[48:49], v[12:13], v[12:13], v[48:49]
	v_pk_add_f32 v[44:45], v[12:13], v[14:15]
	v_pk_add_f32 v[48:49], v[48:49], v[48:49] op_sel_hi:[0,1]
	v_mul_f32_e32 v48, v42, v42
	v_pk_fma_f32 v[42:43], v[42:43], v[42:43], v[48:49] op_sel_hi:[1,1,0]
	v_mul_f32_e32 v41, v38, v38
	v_pk_add_f32 v[44:45], v[44:45], v[44:45] op_sel:[0,1] op_sel_hi:[1,0]
	v_mov_b32_e32 v39, v49
	v_mov_b32_e32 v42, v17
	v_mov_b32_e32 v45, v41
	v_pk_add_f32 v[42:43], v[38:39], v[42:43]
	v_pk_add_f32 v[44:45], v[44:45], v[46:47]
	s_nop 0
	v_pk_add_f32 v[42:43], v[44:45], v[42:43]
	s_nop 0
	v_pk_add_f32 v[42:43], v[42:43], v[36:37]

; __device__ __forceinline__ f32x2 gelu_pk(f32x2 v) {
;     const f32x2 av = __builtin_elementwise_abs(v), d = av * 0.2316418882f + 1.0f;
;     f32x2 t; t.x = __builtin_amdgcn_rcpf(d.x); t.y = __builtin_amdgcn_rcpf(d.y);
;     f32x2 q = t * 0.5307027145f + (-0.7265760135f); q = q * t + 0.7107068705f; q = q * t + (-0.142248368f); q = q * t + 0.127414796f; q = q * t;
;     const f32x2 s = (v * v) * (-0.72134752044f);
;     f32x2 e; e.x = __builtin_amdgcn_exp2f(s.x); e.y = __builtin_amdgcn_exp2f(s.y);
;     const f32x2 m = v * (q * e), r = v - m;
;     f32x2 o; o.x = v.x < 0.f ? m.x : r.x; o.y = v.y < 0.f ? m.y : r.y; return o;
; }
;     __device__ __forceinline__ void operator()(const f32x4 (&acc)[2][2][4][2], const Unit& u, int wr, int wc, int fr, int fq) const {
;     ...
;                         f32x2 a = gelu_pk((f32x2){v0[0], v0[1]}), b = gelu_pk((f32x2){v0[2], v0[3]}), c = gelu_pk((f32x2){v1[0], v1[1]}), d = gelu_pk((f32x2){v1[2], v1[3]});
;                         v0 = (f32x4){a.x, a.y, b.x, b.y}; v1 = (f32x4){c.x, c.y, d.x, d.y};
;                         if (pn >= 9) { const float t1 = (v0[0] + v0[1]) + (v0[2] + v0[3]) + (v1[0] + v1[1]) + (v1[2] + v1[3]);
;                             const float t2 = (v0[0] * v0[0] + v0[1] * v0[1]) + (v0[2] * v0[2] + v0[3] * v0[3]) + (v1[0] * v1[0] + v1[1] * v1[1]) + (v1[2] * v1[2] + v1[3] * v1[3]);
;                             if (bj == 0) { ps = t1; pss = t2; } else { ps += t1; pss += t2; } }
.LBB0_1119:
	s_andn2_b64 vcc, exec, s[14:15]
	s_cbranch_vccnz .LBB0_1122
	v_mov_b64_e32 v[254:255], s[64:65]
	v_fma_f32 v248, |v126|, s60, 1.0
	v_fma_f32 v249, |v127|, s60, 1.0
	v_pk_mul_f32 v[252:253], v[126:127], v[126:127]
	v_rcp_f32_e32 v248, v248
	v_rcp_f32_e32 v249, v249
	v_pk_mul_f32 v[252:253], v[252:253], s[72:73] op_sel_hi:[1,0]
	v_pk_fma_f32 v[250:251], v[248:249], s[62:63], v[254:255] op_sel_hi:[1,0,0]
	v_exp_f32_e32 v252, v252
	v_exp_f32_e32 v253, v253
	v_pk_fma_f32 v[250:251], v[248:249], v[250:251], s[66:67] op_sel_hi:[1,1,0]
	v_pk_fma_f32 v[250:251], v[248:249], v[250:251], s[68:69] op_sel_hi:[1,1,0]
	v_pk_fma_f32 v[250:251], v[248:249], v[250:251], s[70:71] op_sel_hi:[1,1,0]
	v_pk_mul_f32 v[250:251], v[248:249], v[250:251]
	v_pk_fma_f32 v[250:251], v[250:251], v[252:253], 0.5 op_sel_hi:[1,1,0] neg_lo:[1,0,0] neg_hi:[1,0,0]
	v_pk_mul_f32 v[248:249], v[126:127], 0.5 op_sel_hi:[1,0]
	v_fma_f32 v184, |v126|, v250, v248
	v_fma_f32 v186, |v127|, v251, v249
	v_fma_f32 v248, |v128|, s60, 1.0
	v_fma_f32 v249, |v129|, s60, 1.0
	v_pk_mul_f32 v[252:253], v[128:129], v[128:129]
	v_rcp_f32_e32 v248, v248
	v_rcp_f32_e32 v249, v249
	v_pk_mul_f32 v[252:253], v[252:253], s[72:73] op_sel_hi:[1,0]
	v_pk_fma_f32 v[250:251], v[248:249], s[62:63], v[254:255] op_sel_hi:[1,0,0]
	v_exp_f32_e32 v252, v252
	v_exp_f32_e32 v253, v253
	v_pk_fma_f32 v[250:251], v[248:249], v[250:251], s[66:67] op_sel_hi:[1,1,0]
	v_pk_fma_f32 v[250:251], v[248:249], v[250:251], s[68:69] op_sel_hi:[1,1,0]
	v_pk_fma_f32 v[250:251], v[248:249], v[250:251], s[70:71] op_sel_hi:[1,1,0]
	v_pk_mul_f32 v[250:251], v[248:249], v[250:251]
	v_pk_fma_f32 v[250:251], v[250:251], v[252:253], 0.5 op_sel_hi:[1,1,0] neg_lo:[1,0,0] neg_hi:[1,0,0]
	v_pk_mul_f32 v[248:249], v[128:129], 0.5 op_sel_hi:[1,0]
	v_fma_f32 v185, |v128|, v250, v248
	v_fma_f32 v187, |v129|, v251, v249
	v_fma_f32 v248, |v124|, s60, 1.0
	v_fma_f32 v249, |v125|, s60, 1.0
	v_pk_mul_f32 v[252:253], v[124:125], v[124:125]
	v_rcp_f32_e32 v248, v248
	v_rcp_f32_e32 v249, v249
	v_pk_mul_f32 v[252:253], v[252:253], s[72:73] op_sel_hi:[1,0]
	v_pk_fma_f32 v[250:251], v[248:249], s[62:63], v[254:255] op_sel_hi:[1,0,0]
	v_exp_f32_e32 v252, v252
	v_exp_f32_e32 v253, v253
	v_pk_fma_f32 v[250:251], v[248:249], v[250:251], s[66:67] op_sel_hi:[1,1,0]
	v_pk_fma_f32 v[250:251], v[248:249], v[250:251], s[68:69] op_sel_hi:[1,1,0]
	v_pk_fma_f32 v[250:251], v[248:249], v[250:251], s[70:71] op_sel_hi:[1,1,0]
	v_pk_mul_f32 v[250:251], v[248:249], v[250:251]
	v_pk_fma_f32 v[250:251], v[250:251], v[252:253], 0.5 op_sel_hi:[1,1,0] neg_lo:[1,0,0] neg_hi:[1,0,0]
	v_pk_mul_f32 v[248:249], v[124:125], 0.5 op_sel_hi:[1,0]
	v_fma_f32 v190, |v124|, v250, v248
	v_fma_f32 v189, |v125|, v251, v249
	v_fma_f32 v248, |v122|, s60, 1.0
	v_fma_f32 v249, |v123|, s60, 1.0
	v_pk_mul_f32 v[252:253], v[122:123], v[122:123]
	v_rcp_f32_e32 v248, v248
	v_rcp_f32_e32 v249, v249
	v_pk_mul_f32 v[252:253], v[252:253], s[72:73] op_sel_hi:[1,0]
	v_pk_fma_f32 v[250:251], v[248:249], s[62:63], v[254:255] op_sel_hi:[1,0,0]
	v_exp_f32_e32 v252, v252
	v_exp_f32_e32 v253, v253
	v_pk_fma_f32 v[250:251], v[248:249], v[250:251], s[66:67] op_sel_hi:[1,1,0]
	v_pk_fma_f32 v[250:251], v[248:249], v[250:251], s[68:69] op_sel_hi:[1,1,0]
	v_pk_fma_f32 v[250:251], v[248:249], v[250:251], s[70:71] op_sel_hi:[1,1,0]
	v_pk_mul_f32 v[250:251], v[248:249], v[250:251]
	v_pk_fma_f32 v[250:251], v[250:251], v[252:253], 0.5 op_sel_hi:[1,1,0] neg_lo:[1,0,0] neg_hi:[1,0,0]
	v_pk_mul_f32 v[248:249], v[122:123], 0.5 op_sel_hi:[1,0]
	v_fma_f32 v188, |v122|, v250, v248
	v_fma_f32 v192, |v123|, v251, v249
	s_andn2_b64 vcc, exec, s[88:89]
	s_cbranch_vccnz .LBB0_1122
	v_mov_b32_e32 v193, v189
	v_pk_add_f32 v[202:203], v[188:189], v[192:193]
	v_pk_mul_f32 v[204:205], v[188:189], v[192:193]
	v_mov_b32_e32 v182, v188
	v_mov_b32_e32 v203, v205
	v_pk_mul_f32 v[204:205], v[186:187], v[186:187]
	v_mov_b32_e32 v183, v192
	v_pk_add_f32 v[200:201], v[184:185], v[186:187]
	v_pk_fma_f32 v[204:205], v[184:185], v[184:185], v[204:205]
	v_mul_f32_e32 v154, v182, v182
	v_pk_add_f32 v[204:205], v[204:205], v[204:205] op_sel_hi:[0,1]
	v_pk_fma_f32 v[182:183], v[182:183], v[182:183], v[154:155] op_sel_hi:[1,1,0]
	v_mul_f32_e32 v154, v190, v190
	v_pk_add_f32 v[200:201], v[200:201], v[200:201] op_sel:[0,1] op_sel_hi:[1,0]
	v_mov_b32_e32 v191, v205
	v_mov_b32_e32 v182, v189
	v_mov_b32_e32 v201, v154
	v_pk_add_f32 v[182:183], v[190:191], v[182:183]
	v_pk_add_f32 v[200:201], v[200:201], v[202:203]
	s_mov_b64 s[14:15], 0
	v_pk_add_f32 v[182:183], v[200:201], v[182:183]
	s_branch .LBB0_1123

; __device__ __forceinline__ f32x2 gelu_pk(f32x2 v) {
;     const f32x2 av = __builtin_elementwise_abs(v), d = av * 0.2316418882f + 1.0f;
;     f32x2 t; t.x = __builtin_amdgcn_rcpf(d.x); t.y = __builtin_amdgcn_rcpf(d.y);
;     f32x2 q = t * 0.5307027145f + (-0.7265760135f); q = q * t + 0.7107068705f; q = q * t + (-0.142248368f); q = q * t + 0.127414796f; q = q * t;
;     const f32x2 s = (v * v) * (-0.72134752044f);
;     f32x2 e; e.x = __builtin_amdgcn_exp2f(s.x); e.y = __builtin_amdgcn_exp2f(s.y);
;     const f32x2 m = v * (q * e), r = v - m;
;     f32x2 o; o.x = v.x < 0.f ? m.x : r.x; o.y = v.y < 0.f ? m.y : r.y; return o;
; }
;     __device__ __forceinline__ void operator()(const f32x4 (&acc)[2][2][4][2], const Unit& u, int wr, int wc, int fr, int fq) const {
;     ...
;                     } else if (kind == 2) {
;                         f32x2 a = gelu_pk((f32x2){v0[0], v0[1]}), b = gelu_pk((f32x2){v0[2], v0[3]}), c = gelu_pk((f32x2){v1[0], v1[1]}), d = gelu_pk((f32x2){v1[2], v1[3]});
;                         v0 = (f32x4){a.x, a.y, b.x, b.y}; v1 = (f32x4){c.x, c.y, d.x, d.y};
;                         if (pn >= 9) { const float t1 = (v0[0] + v0[1]) + (v0[2] + v0[3]) + (v1[0] + v1[1]) + (v1[2] + v1[3]);
;                             const float t2 = (v0[0] * v0[0] + v0[1] * v0[1]) + (v0[2] * v0[2] + v0[3] * v0[3]) + (v1[0] * v1[0] + v1[1] * v1[1]) + (v1[2] * v1[2] + v1[3] * v1[3]);
;                             if (bj == 0) { ps = t1; pss = t2; } else { ps += t1; pss += t2; } }
.LBB0_1130:
	s_andn2_b64 vcc, exec, s[42:43]
	v_mov_b64_e32 v[188:189], v[182:183]
	s_cbranch_vccnz .LBB0_1133
	v_mov_b64_e32 v[254:255], s[64:65]
	v_fma_f32 v248, |v118|, s60, 1.0
	v_fma_f32 v249, |v119|, s60, 1.0
	v_pk_mul_f32 v[252:253], v[118:119], v[118:119]
	v_rcp_f32_e32 v248, v248
	v_rcp_f32_e32 v249, v249
	v_pk_mul_f32 v[252:253], v[252:253], s[72:73] op_sel_hi:[1,0]
	v_pk_fma_f32 v[250:251], v[248:249], s[62:63], v[254:255] op_sel_hi:[1,0,0]
	v_exp_f32_e32 v252, v252
	v_exp_f32_e32 v253, v253
	v_pk_fma_f32 v[250:251], v[248:249], v[250:251], s[66:67] op_sel_hi:[1,1,0]
	v_pk_fma_f32 v[250:251], v[248:249], v[250:251], s[68:69] op_sel_hi:[1,1,0]
	v_pk_fma_f32 v[250:251], v[248:249], v[250:251], s[70:71] op_sel_hi:[1,1,0]
	v_pk_mul_f32 v[250:251], v[248:249], v[250:251]
	v_pk_fma_f32 v[250:251], v[250:251], v[252:253], 0.5 op_sel_hi:[1,1,0] neg_lo:[1,0,0] neg_hi:[1,0,0]
	v_pk_mul_f32 v[248:249], v[118:119], 0.5 op_sel_hi:[1,0]
	v_fma_f32 v124, |v118|, v250, v248
	v_fma_f32 v126, |v119|, v251, v249
	v_fma_f32 v248, |v120|, s60, 1.0
	v_fma_f32 v249, |v121|, s60, 1.0
	v_pk_mul_f32 v[252:253], v[120:121], v[120:121]
	v_rcp_f32_e32 v248, v248
	v_rcp_f32_e32 v249, v249
	v_pk_mul_f32 v[252:253], v[252:253], s[72:73] op_sel_hi:[1,0]
	v_pk_fma_f32 v[250:251], v[248:249], s[62:63], v[254:255] op_sel_hi:[1,0,0]
	v_exp_f32_e32 v252, v252
	v_exp_f32_e32 v253, v253
	v_pk_fma_f32 v[250:251], v[248:249], v[250:251], s[66:67] op_sel_hi:[1,1,0]
	v_pk_fma_f32 v[250:251], v[248:249], v[250:251], s[68:69] op_sel_hi:[1,1,0]
	v_pk_fma_f32 v[250:251], v[248:249], v[250:251], s[70:71] op_sel_hi:[1,1,0]
	v_pk_mul_f32 v[250:251], v[248:249], v[250:251]
	v_pk_fma_f32 v[250:251], v[250:251], v[252:253], 0.5 op_sel_hi:[1,1,0] neg_lo:[1,0,0] neg_hi:[1,0,0]
	v_pk_mul_f32 v[248:249], v[120:121], 0.5 op_sel_hi:[1,0]
	v_fma_f32 v125, |v120|, v250, v248
	v_fma_f32 v127, |v121|, v251, v249
	v_fma_f32 v248, |v116|, s60, 1.0
	v_fma_f32 v249, |v117|, s60, 1.0
	v_pk_mul_f32 v[252:253], v[116:117], v[116:117]
	v_rcp_f32_e32 v248, v248
	v_rcp_f32_e32 v249, v249
	v_pk_mul_f32 v[252:253], v[252:253], s[72:73] op_sel_hi:[1,0]
	v_pk_fma_f32 v[250:251], v[248:249], s[62:63], v[254:255] op_sel_hi:[1,0,0]
	v_exp_f32_e32 v252, v252
	v_exp_f32_e32 v253, v253
	v_pk_fma_f32 v[250:251], v[248:249], v[250:251], s[66:67] op_sel_hi:[1,1,0]
	v_pk_fma_f32 v[250:251], v[248:249], v[250:251], s[68:69] op_sel_hi:[1,1,0]
	v_pk_fma_f32 v[250:251], v[248:249], v[250:251], s[70:71] op_sel_hi:[1,1,0]
	v_pk_mul_f32 v[250:251], v[248:249], v[250:251]
	v_pk_fma_f32 v[250:251], v[250:251], v[252:253], 0.5 op_sel_hi:[1,1,0] neg_lo:[1,0,0] neg_hi:[1,0,0]
	v_pk_mul_f32 v[248:249], v[116:117], 0.5 op_sel_hi:[1,0]
	v_fma_f32 v184, |v116|, v250, v248
	v_fma_f32 v129, |v117|, v251, v249
	v_fma_f32 v248, |v114|, s60, 1.0
	v_fma_f32 v249, |v115|, s60, 1.0
	v_pk_mul_f32 v[252:253], v[114:115], v[114:115]
	v_rcp_f32_e32 v248, v248
	v_rcp_f32_e32 v249, v249
	v_pk_mul_f32 v[252:253], v[252:253], s[72:73] op_sel_hi:[1,0]
	v_pk_fma_f32 v[250:251], v[248:249], s[62:63], v[254:255] op_sel_hi:[1,0,0]
	v_exp_f32_e32 v252, v252
	v_exp_f32_e32 v253, v253
	v_pk_fma_f32 v[250:251], v[248:249], v[250:251], s[66:67] op_sel_hi:[1,1,0]
	v_pk_fma_f32 v[250:251], v[248:249], v[250:251], s[68:69] op_sel_hi:[1,1,0]
	v_pk_fma_f32 v[250:251], v[248:249], v[250:251], s[70:71] op_sel_hi:[1,1,0]
	v_pk_mul_f32 v[250:251], v[248:249], v[250:251]
	v_pk_fma_f32 v[250:251], v[250:251], v[252:253], 0.5 op_sel_hi:[1,1,0] neg_lo:[1,0,0] neg_hi:[1,0,0]
	v_pk_mul_f32 v[248:249], v[114:115], 0.5 op_sel_hi:[1,0]
	v_fma_f32 v128, |v114|, v250, v248
	v_fma_f32 v186, |v115|, v251, v249
	s_andn2_b64 vcc, exec, s[88:89]
	v_mov_b64_e32 v[188:189], v[182:183]
	s_cbranch_vccnz .LBB0_1133
	v_mov_b32_e32 v187, v129
	v_pk_add_f32 v[192:193], v[128:129], v[186:187]
	v_pk_mul_f32 v[200:201], v[128:129], v[186:187]
	v_mov_b32_e32 v188, v128
	v_mov_b32_e32 v193, v201
	v_pk_mul_f32 v[200:201], v[126:127], v[126:127]
	v_mov_b32_e32 v189, v186
	v_pk_add_f32 v[190:191], v[124:125], v[126:127]
	v_pk_fma_f32 v[200:201], v[124:125], v[124:125], v[200:201]
	v_mul_f32_e32 v154, v188, v188
	v_pk_add_f32 v[200:201], v[200:201], v[200:201] op_sel_hi:[0,1]
	v_pk_fma_f32 v[188:189], v[188:189], v[188:189], v[154:155] op_sel_hi:[1,1,0]
	v_mul_f32_e32 v154, v184, v184
	v_pk_add_f32 v[190:191], v[190:191], v[190:191] op_sel:[0,1] op_sel_hi:[1,0]
	v_mov_b32_e32 v185, v201
	v_mov_b32_e32 v188, v129
	v_mov_b32_e32 v191, v154
	v_pk_add_f32 v[188:189], v[184:185], v[188:189]
	v_pk_add_f32 v[190:191], v[190:191], v[192:193]
	s_nop 0
	v_pk_add_f32 v[188:189], v[190:191], v[188:189]
	s_nop 0
	v_pk_add_f32 v[188:189], v[188:189], v[182:183]

; __device__ __forceinline__ f32x2 gelu_pk(f32x2 v) {
;     const f32x2 av = __builtin_elementwise_abs(v), d = av * 0.2316418882f + 1.0f;
;     f32x2 t; t.x = __builtin_amdgcn_rcpf(d.x); t.y = __builtin_amdgcn_rcpf(d.y);
;     f32x2 q = t * 0.5307027145f + (-0.7265760135f); q = q * t + 0.7107068705f; q = q * t + (-0.142248368f); q = q * t + 0.127414796f; q = q * t;
;     const f32x2 s = (v * v) * (-0.72134752044f);
;     f32x2 e; e.x = __builtin_amdgcn_exp2f(s.x); e.y = __builtin_amdgcn_exp2f(s.y);
;     const f32x2 m = v * (q * e), r = v - m;
;     f32x2 o; o.x = v.x < 0.f ? m.x : r.x; o.y = v.y < 0.f ? m.y : r.y; return o;
; }
;     __device__ __forceinline__ void operator()(const f32x4 (&acc)[2][2][4][2], const Unit& u, int wr, int wc, int fr, int fq) const {
;     ...
;                     } else if (kind == 2) {
;                         f32x2 a = gelu_pk((f32x2){v0[0], v0[1]}), b = gelu_pk((f32x2){v0[2], v0[3]}), c = gelu_pk((f32x2){v1[0], v1[1]}), d = gelu_pk((f32x2){v1[2], v1[3]});
;                         v0 = (f32x4){a.x, a.y, b.x, b.y}; v1 = (f32x4){c.x, c.y, d.x, d.y};
;                         if (pn >= 9) { const float t1 = (v0[0] + v0[1]) + (v0[2] + v0[3]) + (v1[0] + v1[1]) + (v1[2] + v1[3]);
;                             const float t2 = (v0[0] * v0[0] + v0[1] * v0[1]) + (v0[2] * v0[2] + v0[3] * v0[3]) + (v1[0] * v1[0] + v1[1] * v1[1]) + (v1[2] * v1[2] + v1[3] * v1[3]);
;                             if (bj == 0) { ps = t1; pss = t2; } else { ps += t1; pss += t2; } }
.LBB0_1147:
	s_andn2_b64 vcc, exec, s[22:23]
	s_cbranch_vccnz .LBB0_1150
	v_mov_b64_e32 v[254:255], s[64:65]
	v_fma_f32 v248, |v110|, s60, 1.0
	v_fma_f32 v249, |v111|, s60, 1.0
	v_pk_mul_f32 v[252:253], v[110:111], v[110:111]
	v_rcp_f32_e32 v248, v248
	v_rcp_f32_e32 v249, v249
	v_pk_mul_f32 v[252:253], v[252:253], s[72:73] op_sel_hi:[1,0]
	v_pk_fma_f32 v[250:251], v[248:249], s[62:63], v[254:255] op_sel_hi:[1,0,0]
	v_exp_f32_e32 v252, v252
	v_exp_f32_e32 v253, v253
	v_pk_fma_f32 v[250:251], v[248:249], v[250:251], s[66:67] op_sel_hi:[1,1,0]
	v_pk_fma_f32 v[250:251], v[248:249], v[250:251], s[68:69] op_sel_hi:[1,1,0]
	v_pk_fma_f32 v[250:251], v[248:249], v[250:251], s[70:71] op_sel_hi:[1,1,0]
	v_pk_mul_f32 v[250:251], v[248:249], v[250:251]
	v_pk_fma_f32 v[250:251], v[250:251], v[252:253], 0.5 op_sel_hi:[1,1,0] neg_lo:[1,0,0] neg_hi:[1,0,0]
	v_pk_mul_f32 v[248:249], v[110:111], 0.5 op_sel_hi:[1,0]
	v_fma_f32 v134, |v110|, v250, v248
	v_fma_f32 v136, |v111|, v251, v249
	v_fma_f32 v248, |v112|, s60, 1.0
	v_fma_f32 v249, |v113|, s60, 1.0
	v_pk_mul_f32 v[252:253], v[112:113], v[112:113]
	v_rcp_f32_e32 v248, v248
	v_rcp_f32_e32 v249, v249
	v_pk_mul_f32 v[252:253], v[252:253], s[72:73] op_sel_hi:[1,0]
	v_pk_fma_f32 v[250:251], v[248:249], s[62:63], v[254:255] op_sel_hi:[1,0,0]
	v_exp_f32_e32 v252, v252
	v_exp_f32_e32 v253, v253
	v_pk_fma_f32 v[250:251], v[248:249], v[250:251], s[66:67] op_sel_hi:[1,1,0]
	v_pk_fma_f32 v[250:251], v[248:249], v[250:251], s[68:69] op_sel_hi:[1,1,0]
	v_pk_fma_f32 v[250:251], v[248:249], v[250:251], s[70:71] op_sel_hi:[1,1,0]
	v_pk_mul_f32 v[250:251], v[248:249], v[250:251]
	v_pk_fma_f32 v[250:251], v[250:251], v[252:253], 0.5 op_sel_hi:[1,1,0] neg_lo:[1,0,0] neg_hi:[1,0,0]
	v_pk_mul_f32 v[248:249], v[112:113], 0.5 op_sel_hi:[1,0]
	v_fma_f32 v135, |v112|, v250, v248
	v_fma_f32 v137, |v113|, v251, v249
	v_fma_f32 v248, |v108|, s60, 1.0
	v_fma_f32 v249, |v109|, s60, 1.0
	v_pk_mul_f32 v[252:253], v[108:109], v[108:109]
	v_rcp_f32_e32 v248, v248
	v_rcp_f32_e32 v249, v249
	v_pk_mul_f32 v[252:253], v[252:253], s[72:73] op_sel_hi:[1,0]
	v_pk_fma_f32 v[250:251], v[248:249], s[62:63], v[254:255] op_sel_hi:[1,0,0]
	v_exp_f32_e32 v252, v252
	v_exp_f32_e32 v253, v253
	v_pk_fma_f32 v[250:251], v[248:249], v[250:251], s[66:67] op_sel_hi:[1,1,0]
	v_pk_fma_f32 v[250:251], v[248:249], v[250:251], s[68:69] op_sel_hi:[1,1,0]
	v_pk_fma_f32 v[250:251], v[248:249], v[250:251], s[70:71] op_sel_hi:[1,1,0]
	v_pk_mul_f32 v[250:251], v[248:249], v[250:251]
	v_pk_fma_f32 v[250:251], v[250:251], v[252:253], 0.5 op_sel_hi:[1,1,0] neg_lo:[1,0,0] neg_hi:[1,0,0]
	v_pk_mul_f32 v[248:249], v[108:109], 0.5 op_sel_hi:[1,0]
	v_fma_f32 v140, |v108|, v250, v248
	v_fma_f32 v139, |v109|, v251, v249
	v_fma_f32 v248, |v106|, s60, 1.0
	v_fma_f32 v249, |v107|, s60, 1.0
	v_pk_mul_f32 v[252:253], v[106:107], v[106:107]
	v_rcp_f32_e32 v248, v248
	v_rcp_f32_e32 v249, v249
	v_pk_mul_f32 v[252:253], v[252:253], s[72:73] op_sel_hi:[1,0]
	v_pk_fma_f32 v[250:251], v[248:249], s[62:63], v[254:255] op_sel_hi:[1,0,0]
	v_exp_f32_e32 v252, v252
	v_exp_f32_e32 v253, v253
	v_pk_fma_f32 v[250:251], v[248:249], v[250:251], s[66:67] op_sel_hi:[1,1,0]
	v_pk_fma_f32 v[250:251], v[248:249], v[250:251], s[68:69] op_sel_hi:[1,1,0]
	v_pk_fma_f32 v[250:251], v[248:249], v[250:251], s[70:71] op_sel_hi:[1,1,0]
	v_pk_mul_f32 v[250:251], v[248:249], v[250:251]
	v_pk_fma_f32 v[250:251], v[250:251], v[252:253], 0.5 op_sel_hi:[1,1,0] neg_lo:[1,0,0] neg_hi:[1,0,0]
	v_pk_mul_f32 v[248:249], v[106:107], 0.5 op_sel_hi:[1,0]
	v_fma_f32 v138, |v106|, v250, v248
	v_fma_f32 v142, |v107|, v251, v249
	s_andn2_b64 vcc, exec, s[88:89]
	s_cbranch_vccnz .LBB0_1150
	v_mov_b32_e32 v143, v139
	v_pk_add_f32 v[182:183], v[138:139], v[142:143]
	v_pk_mul_f32 v[184:185], v[138:139], v[142:143]
	v_mov_b32_e32 v132, v138
	v_mov_b32_e32 v183, v185
	v_pk_mul_f32 v[184:185], v[136:137], v[136:137]
	v_mov_b32_e32 v133, v142
	v_pk_add_f32 v[144:145], v[134:135], v[136:137]
	v_pk_fma_f32 v[184:185], v[134:135], v[134:135], v[184:185]
	v_mul_f32_e32 v154, v132, v132
	v_pk_add_f32 v[184:185], v[184:185], v[184:185] op_sel_hi:[0,1]
	v_pk_fma_f32 v[132:133], v[132:133], v[132:133], v[154:155] op_sel_hi:[1,1,0]
	v_mul_f32_e32 v143, v140, v140
	v_pk_add_f32 v[144:145], v[144:145], v[144:145] op_sel:[0,1] op_sel_hi:[1,0]
	v_mov_b32_e32 v141, v185
	v_mov_b32_e32 v132, v139
	v_mov_b32_e32 v145, v143
	v_pk_add_f32 v[132:133], v[140:141], v[132:133]
	v_pk_add_f32 v[144:145], v[144:145], v[182:183]
	s_nop 0
	v_pk_add_f32 v[132:133], v[144:145], v[132:133]
	s_branch .LBB0_1151

; __device__ __forceinline__ f32x2 gelu_pk(f32x2 v) {
;     const f32x2 av = __builtin_elementwise_abs(v), d = av * 0.2316418882f + 1.0f;
;     f32x2 t; t.x = __builtin_amdgcn_rcpf(d.x); t.y = __builtin_amdgcn_rcpf(d.y);
;     f32x2 q = t * 0.5307027145f + (-0.7265760135f); q = q * t + 0.7107068705f; q = q * t + (-0.142248368f); q = q * t + 0.127414796f; q = q * t;
;     const f32x2 s = (v * v) * (-0.72134752044f);
;     f32x2 e; e.x = __builtin_amdgcn_exp2f(s.x); e.y = __builtin_amdgcn_exp2f(s.y);
;     const f32x2 m = v * (q * e), r = v - m;
;     f32x2 o; o.x = v.x < 0.f ? m.x : r.x; o.y = v.y < 0.f ? m.y : r.y; return o;
; }
;     __device__ __forceinline__ void operator()(const f32x4 (&acc)[2][2][4][2], const Unit& u, int wr, int wc, int fr, int fq) const {
;     ...
;                     } else if (kind == 2) {
;                         f32x2 a = gelu_pk((f32x2){v0[0], v0[1]}), b = gelu_pk((f32x2){v0[2], v0[3]}), c = gelu_pk((f32x2){v1[0], v1[1]}), d = gelu_pk((f32x2){v1[2], v1[3]});
;                         v0 = (f32x4){a.x, a.y, b.x, b.y}; v1 = (f32x4){c.x, c.y, d.x, d.y};
;                         if (pn >= 9) { const float t1 = (v0[0] + v0[1]) + (v0[2] + v0[3]) + (v1[0] + v1[1]) + (v1[2] + v1[3]);
;                             const float t2 = (v0[0] * v0[0] + v0[1] * v0[1]) + (v0[2] * v0[2] + v0[3] * v0[3]) + (v1[0] * v1[0] + v1[1] * v1[1]) + (v1[2] * v1[2] + v1[3] * v1[3]);
;                             if (bj == 0) { ps = t1; pss = t2; } else { ps += t1; pss += t2; } }
.LBB0_1159:
	s_andn2_b64 vcc, exec, s[22:23]
	v_mov_b64_e32 v[138:139], v[132:133]
	s_cbranch_vccnz .LBB0_1162
	v_mov_b64_e32 v[254:255], s[64:65]
	v_fma_f32 v248, |v102|, s60, 1.0
	v_fma_f32 v249, |v103|, s60, 1.0
	v_pk_mul_f32 v[252:253], v[102:103], v[102:103]
	v_rcp_f32_e32 v248, v248
	v_rcp_f32_e32 v249, v249
	v_pk_mul_f32 v[252:253], v[252:253], s[72:73] op_sel_hi:[1,0]
	v_pk_fma_f32 v[250:251], v[248:249], s[62:63], v[254:255] op_sel_hi:[1,0,0]
	v_exp_f32_e32 v252, v252
	v_exp_f32_e32 v253, v253
	v_pk_fma_f32 v[250:251], v[248:249], v[250:251], s[66:67] op_sel_hi:[1,1,0]
	v_pk_fma_f32 v[250:251], v[248:249], v[250:251], s[68:69] op_sel_hi:[1,1,0]
	v_pk_fma_f32 v[250:251], v[248:249], v[250:251], s[70:71] op_sel_hi:[1,1,0]
	v_pk_mul_f32 v[250:251], v[248:249], v[250:251]
	v_pk_fma_f32 v[250:251], v[250:251], v[252:253], 0.5 op_sel_hi:[1,1,0] neg_lo:[1,0,0] neg_hi:[1,0,0]
	v_pk_mul_f32 v[248:249], v[102:103], 0.5 op_sel_hi:[1,0]
	v_fma_f32 v108, |v102|, v250, v248
	v_fma_f32 v110, |v103|, v251, v249
	v_fma_f32 v248, |v104|, s60, 1.0
	v_fma_f32 v249, |v105|, s60, 1.0
	v_pk_mul_f32 v[252:253], v[104:105], v[104:105]
	v_rcp_f32_e32 v248, v248
	v_rcp_f32_e32 v249, v249
	v_pk_mul_f32 v[252:253], v[252:253], s[72:73] op_sel_hi:[1,0]
	v_pk_fma_f32 v[250:251], v[248:249], s[62:63], v[254:255] op_sel_hi:[1,0,0]
	v_exp_f32_e32 v252, v252
	v_exp_f32_e32 v253, v253
	v_pk_fma_f32 v[250:251], v[248:249], v[250:251], s[66:67] op_sel_hi:[1,1,0]
	v_pk_fma_f32 v[250:251], v[248:249], v[250:251], s[68:69] op_sel_hi:[1,1,0]
	v_pk_fma_f32 v[250:251], v[248:249], v[250:251], s[70:71] op_sel_hi:[1,1,0]
	v_pk_mul_f32 v[250:251], v[248:249], v[250:251]
	v_pk_fma_f32 v[250:251], v[250:251], v[252:253], 0.5 op_sel_hi:[1,1,0] neg_lo:[1,0,0] neg_hi:[1,0,0]
	v_pk_mul_f32 v[248:249], v[104:105], 0.5 op_sel_hi:[1,0]
	v_fma_f32 v109, |v104|, v250, v248
	v_fma_f32 v111, |v105|, v251, v249
	v_fma_f32 v248, |v100|, s60, 1.0
	v_fma_f32 v249, |v101|, s60, 1.0
	v_pk_mul_f32 v[252:253], v[100:101], v[100:101]
	v_rcp_f32_e32 v248, v248
	v_rcp_f32_e32 v249, v249
	v_pk_mul_f32 v[252:253], v[252:253], s[72:73] op_sel_hi:[1,0]
	v_pk_fma_f32 v[250:251], v[248:249], s[62:63], v[254:255] op_sel_hi:[1,0,0]
	v_exp_f32_e32 v252, v252
	v_exp_f32_e32 v253, v253
	v_pk_fma_f32 v[250:251], v[248:249], v[250:251], s[66:67] op_sel_hi:[1,1,0]
	v_pk_fma_f32 v[250:251], v[248:249], v[250:251], s[68:69] op_sel_hi:[1,1,0]
	v_pk_fma_f32 v[250:251], v[248:249], v[250:251], s[70:71] op_sel_hi:[1,1,0]
	v_pk_mul_f32 v[250:251], v[248:249], v[250:251]
	v_pk_fma_f32 v[250:251], v[250:251], v[252:253], 0.5 op_sel_hi:[1,1,0] neg_lo:[1,0,0] neg_hi:[1,0,0]
	v_pk_mul_f32 v[248:249], v[100:101], 0.5 op_sel_hi:[1,0]
	v_fma_f32 v134, |v100|, v250, v248
	v_fma_f32 v113, |v101|, v251, v249
	v_fma_f32 v248, |v98|, s60, 1.0
	v_fma_f32 v249, |v99|, s60, 1.0
	v_pk_mul_f32 v[252:253], v[98:99], v[98:99]
	v_rcp_f32_e32 v248, v248
	v_rcp_f32_e32 v249, v249
	v_pk_mul_f32 v[252:253], v[252:253], s[72:73] op_sel_hi:[1,0]
	v_pk_fma_f32 v[250:251], v[248:249], s[62:63], v[254:255] op_sel_hi:[1,0,0]
	v_exp_f32_e32 v252, v252
	v_exp_f32_e32 v253, v253
	v_pk_fma_f32 v[250:251], v[248:249], v[250:251], s[66:67] op_sel_hi:[1,1,0]
	v_pk_fma_f32 v[250:251], v[248:249], v[250:251], s[68:69] op_sel_hi:[1,1,0]
	v_pk_fma_f32 v[250:251], v[248:249], v[250:251], s[70:71] op_sel_hi:[1,1,0]
	v_pk_mul_f32 v[250:251], v[248:249], v[250:251]
	v_pk_fma_f32 v[250:251], v[250:251], v[252:253], 0.5 op_sel_hi:[1,1,0] neg_lo:[1,0,0] neg_hi:[1,0,0]
	v_pk_mul_f32 v[248:249], v[98:99], 0.5 op_sel_hi:[1,0]
	v_fma_f32 v112, |v98|, v250, v248
	v_fma_f32 v136, |v99|, v251, v249
	s_andn2_b64 vcc, exec, s[88:89]
	v_mov_b64_e32 v[138:139], v[132:133]
	s_cbranch_vccnz .LBB0_1162
	v_mov_b32_e32 v137, v113
	v_pk_add_f32 v[142:143], v[112:113], v[136:137]
	v_pk_mul_f32 v[144:145], v[112:113], v[136:137]
	v_mov_b32_e32 v138, v112
	v_mov_b32_e32 v143, v145
	v_pk_mul_f32 v[144:145], v[110:111], v[110:111]
	v_mov_b32_e32 v139, v136
	v_pk_fma_f32 v[144:145], v[108:109], v[108:109], v[144:145]
	v_pk_add_f32 v[140:141], v[108:109], v[110:111]
	v_pk_add_f32 v[144:145], v[144:145], v[144:145] op_sel_hi:[0,1]
	v_mul_f32_e32 v144, v138, v138
	v_pk_fma_f32 v[138:139], v[138:139], v[138:139], v[144:145] op_sel_hi:[1,1,0]
	v_mul_f32_e32 v137, v134, v134
	v_pk_add_f32 v[140:141], v[140:141], v[140:141] op_sel:[0,1] op_sel_hi:[1,0]
	v_mov_b32_e32 v135, v145
	v_mov_b32_e32 v138, v113
	v_mov_b32_e32 v141, v137
	v_pk_add_f32 v[138:139], v[134:135], v[138:139]
	v_pk_add_f32 v[140:141], v[140:141], v[142:143]
	s_nop 0
	v_pk_add_f32 v[138:139], v[140:141], v[138:139]
	s_nop 0
	v_pk_add_f32 v[138:139], v[138:139], v[132:133]

; __device__ __forceinline__ f32x2 gelu_pk(f32x2 v) {
;     const f32x2 av = __builtin_elementwise_abs(v), d = av * 0.2316418882f + 1.0f;
;     f32x2 t; t.x = __builtin_amdgcn_rcpf(d.x); t.y = __builtin_amdgcn_rcpf(d.y);
;     f32x2 q = t * 0.5307027145f + (-0.7265760135f); q = q * t + 0.7107068705f; q = q * t + (-0.142248368f); q = q * t + 0.127414796f; q = q * t;
;     const f32x2 s = (v * v) * (-0.72134752044f);
;     f32x2 e; e.x = __builtin_amdgcn_exp2f(s.x); e.y = __builtin_amdgcn_exp2f(s.y);
;     const f32x2 m = v * (q * e), r = v - m;
;     f32x2 o; o.x = v.x < 0.f ? m.x : r.x; o.y = v.y < 0.f ? m.y : r.y; return o;
; }
;     __device__ __forceinline__ void operator()(const f32x4 (&acc)[2][2][4][2], const Unit& u, int wr, int wc, int fr, int fq) const {
;     ...
;                     } else if (kind == 2) {
;                         f32x2 a = gelu_pk((f32x2){v0[0], v0[1]}), b = gelu_pk((f32x2){v0[2], v0[3]}), c = gelu_pk((f32x2){v1[0], v1[1]}), d = gelu_pk((f32x2){v1[2], v1[3]});
;                         v0 = (f32x4){a.x, a.y, b.x, b.y}; v1 = (f32x4){c.x, c.y, d.x, d.y};
;                         if (pn >= 9) { const float t1 = (v0[0] + v0[1]) + (v0[2] + v0[3]) + (v1[0] + v1[1]) + (v1[2] + v1[3]);
;                             const float t2 = (v0[0] * v0[0] + v0[1] * v0[1]) + (v0[2] * v0[2] + v0[3] * v0[3]) + (v1[0] * v1[0] + v1[1] * v1[1]) + (v1[2] * v1[2] + v1[3] * v1[3]);
;                             if (bj == 0) { ps = t1; pss = t2; } else { ps += t1; pss += t2; } }
.LBB0_1176:
	s_andn2_b64 vcc, exec, s[22:23]
	s_cbranch_vccnz .LBB0_1334
	s_waitcnt vmcnt(4)
	s_waitcnt vmcnt(3)
	s_waitcnt vmcnt(2)
	v_mov_b64_e32 v[254:255], s[64:65]
	v_fma_f32 v248, |v94|, s60, 1.0
	v_fma_f32 v249, |v95|, s60, 1.0
	v_pk_mul_f32 v[252:253], v[94:95], v[94:95]
	v_rcp_f32_e32 v248, v248
	v_rcp_f32_e32 v249, v249
	v_pk_mul_f32 v[252:253], v[252:253], s[72:73] op_sel_hi:[1,0]
	v_pk_fma_f32 v[250:251], v[248:249], s[62:63], v[254:255] op_sel_hi:[1,0,0]
	v_exp_f32_e32 v252, v252
	v_exp_f32_e32 v253, v253
	v_pk_fma_f32 v[250:251], v[248:249], v[250:251], s[66:67] op_sel_hi:[1,1,0]
	v_pk_fma_f32 v[250:251], v[248:249], v[250:251], s[68:69] op_sel_hi:[1,1,0]
	v_pk_fma_f32 v[250:251], v[248:249], v[250:251], s[70:71] op_sel_hi:[1,1,0]
	v_pk_mul_f32 v[250:251], v[248:249], v[250:251]
	v_pk_fma_f32 v[250:251], v[250:251], v[252:253], 0.5 op_sel_hi:[1,1,0] neg_lo:[1,0,0] neg_hi:[1,0,0]
	v_pk_mul_f32 v[248:249], v[94:95], 0.5 op_sel_hi:[1,0]
	v_fma_f32 v118, |v94|, v250, v248
	v_fma_f32 v120, |v95|, v251, v249
	v_fma_f32 v248, |v96|, s60, 1.0
	v_fma_f32 v249, |v97|, s60, 1.0
	v_pk_mul_f32 v[252:253], v[96:97], v[96:97]
	v_rcp_f32_e32 v248, v248
	v_rcp_f32_e32 v249, v249
	v_pk_mul_f32 v[252:253], v[252:253], s[72:73] op_sel_hi:[1,0]
	v_pk_fma_f32 v[250:251], v[248:249], s[62:63], v[254:255] op_sel_hi:[1,0,0]
	v_exp_f32_e32 v252, v252
	v_exp_f32_e32 v253, v253
	v_pk_fma_f32 v[250:251], v[248:249], v[250:251], s[66:67] op_sel_hi:[1,1,0]
	v_pk_fma_f32 v[250:251], v[248:249], v[250:251], s[68:69] op_sel_hi:[1,1,0]
	v_pk_fma_f32 v[250:251], v[248:249], v[250:251], s[70:71] op_sel_hi:[1,1,0]
	v_pk_mul_f32 v[250:251], v[248:249], v[250:251]
	v_pk_fma_f32 v[250:251], v[250:251], v[252:253], 0.5 op_sel_hi:[1,1,0] neg_lo:[1,0,0] neg_hi:[1,0,0]
	v_pk_mul_f32 v[248:249], v[96:97], 0.5 op_sel_hi:[1,0]
	v_fma_f32 v119, |v96|, v250, v248
	v_fma_f32 v121, |v97|, v251, v249
	v_fma_f32 v248, |v92|, s60, 1.0
	v_fma_f32 v249, |v93|, s60, 1.0
	v_pk_mul_f32 v[252:253], v[92:93], v[92:93]
	v_rcp_f32_e32 v248, v248
	v_rcp_f32_e32 v249, v249
	v_pk_mul_f32 v[252:253], v[252:253], s[72:73] op_sel_hi:[1,0]
	v_pk_fma_f32 v[250:251], v[248:249], s[62:63], v[254:255] op_sel_hi:[1,0,0]
	v_exp_f32_e32 v252, v252
	v_exp_f32_e32 v253, v253
	v_pk_fma_f32 v[250:251], v[248:249], v[250:251], s[66:67] op_sel_hi:[1,1,0]
	v_pk_fma_f32 v[250:251], v[248:249], v[250:251], s[68:69] op_sel_hi:[1,1,0]
	v_pk_fma_f32 v[250:251], v[248:249], v[250:251], s[70:71] op_sel_hi:[1,1,0]
	v_pk_mul_f32 v[250:251], v[248:249], v[250:251]
	v_pk_fma_f32 v[250:251], v[250:251], v[252:253], 0.5 op_sel_hi:[1,1,0] neg_lo:[1,0,0] neg_hi:[1,0,0]
	v_pk_mul_f32 v[248:249], v[92:93], 0.5 op_sel_hi:[1,0]
	v_fma_f32 v124, |v92|, v250, v248
	v_fma_f32 v123, |v93|, v251, v249
	v_fma_f32 v248, |v90|, s60, 1.0
	v_fma_f32 v249, |v91|, s60, 1.0
	v_pk_mul_f32 v[252:253], v[90:91], v[90:91]
	v_rcp_f32_e32 v248, v248
	v_rcp_f32_e32 v249, v249
	v_pk_mul_f32 v[252:253], v[252:253], s[72:73] op_sel_hi:[1,0]
	v_pk_fma_f32 v[250:251], v[248:249], s[62:63], v[254:255] op_sel_hi:[1,0,0]
	v_exp_f32_e32 v252, v252
	v_exp_f32_e32 v253, v253
	v_pk_fma_f32 v[250:251], v[248:249], v[250:251], s[66:67] op_sel_hi:[1,1,0]
	v_pk_fma_f32 v[250:251], v[248:249], v[250:251], s[68:69] op_sel_hi:[1,1,0]
	v_pk_fma_f32 v[250:251], v[248:249], v[250:251], s[70:71] op_sel_hi:[1,1,0]
	v_pk_mul_f32 v[250:251], v[248:249], v[250:251]
	v_pk_fma_f32 v[250:251], v[250:251], v[252:253], 0.5 op_sel_hi:[1,1,0] neg_lo:[1,0,0] neg_hi:[1,0,0]
	v_pk_mul_f32 v[248:249], v[90:91], 0.5 op_sel_hi:[1,0]
	v_fma_f32 v122, |v90|, v250, v248
	v_fma_f32 v126, |v91|, v251, v249
	s_andn2_b64 vcc, exec, s[88:89]
	s_cbranch_vccnz .LBB0_1334
	v_mov_b32_e32 v127, v123
	v_pk_add_f32 v[130:131], v[122:123], v[126:127]
	v_pk_mul_f32 v[132:133], v[122:123], v[126:127]
	v_mov_b32_e32 v116, v122
	v_mov_b32_e32 v131, v133
	v_pk_mul_f32 v[132:133], v[120:121], v[120:121]
	v_mov_b32_e32 v117, v126
	v_pk_fma_f32 v[132:133], v[118:119], v[118:119], v[132:133]
	v_pk_add_f32 v[128:129], v[118:119], v[120:121]
	v_pk_add_f32 v[132:133], v[132:133], v[132:133] op_sel_hi:[0,1]
	v_mul_f32_e32 v132, v116, v116
	v_pk_fma_f32 v[116:117], v[116:117], v[116:117], v[132:133] op_sel_hi:[1,1,0]
	v_mul_f32_e32 v127, v124, v124
	v_pk_add_f32 v[128:129], v[128:129], v[128:129] op_sel:[0,1] op_sel_hi:[1,0]
	v_mov_b32_e32 v125, v133
	v_mov_b32_e32 v116, v123
	v_mov_b32_e32 v129, v127
	v_pk_add_f32 v[116:117], v[124:125], v[116:117]
	v_pk_add_f32 v[128:129], v[128:129], v[130:131]
	s_nop 0
	v_pk_add_f32 v[116:117], v[128:129], v[116:117]
	s_cbranch_execz .LBB0_1180
	s_branch .LBB0_1181

; __device__ __forceinline__ f32x2 gelu_pk(f32x2 v) {
;     const f32x2 av = __builtin_elementwise_abs(v), d = av * 0.2316418882f + 1.0f;
;     f32x2 t; t.x = __builtin_amdgcn_rcpf(d.x); t.y = __builtin_amdgcn_rcpf(d.y);
;     f32x2 q = t * 0.5307027145f + (-0.7265760135f); q = q * t + 0.7107068705f; q = q * t + (-0.142248368f); q = q * t + 0.127414796f; q = q * t;
;     const f32x2 s = (v * v) * (-0.72134752044f);
;     f32x2 e; e.x = __builtin_amdgcn_exp2f(s.x); e.y = __builtin_amdgcn_exp2f(s.y);
;     const f32x2 m = v * (q * e), r = v - m;
;     f32x2 o; o.x = v.x < 0.f ? m.x : r.x; o.y = v.y < 0.f ? m.y : r.y; return o;
; }
;     __device__ __forceinline__ void operator()(const f32x4 (&acc)[2][2][4][2], const Unit& u, int wr, int wc, int fr, int fq) const {
;     ...
;                     } else if (kind == 2) {
;                         f32x2 a = gelu_pk((f32x2){v0[0], v0[1]}), b = gelu_pk((f32x2){v0[2], v0[3]}), c = gelu_pk((f32x2){v1[0], v1[1]}), d = gelu_pk((f32x2){v1[2], v1[3]});
;                         v0 = (f32x4){a.x, a.y, b.x, b.y}; v1 = (f32x4){c.x, c.y, d.x, d.y};
;                         if (pn >= 9) { const float t1 = (v0[0] + v0[1]) + (v0[2] + v0[3]) + (v1[0] + v1[1]) + (v1[2] + v1[3]);
;                             const float t2 = (v0[0] * v0[0] + v0[1] * v0[1]) + (v0[2] * v0[2] + v0[3] * v0[3]) + (v1[0] * v1[0] + v1[1] * v1[1]) + (v1[2] * v1[2] + v1[3] * v1[3]);
;                             if (bj == 0) { ps = t1; pss = t2; } else { ps += t1; pss += t2; } }
.LBB0_1186:
	s_andn2_b64 vcc, exec, s[22:23]
	v_mov_b64_e32 v[122:123], v[116:117]
	s_cbranch_vccnz .LBB0_1189
	v_mov_b64_e32 v[254:255], s[64:65]
	v_fma_f32 v248, |v86|, s60, 1.0
	v_fma_f32 v249, |v87|, s60, 1.0
	v_pk_mul_f32 v[252:253], v[86:87], v[86:87]
	v_rcp_f32_e32 v248, v248
	v_rcp_f32_e32 v249, v249
	v_pk_mul_f32 v[252:253], v[252:253], s[72:73] op_sel_hi:[1,0]
	v_pk_fma_f32 v[250:251], v[248:249], s[62:63], v[254:255] op_sel_hi:[1,0,0]
	v_exp_f32_e32 v252, v252
	v_exp_f32_e32 v253, v253
	v_pk_fma_f32 v[250:251], v[248:249], v[250:251], s[66:67] op_sel_hi:[1,1,0]
	v_pk_fma_f32 v[250:251], v[248:249], v[250:251], s[68:69] op_sel_hi:[1,1,0]
	v_pk_fma_f32 v[250:251], v[248:249], v[250:251], s[70:71] op_sel_hi:[1,1,0]
	v_pk_mul_f32 v[250:251], v[248:249], v[250:251]
	v_pk_fma_f32 v[250:251], v[250:251], v[252:253], 0.5 op_sel_hi:[1,1,0] neg_lo:[1,0,0] neg_hi:[1,0,0]
	v_pk_mul_f32 v[248:249], v[86:87], 0.5 op_sel_hi:[1,0]
	v_fma_f32 v92, |v86|, v250, v248
	v_fma_f32 v94, |v87|, v251, v249
	v_fma_f32 v248, |v88|, s60, 1.0
	v_fma_f32 v249, |v89|, s60, 1.0
	v_pk_mul_f32 v[252:253], v[88:89], v[88:89]
	v_rcp_f32_e32 v248, v248
	v_rcp_f32_e32 v249, v249
	v_pk_mul_f32 v[252:253], v[252:253], s[72:73] op_sel_hi:[1,0]
	v_pk_fma_f32 v[250:251], v[248:249], s[62:63], v[254:255] op_sel_hi:[1,0,0]
	v_exp_f32_e32 v252, v252
	v_exp_f32_e32 v253, v253
	v_pk_fma_f32 v[250:251], v[248:249], v[250:251], s[66:67] op_sel_hi:[1,1,0]
	v_pk_fma_f32 v[250:251], v[248:249], v[250:251], s[68:69] op_sel_hi:[1,1,0]
	v_pk_fma_f32 v[250:251], v[248:249], v[250:251], s[70:71] op_sel_hi:[1,1,0]
	v_pk_mul_f32 v[250:251], v[248:249], v[250:251]
	v_pk_fma_f32 v[250:251], v[250:251], v[252:253], 0.5 op_sel_hi:[1,1,0] neg_lo:[1,0,0] neg_hi:[1,0,0]
	v_pk_mul_f32 v[248:249], v[88:89], 0.5 op_sel_hi:[1,0]
	v_fma_f32 v93, |v88|, v250, v248
	v_fma_f32 v95, |v89|, v251, v249
	v_fma_f32 v248, |v84|, s60, 1.0
	v_fma_f32 v249, |v85|, s60, 1.0
	v_pk_mul_f32 v[252:253], v[84:85], v[84:85]
	v_rcp_f32_e32 v248, v248
	v_rcp_f32_e32 v249, v249
	v_pk_mul_f32 v[252:253], v[252:253], s[72:73] op_sel_hi:[1,0]
	v_pk_fma_f32 v[250:251], v[248:249], s[62:63], v[254:255] op_sel_hi:[1,0,0]
	v_exp_f32_e32 v252, v252
	v_exp_f32_e32 v253, v253
	v_pk_fma_f32 v[250:251], v[248:249], v[250:251], s[66:67] op_sel_hi:[1,1,0]
	v_pk_fma_f32 v[250:251], v[248:249], v[250:251], s[68:69] op_sel_hi:[1,1,0]
	v_pk_fma_f32 v[250:251], v[248:249], v[250:251], s[70:71] op_sel_hi:[1,1,0]
	v_pk_mul_f32 v[250:251], v[248:249], v[250:251]
	v_pk_fma_f32 v[250:251], v[250:251], v[252:253], 0.5 op_sel_hi:[1,1,0] neg_lo:[1,0,0] neg_hi:[1,0,0]
	v_pk_mul_f32 v[248:249], v[84:85], 0.5 op_sel_hi:[1,0]
	v_fma_f32 v118, |v84|, v250, v248
	v_fma_f32 v97, |v85|, v251, v249
	v_fma_f32 v248, |v82|, s60, 1.0
	v_fma_f32 v249, |v83|, s60, 1.0
	v_pk_mul_f32 v[252:253], v[82:83], v[82:83]
	v_rcp_f32_e32 v248, v248
	v_rcp_f32_e32 v249, v249
	v_pk_mul_f32 v[252:253], v[252:253], s[72:73] op_sel_hi:[1,0]
	v_pk_fma_f32 v[250:251], v[248:249], s[62:63], v[254:255] op_sel_hi:[1,0,0]
	v_exp_f32_e32 v252, v252
	v_exp_f32_e32 v253, v253
	v_pk_fma_f32 v[250:251], v[248:249], v[250:251], s[66:67] op_sel_hi:[1,1,0]
	v_pk_fma_f32 v[250:251], v[248:249], v[250:251], s[68:69] op_sel_hi:[1,1,0]
	v_pk_fma_f32 v[250:251], v[248:249], v[250:251], s[70:71] op_sel_hi:[1,1,0]
	v_pk_mul_f32 v[250:251], v[248:249], v[250:251]
	v_pk_fma_f32 v[250:251], v[250:251], v[252:253], 0.5 op_sel_hi:[1,1,0] neg_lo:[1,0,0] neg_hi:[1,0,0]
	v_pk_mul_f32 v[248:249], v[82:83], 0.5 op_sel_hi:[1,0]
	v_fma_f32 v96, |v82|, v250, v248
	v_fma_f32 v120, |v83|, v251, v249
	s_andn2_b64 vcc, exec, s[88:89]
	v_mov_b64_e32 v[122:123], v[116:117]
	s_cbranch_vccnz .LBB0_1189
	v_mov_b32_e32 v121, v97
	v_pk_add_f32 v[126:127], v[96:97], v[120:121]
	v_pk_mul_f32 v[128:129], v[96:97], v[120:121]
	v_mov_b32_e32 v122, v96
	v_mov_b32_e32 v127, v129
	v_pk_mul_f32 v[128:129], v[94:95], v[94:95]
	v_mov_b32_e32 v123, v120
	v_pk_fma_f32 v[128:129], v[92:93], v[92:93], v[128:129]
	v_pk_add_f32 v[124:125], v[92:93], v[94:95]
	v_pk_add_f32 v[128:129], v[128:129], v[128:129] op_sel_hi:[0,1]
	v_mul_f32_e32 v128, v122, v122
	v_pk_fma_f32 v[122:123], v[122:123], v[122:123], v[128:129] op_sel_hi:[1,1,0]
	v_mul_f32_e32 v121, v118, v118
	v_pk_add_f32 v[124:125], v[124:125], v[124:125] op_sel:[0,1] op_sel_hi:[1,0]
	v_mov_b32_e32 v119, v129
	v_mov_b32_e32 v122, v97
	v_mov_b32_e32 v125, v121
	v_pk_add_f32 v[122:123], v[118:119], v[122:123]
	v_pk_add_f32 v[124:125], v[124:125], v[126:127]
	s_nop 0
	v_pk_add_f32 v[122:123], v[124:125], v[122:123]
	s_nop 0
	v_pk_add_f32 v[122:123], v[122:123], v[116:117]

; __device__ __forceinline__ f32x2 gelu_pk(f32x2 v) {
;     const f32x2 av = __builtin_elementwise_abs(v), d = av * 0.2316418882f + 1.0f;
;     f32x2 t; t.x = __builtin_amdgcn_rcpf(d.x); t.y = __builtin_amdgcn_rcpf(d.y);
;     f32x2 q = t * 0.5307027145f + (-0.7265760135f); q = q * t + 0.7107068705f; q = q * t + (-0.142248368f); q = q * t + 0.127414796f; q = q * t;
;     const f32x2 s = (v * v) * (-0.72134752044f);
;     f32x2 e; e.x = __builtin_amdgcn_exp2f(s.x); e.y = __builtin_amdgcn_exp2f(s.y);
;     const f32x2 m = v * (q * e), r = v - m;
;     f32x2 o; o.x = v.x < 0.f ? m.x : r.x; o.y = v.y < 0.f ? m.y : r.y; return o;
; }
;     __device__ __forceinline__ void operator()(const f32x4 (&acc)[2][2][4][2], const Unit& u, int wr, int wc, int fr, int fq) const {
;     ...
;                     } else if (kind == 2) {
;                         f32x2 a = gelu_pk((f32x2){v0[0], v0[1]}), b = gelu_pk((f32x2){v0[2], v0[3]}), c = gelu_pk((f32x2){v1[0], v1[1]}), d = gelu_pk((f32x2){v1[2], v1[3]});
;                         v0 = (f32x4){a.x, a.y, b.x, b.y}; v1 = (f32x4){c.x, c.y, d.x, d.y};
;                         if (pn >= 9) { const float t1 = (v0[0] + v0[1]) + (v0[2] + v0[3]) + (v1[0] + v1[1]) + (v1[2] + v1[3]);
;                             const float t2 = (v0[0] * v0[0] + v0[1] * v0[1]) + (v0[2] * v0[2] + v0[3] * v0[3]) + (v1[0] * v1[0] + v1[1] * v1[1]) + (v1[2] * v1[2] + v1[3] * v1[3]);
;                             if (bj == 0) { ps = t1; pss = t2; } else { ps += t1; pss += t2; } }
.LBB0_1203:
	s_andn2_b64 vcc, exec, s[22:23]
	s_cbranch_vccnz .LBB0_1335
	s_waitcnt vmcnt(3)
	s_waitcnt vmcnt(2)
	v_mov_b64_e32 v[254:255], s[64:65]
	v_fma_f32 v248, |v78|, s60, 1.0
	v_fma_f32 v249, |v79|, s60, 1.0
	v_pk_mul_f32 v[252:253], v[78:79], v[78:79]
	v_rcp_f32_e32 v248, v248
	v_rcp_f32_e32 v249, v249
	v_pk_mul_f32 v[252:253], v[252:253], s[72:73] op_sel_hi:[1,0]
	v_pk_fma_f32 v[250:251], v[248:249], s[62:63], v[254:255] op_sel_hi:[1,0,0]
	v_exp_f32_e32 v252, v252
	v_exp_f32_e32 v253, v253
	v_pk_fma_f32 v[250:251], v[248:249], v[250:251], s[66:67] op_sel_hi:[1,1,0]
	v_pk_fma_f32 v[250:251], v[248:249], v[250:251], s[68:69] op_sel_hi:[1,1,0]
	v_pk_fma_f32 v[250:251], v[248:249], v[250:251], s[70:71] op_sel_hi:[1,1,0]
	v_pk_mul_f32 v[250:251], v[248:249], v[250:251]
	v_pk_fma_f32 v[250:251], v[250:251], v[252:253], 0.5 op_sel_hi:[1,1,0] neg_lo:[1,0,0] neg_hi:[1,0,0]
	v_pk_mul_f32 v[248:249], v[78:79], 0.5 op_sel_hi:[1,0]
	v_fma_f32 v102, |v78|, v250, v248
	v_fma_f32 v104, |v79|, v251, v249
	v_fma_f32 v248, |v80|, s60, 1.0
	v_fma_f32 v249, |v81|, s60, 1.0
	v_pk_mul_f32 v[252:253], v[80:81], v[80:81]
	v_rcp_f32_e32 v248, v248
	v_rcp_f32_e32 v249, v249
	v_pk_mul_f32 v[252:253], v[252:253], s[72:73] op_sel_hi:[1,0]
	v_pk_fma_f32 v[250:251], v[248:249], s[62:63], v[254:255] op_sel_hi:[1,0,0]
	v_exp_f32_e32 v252, v252
	v_exp_f32_e32 v253, v253
	v_pk_fma_f32 v[250:251], v[248:249], v[250:251], s[66:67] op_sel_hi:[1,1,0]
	v_pk_fma_f32 v[250:251], v[248:249], v[250:251], s[68:69] op_sel_hi:[1,1,0]
	v_pk_fma_f32 v[250:251], v[248:249], v[250:251], s[70:71] op_sel_hi:[1,1,0]
	v_pk_mul_f32 v[250:251], v[248:249], v[250:251]
	v_pk_fma_f32 v[250:251], v[250:251], v[252:253], 0.5 op_sel_hi:[1,1,0] neg_lo:[1,0,0] neg_hi:[1,0,0]
	v_pk_mul_f32 v[248:249], v[80:81], 0.5 op_sel_hi:[1,0]
	v_fma_f32 v103, |v80|, v250, v248
	v_fma_f32 v105, |v81|, v251, v249
	v_fma_f32 v248, |v76|, s60, 1.0
	v_fma_f32 v249, |v77|, s60, 1.0
	v_pk_mul_f32 v[252:253], v[76:77], v[76:77]
	v_rcp_f32_e32 v248, v248
	v_rcp_f32_e32 v249, v249
	v_pk_mul_f32 v[252:253], v[252:253], s[72:73] op_sel_hi:[1,0]
	v_pk_fma_f32 v[250:251], v[248:249], s[62:63], v[254:255] op_sel_hi:[1,0,0]
	v_exp_f32_e32 v252, v252
	v_exp_f32_e32 v253, v253
	v_pk_fma_f32 v[250:251], v[248:249], v[250:251], s[66:67] op_sel_hi:[1,1,0]
	v_pk_fma_f32 v[250:251], v[248:249], v[250:251], s[68:69] op_sel_hi:[1,1,0]
	v_pk_fma_f32 v[250:251], v[248:249], v[250:251], s[70:71] op_sel_hi:[1,1,0]
	v_pk_mul_f32 v[250:251], v[248:249], v[250:251]
	v_pk_fma_f32 v[250:251], v[250:251], v[252:253], 0.5 op_sel_hi:[1,1,0] neg_lo:[1,0,0] neg_hi:[1,0,0]
	v_pk_mul_f32 v[248:249], v[76:77], 0.5 op_sel_hi:[1,0]
	v_fma_f32 v108, |v76|, v250, v248
	v_fma_f32 v107, |v77|, v251, v249
	v_fma_f32 v248, |v74|, s60, 1.0
	v_fma_f32 v249, |v75|, s60, 1.0
	v_pk_mul_f32 v[252:253], v[74:75], v[74:75]
	v_rcp_f32_e32 v248, v248
	v_rcp_f32_e32 v249, v249
	v_pk_mul_f32 v[252:253], v[252:253], s[72:73] op_sel_hi:[1,0]
	v_pk_fma_f32 v[250:251], v[248:249], s[62:63], v[254:255] op_sel_hi:[1,0,0]
	v_exp_f32_e32 v252, v252
	v_exp_f32_e32 v253, v253
	v_pk_fma_f32 v[250:251], v[248:249], v[250:251], s[66:67] op_sel_hi:[1,1,0]
	v_pk_fma_f32 v[250:251], v[248:249], v[250:251], s[68:69] op_sel_hi:[1,1,0]
	v_pk_fma_f32 v[250:251], v[248:249], v[250:251], s[70:71] op_sel_hi:[1,1,0]
	v_pk_mul_f32 v[250:251], v[248:249], v[250:251]
	v_pk_fma_f32 v[250:251], v[250:251], v[252:253], 0.5 op_sel_hi:[1,1,0] neg_lo:[1,0,0] neg_hi:[1,0,0]
	v_pk_mul_f32 v[248:249], v[74:75], 0.5 op_sel_hi:[1,0]
	v_fma_f32 v106, |v74|, v250, v248
	v_fma_f32 v110, |v75|, v251, v249
	s_andn2_b64 vcc, exec, s[88:89]
	s_cbranch_vccnz .LBB0_1335
	v_mov_b32_e32 v111, v107
	v_pk_add_f32 v[114:115], v[106:107], v[110:111]
	v_pk_mul_f32 v[116:117], v[106:107], v[110:111]
	v_mov_b32_e32 v100, v106
	v_mov_b32_e32 v115, v117
	v_pk_mul_f32 v[116:117], v[104:105], v[104:105]
	v_mov_b32_e32 v101, v110
	v_pk_fma_f32 v[116:117], v[102:103], v[102:103], v[116:117]
	v_pk_add_f32 v[112:113], v[102:103], v[104:105]
	v_pk_add_f32 v[116:117], v[116:117], v[116:117] op_sel_hi:[0,1]
	v_mul_f32_e32 v116, v100, v100
	v_pk_fma_f32 v[100:101], v[100:101], v[100:101], v[116:117] op_sel_hi:[1,1,0]
	v_mul_f32_e32 v111, v108, v108
	v_pk_add_f32 v[112:113], v[112:113], v[112:113] op_sel:[0,1] op_sel_hi:[1,0]
	v_mov_b32_e32 v109, v117
	v_mov_b32_e32 v100, v107
	v_mov_b32_e32 v113, v111
	v_pk_add_f32 v[100:101], v[108:109], v[100:101]
	v_pk_add_f32 v[112:113], v[112:113], v[114:115]
	s_nop 0
	v_pk_add_f32 v[100:101], v[112:113], v[100:101]
	s_cbranch_execz .LBB0_1207
	s_branch .LBB0_1208

; __device__ __forceinline__ f32x2 gelu_pk(f32x2 v) {
;     const f32x2 av = __builtin_elementwise_abs(v), d = av * 0.2316418882f + 1.0f;
;     f32x2 t; t.x = __builtin_amdgcn_rcpf(d.x); t.y = __builtin_amdgcn_rcpf(d.y);
;     f32x2 q = t * 0.5307027145f + (-0.7265760135f); q = q * t + 0.7107068705f; q = q * t + (-0.142248368f); q = q * t + 0.127414796f; q = q * t;
;     const f32x2 s = (v * v) * (-0.72134752044f);
;     f32x2 e; e.x = __builtin_amdgcn_exp2f(s.x); e.y = __builtin_amdgcn_exp2f(s.y);
;     const f32x2 m = v * (q * e), r = v - m;
;     f32x2 o; o.x = v.x < 0.f ? m.x : r.x; o.y = v.y < 0.f ? m.y : r.y; return o;
; }
;     __device__ __forceinline__ void operator()(const f32x4 (&acc)[2][2][4][2], const Unit& u, int wr, int wc, int fr, int fq) const {
;     ...
;                     } else if (kind == 2) {
;                         f32x2 a = gelu_pk((f32x2){v0[0], v0[1]}), b = gelu_pk((f32x2){v0[2], v0[3]}), c = gelu_pk((f32x2){v1[0], v1[1]}), d = gelu_pk((f32x2){v1[2], v1[3]});
;                         v0 = (f32x4){a.x, a.y, b.x, b.y}; v1 = (f32x4){c.x, c.y, d.x, d.y};
;                         if (pn >= 9) { const float t1 = (v0[0] + v0[1]) + (v0[2] + v0[3]) + (v1[0] + v1[1]) + (v1[2] + v1[3]);
;                             const float t2 = (v0[0] * v0[0] + v0[1] * v0[1]) + (v0[2] * v0[2] + v0[3] * v0[3]) + (v1[0] * v1[0] + v1[1] * v1[1]) + (v1[2] * v1[2] + v1[3] * v1[3]);
;                             if (bj == 0) { ps = t1; pss = t2; } else { ps += t1; pss += t2; } }
.LBB0_1213:
	s_andn2_b64 vcc, exec, s[22:23]
	v_mov_b64_e32 v[106:107], v[100:101]
	s_cbranch_vccnz .LBB0_1216
	v_mov_b64_e32 v[254:255], s[64:65]
	v_fma_f32 v248, |v70|, s60, 1.0
	v_fma_f32 v249, |v71|, s60, 1.0
	v_pk_mul_f32 v[252:253], v[70:71], v[70:71]
	v_rcp_f32_e32 v248, v248
	v_rcp_f32_e32 v249, v249
	v_pk_mul_f32 v[252:253], v[252:253], s[72:73] op_sel_hi:[1,0]
	v_pk_fma_f32 v[250:251], v[248:249], s[62:63], v[254:255] op_sel_hi:[1,0,0]
	v_exp_f32_e32 v252, v252
	v_exp_f32_e32 v253, v253
	v_pk_fma_f32 v[250:251], v[248:249], v[250:251], s[66:67] op_sel_hi:[1,1,0]
	v_pk_fma_f32 v[250:251], v[248:249], v[250:251], s[68:69] op_sel_hi:[1,1,0]
	v_pk_fma_f32 v[250:251], v[248:249], v[250:251], s[70:71] op_sel_hi:[1,1,0]
	v_pk_mul_f32 v[250:251], v[248:249], v[250:251]
	v_pk_fma_f32 v[250:251], v[250:251], v[252:253], 0.5 op_sel_hi:[1,1,0] neg_lo:[1,0,0] neg_hi:[1,0,0]
	v_pk_mul_f32 v[248:249], v[70:71], 0.5 op_sel_hi:[1,0]
	v_fma_f32 v76, |v70|, v250, v248
	v_fma_f32 v78, |v71|, v251, v249
	v_fma_f32 v248, |v72|, s60, 1.0
	v_fma_f32 v249, |v73|, s60, 1.0
	v_pk_mul_f32 v[252:253], v[72:73], v[72:73]
	v_rcp_f32_e32 v248, v248
	v_rcp_f32_e32 v249, v249
	v_pk_mul_f32 v[252:253], v[252:253], s[72:73] op_sel_hi:[1,0]
	v_pk_fma_f32 v[250:251], v[248:249], s[62:63], v[254:255] op_sel_hi:[1,0,0]
	v_exp_f32_e32 v252, v252
	v_exp_f32_e32 v253, v253
	v_pk_fma_f32 v[250:251], v[248:249], v[250:251], s[66:67] op_sel_hi:[1,1,0]
	v_pk_fma_f32 v[250:251], v[248:249], v[250:251], s[68:69] op_sel_hi:[1,1,0]
	v_pk_fma_f32 v[250:251], v[248:249], v[250:251], s[70:71] op_sel_hi:[1,1,0]
	v_pk_mul_f32 v[250:251], v[248:249], v[250:251]
	v_pk_fma_f32 v[250:251], v[250:251], v[252:253], 0.5 op_sel_hi:[1,1,0] neg_lo:[1,0,0] neg_hi:[1,0,0]
	v_pk_mul_f32 v[248:249], v[72:73], 0.5 op_sel_hi:[1,0]
	v_fma_f32 v77, |v72|, v250, v248
	v_fma_f32 v79, |v73|, v251, v249
	v_fma_f32 v248, |v68|, s60, 1.0
	v_fma_f32 v249, |v69|, s60, 1.0
	v_pk_mul_f32 v[252:253], v[68:69], v[68:69]
	v_rcp_f32_e32 v248, v248
	v_rcp_f32_e32 v249, v249
	v_pk_mul_f32 v[252:253], v[252:253], s[72:73] op_sel_hi:[1,0]
	v_pk_fma_f32 v[250:251], v[248:249], s[62:63], v[254:255] op_sel_hi:[1,0,0]
	v_exp_f32_e32 v252, v252
	v_exp_f32_e32 v253, v253
	v_pk_fma_f32 v[250:251], v[248:249], v[250:251], s[66:67] op_sel_hi:[1,1,0]
	v_pk_fma_f32 v[250:251], v[248:249], v[250:251], s[68:69] op_sel_hi:[1,1,0]
	v_pk_fma_f32 v[250:251], v[248:249], v[250:251], s[70:71] op_sel_hi:[1,1,0]
	v_pk_mul_f32 v[250:251], v[248:249], v[250:251]
	v_pk_fma_f32 v[250:251], v[250:251], v[252:253], 0.5 op_sel_hi:[1,1,0] neg_lo:[1,0,0] neg_hi:[1,0,0]
	v_pk_mul_f32 v[248:249], v[68:69], 0.5 op_sel_hi:[1,0]
	v_fma_f32 v102, |v68|, v250, v248
	v_fma_f32 v81, |v69|, v251, v249
	v_fma_f32 v248, |v66|, s60, 1.0
	v_fma_f32 v249, |v67|, s60, 1.0
	v_pk_mul_f32 v[252:253], v[66:67], v[66:67]
	v_rcp_f32_e32 v248, v248
	v_rcp_f32_e32 v249, v249
	v_pk_mul_f32 v[252:253], v[252:253], s[72:73] op_sel_hi:[1,0]
	v_pk_fma_f32 v[250:251], v[248:249], s[62:63], v[254:255] op_sel_hi:[1,0,0]
	v_exp_f32_e32 v252, v252
	v_exp_f32_e32 v253, v253
	v_pk_fma_f32 v[250:251], v[248:249], v[250:251], s[66:67] op_sel_hi:[1,1,0]
	v_pk_fma_f32 v[250:251], v[248:249], v[250:251], s[68:69] op_sel_hi:[1,1,0]
	v_pk_fma_f32 v[250:251], v[248:249], v[250:251], s[70:71] op_sel_hi:[1,1,0]
	v_pk_mul_f32 v[250:251], v[248:249], v[250:251]
	v_pk_fma_f32 v[250:251], v[250:251], v[252:253], 0.5 op_sel_hi:[1,1,0] neg_lo:[1,0,0] neg_hi:[1,0,0]
	v_pk_mul_f32 v[248:249], v[66:67], 0.5 op_sel_hi:[1,0]
	v_fma_f32 v80, |v66|, v250, v248
	v_fma_f32 v104, |v67|, v251, v249
	s_andn2_b64 vcc, exec, s[88:89]
	v_mov_b64_e32 v[106:107], v[100:101]
	s_cbranch_vccnz .LBB0_1216
	v_mov_b32_e32 v105, v81
	v_pk_add_f32 v[110:111], v[80:81], v[104:105]
	v_pk_mul_f32 v[112:113], v[80:81], v[104:105]
	v_mov_b32_e32 v106, v80
	v_mov_b32_e32 v111, v113
	v_pk_mul_f32 v[112:113], v[78:79], v[78:79]
	v_mov_b32_e32 v107, v104
	v_pk_fma_f32 v[112:113], v[76:77], v[76:77], v[112:113]
	v_pk_add_f32 v[108:109], v[76:77], v[78:79]
	v_pk_add_f32 v[112:113], v[112:113], v[112:113] op_sel_hi:[0,1]
	v_mul_f32_e32 v112, v106, v106
	v_pk_fma_f32 v[106:107], v[106:107], v[106:107], v[112:113] op_sel_hi:[1,1,0]
	v_mul_f32_e32 v105, v102, v102
	v_pk_add_f32 v[108:109], v[108:109], v[108:109] op_sel:[0,1] op_sel_hi:[1,0]
	v_mov_b32_e32 v103, v113
	v_mov_b32_e32 v106, v81
	v_mov_b32_e32 v109, v105
	v_pk_add_f32 v[106:107], v[102:103], v[106:107]
	v_pk_add_f32 v[108:109], v[108:109], v[110:111]
	s_nop 0
	v_pk_add_f32 v[106:107], v[108:109], v[106:107]
	s_nop 0
	v_pk_add_f32 v[106:107], v[106:107], v[100:101]

; __device__ __forceinline__ f32x2 gelu_pk(f32x2 v) {
;     const f32x2 av = __builtin_elementwise_abs(v), d = av * 0.2316418882f + 1.0f;
;     f32x2 t; t.x = __builtin_amdgcn_rcpf(d.x); t.y = __builtin_amdgcn_rcpf(d.y);
;     f32x2 q = t * 0.5307027145f + (-0.7265760135f); q = q * t + 0.7107068705f; q = q * t + (-0.142248368f); q = q * t + 0.127414796f; q = q * t;
;     const f32x2 s = (v * v) * (-0.72134752044f);
;     f32x2 e; e.x = __builtin_amdgcn_exp2f(s.x); e.y = __builtin_amdgcn_exp2f(s.y);
;     const f32x2 m = v * (q * e), r = v - m;
;     f32x2 o; o.x = v.x < 0.f ? m.x : r.x; o.y = v.y < 0.f ? m.y : r.y; return o;
; }
;     __device__ __forceinline__ void operator()(const f32x4 (&acc)[2][2][4][2], const Unit& u, int wr, int wc, int fr, int fq) const {
;     ...
;                     } else if (kind == 2) {
;                         f32x2 a = gelu_pk((f32x2){v0[0], v0[1]}), b = gelu_pk((f32x2){v0[2], v0[3]}), c = gelu_pk((f32x2){v1[0], v1[1]}), d = gelu_pk((f32x2){v1[2], v1[3]});
;                         v0 = (f32x4){a.x, a.y, b.x, b.y}; v1 = (f32x4){c.x, c.y, d.x, d.y};
;                         if (pn >= 9) { const float t1 = (v0[0] + v0[1]) + (v0[2] + v0[3]) + (v1[0] + v1[1]) + (v1[2] + v1[3]);
;                             const float t2 = (v0[0] * v0[0] + v0[1] * v0[1]) + (v0[2] * v0[2] + v0[3] * v0[3]) + (v1[0] * v1[0] + v1[1] * v1[1]) + (v1[2] * v1[2] + v1[3] * v1[3]);
;                             if (bj == 0) { ps = t1; pss = t2; } else { ps += t1; pss += t2; } }
.LBB0_1230:
	s_andn2_b64 vcc, exec, s[22:23]
	s_cbranch_vccnz .LBB0_1336
	s_waitcnt vmcnt(3)
	s_waitcnt vmcnt(2)
	v_mov_b64_e32 v[254:255], s[64:65]
	v_fma_f32 v248, |v62|, s60, 1.0
	v_fma_f32 v249, |v63|, s60, 1.0
	v_pk_mul_f32 v[252:253], v[62:63], v[62:63]
	v_rcp_f32_e32 v248, v248
	v_rcp_f32_e32 v249, v249
	v_pk_mul_f32 v[252:253], v[252:253], s[72:73] op_sel_hi:[1,0]
	v_pk_fma_f32 v[250:251], v[248:249], s[62:63], v[254:255] op_sel_hi:[1,0,0]
	v_exp_f32_e32 v252, v252
	v_exp_f32_e32 v253, v253
	v_pk_fma_f32 v[250:251], v[248:249], v[250:251], s[66:67] op_sel_hi:[1,1,0]
	v_pk_fma_f32 v[250:251], v[248:249], v[250:251], s[68:69] op_sel_hi:[1,1,0]
	v_pk_fma_f32 v[250:251], v[248:249], v[250:251], s[70:71] op_sel_hi:[1,1,0]
	v_pk_mul_f32 v[250:251], v[248:249], v[250:251]
	v_pk_fma_f32 v[250:251], v[250:251], v[252:253], 0.5 op_sel_hi:[1,1,0] neg_lo:[1,0,0] neg_hi:[1,0,0]
	v_pk_mul_f32 v[248:249], v[62:63], 0.5 op_sel_hi:[1,0]
	v_fma_f32 v86, |v62|, v250, v248
	v_fma_f32 v88, |v63|, v251, v249
	v_fma_f32 v248, |v64|, s60, 1.0
	v_fma_f32 v249, |v65|, s60, 1.0
	v_pk_mul_f32 v[252:253], v[64:65], v[64:65]
	v_rcp_f32_e32 v248, v248
	v_rcp_f32_e32 v249, v249
	v_pk_mul_f32 v[252:253], v[252:253], s[72:73] op_sel_hi:[1,0]
	v_pk_fma_f32 v[250:251], v[248:249], s[62:63], v[254:255] op_sel_hi:[1,0,0]
	v_exp_f32_e32 v252, v252
	v_exp_f32_e32 v253, v253
	v_pk_fma_f32 v[250:251], v[248:249], v[250:251], s[66:67] op_sel_hi:[1,1,0]
	v_pk_fma_f32 v[250:251], v[248:249], v[250:251], s[68:69] op_sel_hi:[1,1,0]
	v_pk_fma_f32 v[250:251], v[248:249], v[250:251], s[70:71] op_sel_hi:[1,1,0]
	v_pk_mul_f32 v[250:251], v[248:249], v[250:251]
	v_pk_fma_f32 v[250:251], v[250:251], v[252:253], 0.5 op_sel_hi:[1,1,0] neg_lo:[1,0,0] neg_hi:[1,0,0]
	v_pk_mul_f32 v[248:249], v[64:65], 0.5 op_sel_hi:[1,0]
	v_fma_f32 v87, |v64|, v250, v248
	v_fma_f32 v89, |v65|, v251, v249
	v_fma_f32 v248, |v60|, s60, 1.0
	v_fma_f32 v249, |v61|, s60, 1.0
	v_pk_mul_f32 v[252:253], v[60:61], v[60:61]
	v_rcp_f32_e32 v248, v248
	v_rcp_f32_e32 v249, v249
	v_pk_mul_f32 v[252:253], v[252:253], s[72:73] op_sel_hi:[1,0]
	v_pk_fma_f32 v[250:251], v[248:249], s[62:63], v[254:255] op_sel_hi:[1,0,0]
	v_exp_f32_e32 v252, v252
	v_exp_f32_e32 v253, v253
	v_pk_fma_f32 v[250:251], v[248:249], v[250:251], s[66:67] op_sel_hi:[1,1,0]
	v_pk_fma_f32 v[250:251], v[248:249], v[250:251], s[68:69] op_sel_hi:[1,1,0]
	v_pk_fma_f32 v[250:251], v[248:249], v[250:251], s[70:71] op_sel_hi:[1,1,0]
	v_pk_mul_f32 v[250:251], v[248:249], v[250:251]
	v_pk_fma_f32 v[250:251], v[250:251], v[252:253], 0.5 op_sel_hi:[1,1,0] neg_lo:[1,0,0] neg_hi:[1,0,0]
	v_pk_mul_f32 v[248:249], v[60:61], 0.5 op_sel_hi:[1,0]
	v_fma_f32 v92, |v60|, v250, v248
	v_fma_f32 v91, |v61|, v251, v249
	v_fma_f32 v248, |v58|, s60, 1.0
	v_fma_f32 v249, |v59|, s60, 1.0
	v_pk_mul_f32 v[252:253], v[58:59], v[58:59]
	v_rcp_f32_e32 v248, v248
	v_rcp_f32_e32 v249, v249
	v_pk_mul_f32 v[252:253], v[252:253], s[72:73] op_sel_hi:[1,0]
	v_pk_fma_f32 v[250:251], v[248:249], s[62:63], v[254:255] op_sel_hi:[1,0,0]
	v_exp_f32_e32 v252, v252
	v_exp_f32_e32 v253, v253
	v_pk_fma_f32 v[250:251], v[248:249], v[250:251], s[66:67] op_sel_hi:[1,1,0]
	v_pk_fma_f32 v[250:251], v[248:249], v[250:251], s[68:69] op_sel_hi:[1,1,0]
	v_pk_fma_f32 v[250:251], v[248:249], v[250:251], s[70:71] op_sel_hi:[1,1,0]
	v_pk_mul_f32 v[250:251], v[248:249], v[250:251]
	v_pk_fma_f32 v[250:251], v[250:251], v[252:253], 0.5 op_sel_hi:[1,1,0] neg_lo:[1,0,0] neg_hi:[1,0,0]
	v_pk_mul_f32 v[248:249], v[58:59], 0.5 op_sel_hi:[1,0]
	v_fma_f32 v90, |v58|, v250, v248
	v_fma_f32 v94, |v59|, v251, v249
	s_andn2_b64 vcc, exec, s[88:89]
	s_cbranch_vccnz .LBB0_1336
	v_mov_b32_e32 v95, v91
	v_pk_add_f32 v[98:99], v[90:91], v[94:95]
	v_pk_mul_f32 v[100:101], v[90:91], v[94:95]
	v_mov_b32_e32 v84, v90
	v_mov_b32_e32 v99, v101
	v_pk_mul_f32 v[100:101], v[88:89], v[88:89]
	v_mov_b32_e32 v85, v94
	v_pk_fma_f32 v[100:101], v[86:87], v[86:87], v[100:101]
	v_pk_add_f32 v[96:97], v[86:87], v[88:89]
	v_pk_add_f32 v[100:101], v[100:101], v[100:101] op_sel_hi:[0,1]
	v_mul_f32_e32 v100, v84, v84
	v_pk_fma_f32 v[84:85], v[84:85], v[84:85], v[100:101] op_sel_hi:[1,1,0]
	v_mul_f32_e32 v95, v92, v92
	v_pk_add_f32 v[96:97], v[96:97], v[96:97] op_sel:[0,1] op_sel_hi:[1,0]
	v_mov_b32_e32 v93, v101
	v_mov_b32_e32 v84, v91
	v_mov_b32_e32 v97, v95
	v_pk_add_f32 v[84:85], v[92:93], v[84:85]
	v_pk_add_f32 v[96:97], v[96:97], v[98:99]
	s_nop 0
	v_pk_add_f32 v[84:85], v[96:97], v[84:85]
	s_cbranch_execz .LBB0_1234
	s_branch .LBB0_1235

; __device__ __forceinline__ f32x2 gelu_pk(f32x2 v) {
;     const f32x2 av = __builtin_elementwise_abs(v), d = av * 0.2316418882f + 1.0f;
;     f32x2 t; t.x = __builtin_amdgcn_rcpf(d.x); t.y = __builtin_amdgcn_rcpf(d.y);
;     f32x2 q = t * 0.5307027145f + (-0.7265760135f); q = q * t + 0.7107068705f; q = q * t + (-0.142248368f); q = q * t + 0.127414796f; q = q * t;
;     const f32x2 s = (v * v) * (-0.72134752044f);
;     f32x2 e; e.x = __builtin_amdgcn_exp2f(s.x); e.y = __builtin_amdgcn_exp2f(s.y);
;     const f32x2 m = v * (q * e), r = v - m;
;     f32x2 o; o.x = v.x < 0.f ? m.x : r.x; o.y = v.y < 0.f ? m.y : r.y; return o;
; }
;     __device__ __forceinline__ void operator()(const f32x4 (&acc)[2][2][4][2], const Unit& u, int wr, int wc, int fr, int fq) const {
;     ...
;                     } else if (kind == 2) {
;                         f32x2 a = gelu_pk((f32x2){v0[0], v0[1]}), b = gelu_pk((f32x2){v0[2], v0[3]}), c = gelu_pk((f32x2){v1[0], v1[1]}), d = gelu_pk((f32x2){v1[2], v1[3]});
;                         v0 = (f32x4){a.x, a.y, b.x, b.y}; v1 = (f32x4){c.x, c.y, d.x, d.y};
;                         if (pn >= 9) { const float t1 = (v0[0] + v0[1]) + (v0[2] + v0[3]) + (v1[0] + v1[1]) + (v1[2] + v1[3]);
;                             const float t2 = (v0[0] * v0[0] + v0[1] * v0[1]) + (v0[2] * v0[2] + v0[3] * v0[3]) + (v1[0] * v1[0] + v1[1] * v1[1]) + (v1[2] * v1[2] + v1[3] * v1[3]);
;                             if (bj == 0) { ps = t1; pss = t2; } else { ps += t1; pss += t2; } }
.LBB0_1240:
	s_andn2_b64 vcc, exec, s[22:23]
	v_mov_b64_e32 v[90:91], v[84:85]
	s_cbranch_vccnz .LBB0_1243
	v_mov_b64_e32 v[254:255], s[64:65]
	v_fma_f32 v248, |v54|, s60, 1.0
	v_fma_f32 v249, |v55|, s60, 1.0
	v_pk_mul_f32 v[252:253], v[54:55], v[54:55]
	v_rcp_f32_e32 v248, v248
	v_rcp_f32_e32 v249, v249
	v_pk_mul_f32 v[252:253], v[252:253], s[72:73] op_sel_hi:[1,0]
	v_pk_fma_f32 v[250:251], v[248:249], s[62:63], v[254:255] op_sel_hi:[1,0,0]
	v_exp_f32_e32 v252, v252
	v_exp_f32_e32 v253, v253
	v_pk_fma_f32 v[250:251], v[248:249], v[250:251], s[66:67] op_sel_hi:[1,1,0]
	v_pk_fma_f32 v[250:251], v[248:249], v[250:251], s[68:69] op_sel_hi:[1,1,0]
	v_pk_fma_f32 v[250:251], v[248:249], v[250:251], s[70:71] op_sel_hi:[1,1,0]
	v_pk_mul_f32 v[250:251], v[248:249], v[250:251]
	v_pk_fma_f32 v[250:251], v[250:251], v[252:253], 0.5 op_sel_hi:[1,1,0] neg_lo:[1,0,0] neg_hi:[1,0,0]
	v_pk_mul_f32 v[248:249], v[54:55], 0.5 op_sel_hi:[1,0]
	v_fma_f32 v60, |v54|, v250, v248
	v_fma_f32 v62, |v55|, v251, v249
	v_fma_f32 v248, |v56|, s60, 1.0
	v_fma_f32 v249, |v57|, s60, 1.0
	v_pk_mul_f32 v[252:253], v[56:57], v[56:57]
	v_rcp_f32_e32 v248, v248
	v_rcp_f32_e32 v249, v249
	v_pk_mul_f32 v[252:253], v[252:253], s[72:73] op_sel_hi:[1,0]
	v_pk_fma_f32 v[250:251], v[248:249], s[62:63], v[254:255] op_sel_hi:[1,0,0]
	v_exp_f32_e32 v252, v252
	v_exp_f32_e32 v253, v253
	v_pk_fma_f32 v[250:251], v[248:249], v[250:251], s[66:67] op_sel_hi:[1,1,0]
	v_pk_fma_f32 v[250:251], v[248:249], v[250:251], s[68:69] op_sel_hi:[1,1,0]
	v_pk_fma_f32 v[250:251], v[248:249], v[250:251], s[70:71] op_sel_hi:[1,1,0]
	v_pk_mul_f32 v[250:251], v[248:249], v[250:251]
	v_pk_fma_f32 v[250:251], v[250:251], v[252:253], 0.5 op_sel_hi:[1,1,0] neg_lo:[1,0,0] neg_hi:[1,0,0]
	v_pk_mul_f32 v[248:249], v[56:57], 0.5 op_sel_hi:[1,0]
	v_fma_f32 v61, |v56|, v250, v248
	v_fma_f32 v63, |v57|, v251, v249
	v_fma_f32 v248, |v52|, s60, 1.0
	v_fma_f32 v249, |v53|, s60, 1.0
	v_pk_mul_f32 v[252:253], v[52:53], v[52:53]
	v_rcp_f32_e32 v248, v248
	v_rcp_f32_e32 v249, v249
	v_pk_mul_f32 v[252:253], v[252:253], s[72:73] op_sel_hi:[1,0]
	v_pk_fma_f32 v[250:251], v[248:249], s[62:63], v[254:255] op_sel_hi:[1,0,0]
	v_exp_f32_e32 v252, v252
	v_exp_f32_e32 v253, v253
	v_pk_fma_f32 v[250:251], v[248:249], v[250:251], s[66:67] op_sel_hi:[1,1,0]
	v_pk_fma_f32 v[250:251], v[248:249], v[250:251], s[68:69] op_sel_hi:[1,1,0]
	v_pk_fma_f32 v[250:251], v[248:249], v[250:251], s[70:71] op_sel_hi:[1,1,0]
	v_pk_mul_f32 v[250:251], v[248:249], v[250:251]
	v_pk_fma_f32 v[250:251], v[250:251], v[252:253], 0.5 op_sel_hi:[1,1,0] neg_lo:[1,0,0] neg_hi:[1,0,0]
	v_pk_mul_f32 v[248:249], v[52:53], 0.5 op_sel_hi:[1,0]
	v_fma_f32 v86, |v52|, v250, v248
	v_fma_f32 v65, |v53|, v251, v249
	v_fma_f32 v248, |v50|, s60, 1.0
	v_fma_f32 v249, |v51|, s60, 1.0
	v_pk_mul_f32 v[252:253], v[50:51], v[50:51]
	v_rcp_f32_e32 v248, v248
	v_rcp_f32_e32 v249, v249
	v_pk_mul_f32 v[252:253], v[252:253], s[72:73] op_sel_hi:[1,0]
	v_pk_fma_f32 v[250:251], v[248:249], s[62:63], v[254:255] op_sel_hi:[1,0,0]
	v_exp_f32_e32 v252, v252
	v_exp_f32_e32 v253, v253
	v_pk_fma_f32 v[250:251], v[248:249], v[250:251], s[66:67] op_sel_hi:[1,1,0]
	v_pk_fma_f32 v[250:251], v[248:249], v[250:251], s[68:69] op_sel_hi:[1,1,0]
	v_pk_fma_f32 v[250:251], v[248:249], v[250:251], s[70:71] op_sel_hi:[1,1,0]
	v_pk_mul_f32 v[250:251], v[248:249], v[250:251]
	v_pk_fma_f32 v[250:251], v[250:251], v[252:253], 0.5 op_sel_hi:[1,1,0] neg_lo:[1,0,0] neg_hi:[1,0,0]
	v_pk_mul_f32 v[248:249], v[50:51], 0.5 op_sel_hi:[1,0]
	v_fma_f32 v64, |v50|, v250, v248
	v_fma_f32 v88, |v51|, v251, v249
	s_andn2_b64 vcc, exec, s[88:89]
	v_mov_b64_e32 v[90:91], v[84:85]
	s_cbranch_vccnz .LBB0_1243
	v_mov_b32_e32 v89, v65
	v_pk_add_f32 v[94:95], v[64:65], v[88:89]
	v_pk_mul_f32 v[96:97], v[64:65], v[88:89]
	v_mov_b32_e32 v90, v64
	v_mov_b32_e32 v95, v97
	v_pk_mul_f32 v[96:97], v[62:63], v[62:63]
	v_mov_b32_e32 v91, v88
	v_pk_fma_f32 v[96:97], v[60:61], v[60:61], v[96:97]
	v_pk_add_f32 v[92:93], v[60:61], v[62:63]
	v_pk_add_f32 v[96:97], v[96:97], v[96:97] op_sel_hi:[0,1]
	v_mul_f32_e32 v96, v90, v90
	v_pk_fma_f32 v[90:91], v[90:91], v[90:91], v[96:97] op_sel_hi:[1,1,0]
	v_mul_f32_e32 v89, v86, v86
	v_pk_add_f32 v[92:93], v[92:93], v[92:93] op_sel:[0,1] op_sel_hi:[1,0]
	v_mov_b32_e32 v87, v97
	v_mov_b32_e32 v90, v65
	v_mov_b32_e32 v93, v89
	v_pk_add_f32 v[90:91], v[86:87], v[90:91]
	v_pk_add_f32 v[92:93], v[92:93], v[94:95]
	s_nop 0
	v_pk_add_f32 v[90:91], v[92:93], v[90:91]
	s_nop 0
	v_pk_add_f32 v[90:91], v[90:91], v[84:85]

; __device__ __forceinline__ f32x2 gelu_pk(f32x2 v) {
;     const f32x2 av = __builtin_elementwise_abs(v), d = av * 0.2316418882f + 1.0f;
;     f32x2 t; t.x = __builtin_amdgcn_rcpf(d.x); t.y = __builtin_amdgcn_rcpf(d.y);
;     f32x2 q = t * 0.5307027145f + (-0.7265760135f); q = q * t + 0.7107068705f; q = q * t + (-0.142248368f); q = q * t + 0.127414796f; q = q * t;
;     const f32x2 s = (v * v) * (-0.72134752044f);
;     f32x2 e; e.x = __builtin_amdgcn_exp2f(s.x); e.y = __builtin_amdgcn_exp2f(s.y);
;     const f32x2 m = v * (q * e), r = v - m;
;     f32x2 o; o.x = v.x < 0.f ? m.x : r.x; o.y = v.y < 0.f ? m.y : r.y; return o;
; }
;     __device__ __forceinline__ void operator()(const f32x4 (&acc)[2][2][4][2], const Unit& u, int wr, int wc, int fr, int fq) const {
;     ...
;                     } else if (kind == 2) {
;                         f32x2 a = gelu_pk((f32x2){v0[0], v0[1]}), b = gelu_pk((f32x2){v0[2], v0[3]}), c = gelu_pk((f32x2){v1[0], v1[1]}), d = gelu_pk((f32x2){v1[2], v1[3]});
;                         v0 = (f32x4){a.x, a.y, b.x, b.y}; v1 = (f32x4){c.x, c.y, d.x, d.y};
;                         if (pn >= 9) { const float t1 = (v0[0] + v0[1]) + (v0[2] + v0[3]) + (v1[0] + v1[1]) + (v1[2] + v1[3]);
;                             const float t2 = (v0[0] * v0[0] + v0[1] * v0[1]) + (v0[2] * v0[2] + v0[3] * v0[3]) + (v1[0] * v1[0] + v1[1] * v1[1]) + (v1[2] * v1[2] + v1[3] * v1[3]);
;                             if (bj == 0) { ps = t1; pss = t2; } else { ps += t1; pss += t2; } }
.LBB0_1257:
	s_andn2_b64 vcc, exec, s[22:23]
	s_cbranch_vccnz .LBB0_1337
	s_waitcnt vmcnt(3)
	s_waitcnt vmcnt(2)
	v_mov_b64_e32 v[254:255], s[64:65]
	v_fma_f32 v248, |v46|, s60, 1.0
	v_fma_f32 v249, |v47|, s60, 1.0
	v_pk_mul_f32 v[252:253], v[46:47], v[46:47]
	v_rcp_f32_e32 v248, v248
	v_rcp_f32_e32 v249, v249
	v_pk_mul_f32 v[252:253], v[252:253], s[72:73] op_sel_hi:[1,0]
	v_pk_fma_f32 v[250:251], v[248:249], s[62:63], v[254:255] op_sel_hi:[1,0,0]
	v_exp_f32_e32 v252, v252
	v_exp_f32_e32 v253, v253
	v_pk_fma_f32 v[250:251], v[248:249], v[250:251], s[66:67] op_sel_hi:[1,1,0]
	v_pk_fma_f32 v[250:251], v[248:249], v[250:251], s[68:69] op_sel_hi:[1,1,0]
	v_pk_fma_f32 v[250:251], v[248:249], v[250:251], s[70:71] op_sel_hi:[1,1,0]
	v_pk_mul_f32 v[250:251], v[248:249], v[250:251]
	v_pk_fma_f32 v[250:251], v[250:251], v[252:253], 0.5 op_sel_hi:[1,1,0] neg_lo:[1,0,0] neg_hi:[1,0,0]
	v_pk_mul_f32 v[248:249], v[46:47], 0.5 op_sel_hi:[1,0]
	v_fma_f32 v70, |v46|, v250, v248
	v_fma_f32 v72, |v47|, v251, v249
	v_fma_f32 v248, |v48|, s60, 1.0
	v_fma_f32 v249, |v49|, s60, 1.0
	v_pk_mul_f32 v[252:253], v[48:49], v[48:49]
	v_rcp_f32_e32 v248, v248
	v_rcp_f32_e32 v249, v249
	v_pk_mul_f32 v[252:253], v[252:253], s[72:73] op_sel_hi:[1,0]
	v_pk_fma_f32 v[250:251], v[248:249], s[62:63], v[254:255] op_sel_hi:[1,0,0]
	v_exp_f32_e32 v252, v252
	v_exp_f32_e32 v253, v253
	v_pk_fma_f32 v[250:251], v[248:249], v[250:251], s[66:67] op_sel_hi:[1,1,0]
	v_pk_fma_f32 v[250:251], v[248:249], v[250:251], s[68:69] op_sel_hi:[1,1,0]
	v_pk_fma_f32 v[250:251], v[248:249], v[250:251], s[70:71] op_sel_hi:[1,1,0]
	v_pk_mul_f32 v[250:251], v[248:249], v[250:251]
	v_pk_fma_f32 v[250:251], v[250:251], v[252:253], 0.5 op_sel_hi:[1,1,0] neg_lo:[1,0,0] neg_hi:[1,0,0]
	v_pk_mul_f32 v[248:249], v[48:49], 0.5 op_sel_hi:[1,0]
	v_fma_f32 v71, |v48|, v250, v248
	v_fma_f32 v73, |v49|, v251, v249
	v_fma_f32 v248, |v44|, s60, 1.0
	v_fma_f32 v249, |v45|, s60, 1.0
	v_pk_mul_f32 v[252:253], v[44:45], v[44:45]
	v_rcp_f32_e32 v248, v248
	v_rcp_f32_e32 v249, v249
	v_pk_mul_f32 v[252:253], v[252:253], s[72:73] op_sel_hi:[1,0]
	v_pk_fma_f32 v[250:251], v[248:249], s[62:63], v[254:255] op_sel_hi:[1,0,0]
	v_exp_f32_e32 v252, v252
	v_exp_f32_e32 v253, v253
	v_pk_fma_f32 v[250:251], v[248:249], v[250:251], s[66:67] op_sel_hi:[1,1,0]
	v_pk_fma_f32 v[250:251], v[248:249], v[250:251], s[68:69] op_sel_hi:[1,1,0]
	v_pk_fma_f32 v[250:251], v[248:249], v[250:251], s[70:71] op_sel_hi:[1,1,0]
	v_pk_mul_f32 v[250:251], v[248:249], v[250:251]
	v_pk_fma_f32 v[250:251], v[250:251], v[252:253], 0.5 op_sel_hi:[1,1,0] neg_lo:[1,0,0] neg_hi:[1,0,0]
	v_pk_mul_f32 v[248:249], v[44:45], 0.5 op_sel_hi:[1,0]
	v_fma_f32 v76, |v44|, v250, v248
	v_fma_f32 v75, |v45|, v251, v249
	v_fma_f32 v248, |v42|, s60, 1.0
	v_fma_f32 v249, |v43|, s60, 1.0
	v_pk_mul_f32 v[252:253], v[42:43], v[42:43]
	v_rcp_f32_e32 v248, v248
	v_rcp_f32_e32 v249, v249
	v_pk_mul_f32 v[252:253], v[252:253], s[72:73] op_sel_hi:[1,0]
	v_pk_fma_f32 v[250:251], v[248:249], s[62:63], v[254:255] op_sel_hi:[1,0,0]
	v_exp_f32_e32 v252, v252
	v_exp_f32_e32 v253, v253
	v_pk_fma_f32 v[250:251], v[248:249], v[250:251], s[66:67] op_sel_hi:[1,1,0]
	v_pk_fma_f32 v[250:251], v[248:249], v[250:251], s[68:69] op_sel_hi:[1,1,0]
	v_pk_fma_f32 v[250:251], v[248:249], v[250:251], s[70:71] op_sel_hi:[1,1,0]
	v_pk_mul_f32 v[250:251], v[248:249], v[250:251]
	v_pk_fma_f32 v[250:251], v[250:251], v[252:253], 0.5 op_sel_hi:[1,1,0] neg_lo:[1,0,0] neg_hi:[1,0,0]
	v_pk_mul_f32 v[248:249], v[42:43], 0.5 op_sel_hi:[1,0]
	v_fma_f32 v74, |v42|, v250, v248
	v_fma_f32 v78, |v43|, v251, v249
	s_andn2_b64 vcc, exec, s[88:89]
	s_cbranch_vccnz .LBB0_1337
	v_mov_b32_e32 v79, v75
	v_pk_add_f32 v[82:83], v[74:75], v[78:79]
	v_pk_mul_f32 v[84:85], v[74:75], v[78:79]
	v_mov_b32_e32 v68, v74
	v_mov_b32_e32 v83, v85
	v_pk_mul_f32 v[84:85], v[72:73], v[72:73]
	v_mov_b32_e32 v69, v78
	v_pk_fma_f32 v[84:85], v[70:71], v[70:71], v[84:85]
	v_pk_add_f32 v[80:81], v[70:71], v[72:73]
	v_pk_add_f32 v[84:85], v[84:85], v[84:85] op_sel_hi:[0,1]
	v_mul_f32_e32 v84, v68, v68
	v_pk_fma_f32 v[68:69], v[68:69], v[68:69], v[84:85] op_sel_hi:[1,1,0]
	v_mul_f32_e32 v79, v76, v76
	v_pk_add_f32 v[80:81], v[80:81], v[80:81] op_sel:[0,1] op_sel_hi:[1,0]
	v_mov_b32_e32 v77, v85
	v_mov_b32_e32 v68, v75
	v_mov_b32_e32 v81, v79
	v_pk_add_f32 v[68:69], v[76:77], v[68:69]
	v_pk_add_f32 v[80:81], v[80:81], v[82:83]
	s_nop 0
	v_pk_add_f32 v[68:69], v[80:81], v[68:69]
	s_cbranch_execz .LBB0_1261
	s_branch .LBB0_1262

; __device__ __forceinline__ f32x2 gelu_pk(f32x2 v) {
;     const f32x2 av = __builtin_elementwise_abs(v), d = av * 0.2316418882f + 1.0f;
;     f32x2 t; t.x = __builtin_amdgcn_rcpf(d.x); t.y = __builtin_amdgcn_rcpf(d.y);
;     f32x2 q = t * 0.5307027145f + (-0.7265760135f); q = q * t + 0.7107068705f; q = q * t + (-0.142248368f); q = q * t + 0.127414796f; q = q * t;
;     const f32x2 s = (v * v) * (-0.72134752044f);
;     f32x2 e; e.x = __builtin_amdgcn_exp2f(s.x); e.y = __builtin_amdgcn_exp2f(s.y);
;     const f32x2 m = v * (q * e), r = v - m;
;     f32x2 o; o.x = v.x < 0.f ? m.x : r.x; o.y = v.y < 0.f ? m.y : r.y; return o;
; }
;     __device__ __forceinline__ void operator()(const f32x4 (&acc)[2][2][4][2], const Unit& u, int wr, int wc, int fr, int fq) const {
;     ...
;                     } else if (kind == 2) {
;                         f32x2 a = gelu_pk((f32x2){v0[0], v0[1]}), b = gelu_pk((f32x2){v0[2], v0[3]}), c = gelu_pk((f32x2){v1[0], v1[1]}), d = gelu_pk((f32x2){v1[2], v1[3]});
;                         v0 = (f32x4){a.x, a.y, b.x, b.y}; v1 = (f32x4){c.x, c.y, d.x, d.y};
;                         if (pn >= 9) { const float t1 = (v0[0] + v0[1]) + (v0[2] + v0[3]) + (v1[0] + v1[1]) + (v1[2] + v1[3]);
;                             const float t2 = (v0[0] * v0[0] + v0[1] * v0[1]) + (v0[2] * v0[2] + v0[3] * v0[3]) + (v1[0] * v1[0] + v1[1] * v1[1]) + (v1[2] * v1[2] + v1[3] * v1[3]);
;                             if (bj == 0) { ps = t1; pss = t2; } else { ps += t1; pss += t2; } }
.LBB0_1267:
	s_andn2_b64 vcc, exec, s[22:23]
	v_mov_b64_e32 v[74:75], v[68:69]
	s_cbranch_vccnz .LBB0_1270
	v_mov_b64_e32 v[254:255], s[64:65]
	v_fma_f32 v248, |v38|, s60, 1.0
	v_fma_f32 v249, |v39|, s60, 1.0
	v_pk_mul_f32 v[252:253], v[38:39], v[38:39]
	v_rcp_f32_e32 v248, v248
	v_rcp_f32_e32 v249, v249
	v_pk_mul_f32 v[252:253], v[252:253], s[72:73] op_sel_hi:[1,0]
	v_pk_fma_f32 v[250:251], v[248:249], s[62:63], v[254:255] op_sel_hi:[1,0,0]
	v_exp_f32_e32 v252, v252
	v_exp_f32_e32 v253, v253
	v_pk_fma_f32 v[250:251], v[248:249], v[250:251], s[66:67] op_sel_hi:[1,1,0]
	v_pk_fma_f32 v[250:251], v[248:249], v[250:251], s[68:69] op_sel_hi:[1,1,0]
	v_pk_fma_f32 v[250:251], v[248:249], v[250:251], s[70:71] op_sel_hi:[1,1,0]
	v_pk_mul_f32 v[250:251], v[248:249], v[250:251]
	v_pk_fma_f32 v[250:251], v[250:251], v[252:253], 0.5 op_sel_hi:[1,1,0] neg_lo:[1,0,0] neg_hi:[1,0,0]
	v_pk_mul_f32 v[248:249], v[38:39], 0.5 op_sel_hi:[1,0]
	v_fma_f32 v44, |v38|, v250, v248
	v_fma_f32 v46, |v39|, v251, v249
	v_fma_f32 v248, |v40|, s60, 1.0
	v_fma_f32 v249, |v41|, s60, 1.0
	v_pk_mul_f32 v[252:253], v[40:41], v[40:41]
	v_rcp_f32_e32 v248, v248
	v_rcp_f32_e32 v249, v249
	v_pk_mul_f32 v[252:253], v[252:253], s[72:73] op_sel_hi:[1,0]
	v_pk_fma_f32 v[250:251], v[248:249], s[62:63], v[254:255] op_sel_hi:[1,0,0]
	v_exp_f32_e32 v252, v252
	v_exp_f32_e32 v253, v253
	v_pk_fma_f32 v[250:251], v[248:249], v[250:251], s[66:67] op_sel_hi:[1,1,0]
	v_pk_fma_f32 v[250:251], v[248:249], v[250:251], s[68:69] op_sel_hi:[1,1,0]
	v_pk_fma_f32 v[250:251], v[248:249], v[250:251], s[70:71] op_sel_hi:[1,1,0]
	v_pk_mul_f32 v[250:251], v[248:249], v[250:251]
	v_pk_fma_f32 v[250:251], v[250:251], v[252:253], 0.5 op_sel_hi:[1,1,0] neg_lo:[1,0,0] neg_hi:[1,0,0]
	v_pk_mul_f32 v[248:249], v[40:41], 0.5 op_sel_hi:[1,0]
	v_fma_f32 v45, |v40|, v250, v248
	v_fma_f32 v47, |v41|, v251, v249
	v_fma_f32 v248, |v36|, s60, 1.0
	v_fma_f32 v249, |v37|, s60, 1.0
	v_pk_mul_f32 v[252:253], v[36:37], v[36:37]
	v_rcp_f32_e32 v248, v248
	v_rcp_f32_e32 v249, v249
	v_pk_mul_f32 v[252:253], v[252:253], s[72:73] op_sel_hi:[1,0]
	v_pk_fma_f32 v[250:251], v[248:249], s[62:63], v[254:255] op_sel_hi:[1,0,0]
	v_exp_f32_e32 v252, v252
	v_exp_f32_e32 v253, v253
	v_pk_fma_f32 v[250:251], v[248:249], v[250:251], s[66:67] op_sel_hi:[1,1,0]
	v_pk_fma_f32 v[250:251], v[248:249], v[250:251], s[68:69] op_sel_hi:[1,1,0]
	v_pk_fma_f32 v[250:251], v[248:249], v[250:251], s[70:71] op_sel_hi:[1,1,0]
	v_pk_mul_f32 v[250:251], v[248:249], v[250:251]
	v_pk_fma_f32 v[250:251], v[250:251], v[252:253], 0.5 op_sel_hi:[1,1,0] neg_lo:[1,0,0] neg_hi:[1,0,0]
	v_pk_mul_f32 v[248:249], v[36:37], 0.5 op_sel_hi:[1,0]
	v_fma_f32 v70, |v36|, v250, v248
	v_fma_f32 v49, |v37|, v251, v249
	v_fma_f32 v248, |v34|, s60, 1.0
	v_fma_f32 v249, |v35|, s60, 1.0
	v_pk_mul_f32 v[252:253], v[34:35], v[34:35]
	v_rcp_f32_e32 v248, v248
	v_rcp_f32_e32 v249, v249
	v_pk_mul_f32 v[252:253], v[252:253], s[72:73] op_sel_hi:[1,0]
	v_pk_fma_f32 v[250:251], v[248:249], s[62:63], v[254:255] op_sel_hi:[1,0,0]
	v_exp_f32_e32 v252, v252
	v_exp_f32_e32 v253, v253
	v_pk_fma_f32 v[250:251], v[248:249], v[250:251], s[66:67] op_sel_hi:[1,1,0]
	v_pk_fma_f32 v[250:251], v[248:249], v[250:251], s[68:69] op_sel_hi:[1,1,0]
	v_pk_fma_f32 v[250:251], v[248:249], v[250:251], s[70:71] op_sel_hi:[1,1,0]
	v_pk_mul_f32 v[250:251], v[248:249], v[250:251]
	v_pk_fma_f32 v[250:251], v[250:251], v[252:253], 0.5 op_sel_hi:[1,1,0] neg_lo:[1,0,0] neg_hi:[1,0,0]
	v_pk_mul_f32 v[248:249], v[34:35], 0.5 op_sel_hi:[1,0]
	v_fma_f32 v48, |v34|, v250, v248
	v_fma_f32 v72, |v35|, v251, v249
	s_andn2_b64 vcc, exec, s[88:89]
	v_mov_b64_e32 v[74:75], v[68:69]
	s_cbranch_vccnz .LBB0_1270
	v_mov_b32_e32 v73, v49
	v_pk_add_f32 v[78:79], v[48:49], v[72:73]
	v_pk_mul_f32 v[80:81], v[48:49], v[72:73]
	v_mov_b32_e32 v74, v48
	v_mov_b32_e32 v79, v81
	v_pk_mul_f32 v[80:81], v[46:47], v[46:47]
	v_mov_b32_e32 v75, v72
	v_pk_fma_f32 v[80:81], v[44:45], v[44:45], v[80:81]
	v_pk_add_f32 v[76:77], v[44:45], v[46:47]
	v_pk_add_f32 v[80:81], v[80:81], v[80:81] op_sel_hi:[0,1]
	v_mul_f32_e32 v80, v74, v74
	v_pk_fma_f32 v[74:75], v[74:75], v[74:75], v[80:81] op_sel_hi:[1,1,0]
	v_mul_f32_e32 v73, v70, v70
	v_pk_add_f32 v[76:77], v[76:77], v[76:77] op_sel:[0,1] op_sel_hi:[1,0]
	v_mov_b32_e32 v71, v81
	v_mov_b32_e32 v74, v49
	v_mov_b32_e32 v77, v73
	v_pk_add_f32 v[74:75], v[70:71], v[74:75]
	v_pk_add_f32 v[76:77], v[76:77], v[78:79]
	s_nop 0
	v_pk_add_f32 v[74:75], v[76:77], v[74:75]
	s_nop 0
	v_pk_add_f32 v[74:75], v[74:75], v[68:69]

; __device__ __forceinline__ f32x2 gelu_pk(f32x2 v) {
;     const f32x2 av = __builtin_elementwise_abs(v), d = av * 0.2316418882f + 1.0f;
;     f32x2 t; t.x = __builtin_amdgcn_rcpf(d.x); t.y = __builtin_amdgcn_rcpf(d.y);
;     f32x2 q = t * 0.5307027145f + (-0.7265760135f); q = q * t + 0.7107068705f; q = q * t + (-0.142248368f); q = q * t + 0.127414796f; q = q * t;
;     const f32x2 s = (v * v) * (-0.72134752044f);
;     f32x2 e; e.x = __builtin_amdgcn_exp2f(s.x); e.y = __builtin_amdgcn_exp2f(s.y);
;     const f32x2 m = v * (q * e), r = v - m;
;     f32x2 o; o.x = v.x < 0.f ? m.x : r.x; o.y = v.y < 0.f ? m.y : r.y; return o;
; }
;     __device__ __forceinline__ void operator()(const f32x4 (&acc)[2][2][4][2], const Unit& u, int wr, int wc, int fr, int fq) const {
;     ...
;                     } else if (kind == 2) {
;                         f32x2 a = gelu_pk((f32x2){v0[0], v0[1]}), b = gelu_pk((f32x2){v0[2], v0[3]}), c = gelu_pk((f32x2){v1[0], v1[1]}), d = gelu_pk((f32x2){v1[2], v1[3]});
;                         v0 = (f32x4){a.x, a.y, b.x, b.y}; v1 = (f32x4){c.x, c.y, d.x, d.y};
;                         if (pn >= 9) { const float t1 = (v0[0] + v0[1]) + (v0[2] + v0[3]) + (v1[0] + v1[1]) + (v1[2] + v1[3]);
;                             const float t2 = (v0[0] * v0[0] + v0[1] * v0[1]) + (v0[2] * v0[2] + v0[3] * v0[3]) + (v1[0] * v1[0] + v1[1] * v1[1]) + (v1[2] * v1[2] + v1[3] * v1[3]);
;                             if (bj == 0) { ps = t1; pss = t2; } else { ps += t1; pss += t2; } }
.LBB0_1284:
	s_andn2_b64 vcc, exec, s[22:23]
	s_cbranch_vccnz .LBB0_1338
	s_waitcnt vmcnt(3)
	s_waitcnt vmcnt(2)
	v_mov_b64_e32 v[254:255], s[64:65]
	v_fma_f32 v248, |v30|, s60, 1.0
	v_fma_f32 v249, |v31|, s60, 1.0
	v_pk_mul_f32 v[252:253], v[30:31], v[30:31]
	v_rcp_f32_e32 v248, v248
	v_rcp_f32_e32 v249, v249
	v_pk_mul_f32 v[252:253], v[252:253], s[72:73] op_sel_hi:[1,0]
	v_pk_fma_f32 v[250:251], v[248:249], s[62:63], v[254:255] op_sel_hi:[1,0,0]
	v_exp_f32_e32 v252, v252
	v_exp_f32_e32 v253, v253
	v_pk_fma_f32 v[250:251], v[248:249], v[250:251], s[66:67] op_sel_hi:[1,1,0]
	v_pk_fma_f32 v[250:251], v[248:249], v[250:251], s[68:69] op_sel_hi:[1,1,0]
	v_pk_fma_f32 v[250:251], v[248:249], v[250:251], s[70:71] op_sel_hi:[1,1,0]
	v_pk_mul_f32 v[250:251], v[248:249], v[250:251]
	v_pk_fma_f32 v[250:251], v[250:251], v[252:253], 0.5 op_sel_hi:[1,1,0] neg_lo:[1,0,0] neg_hi:[1,0,0]
	v_pk_mul_f32 v[248:249], v[30:31], 0.5 op_sel_hi:[1,0]
	v_fma_f32 v54, |v30|, v250, v248
	v_fma_f32 v56, |v31|, v251, v249
	v_fma_f32 v248, |v32|, s60, 1.0
	v_fma_f32 v249, |v33|, s60, 1.0
	v_pk_mul_f32 v[252:253], v[32:33], v[32:33]
	v_rcp_f32_e32 v248, v248
	v_rcp_f32_e32 v249, v249
	v_pk_mul_f32 v[252:253], v[252:253], s[72:73] op_sel_hi:[1,0]
	v_pk_fma_f32 v[250:251], v[248:249], s[62:63], v[254:255] op_sel_hi:[1,0,0]
	v_exp_f32_e32 v252, v252
	v_exp_f32_e32 v253, v253
	v_pk_fma_f32 v[250:251], v[248:249], v[250:251], s[66:67] op_sel_hi:[1,1,0]
	v_pk_fma_f32 v[250:251], v[248:249], v[250:251], s[68:69] op_sel_hi:[1,1,0]
	v_pk_fma_f32 v[250:251], v[248:249], v[250:251], s[70:71] op_sel_hi:[1,1,0]
	v_pk_mul_f32 v[250:251], v[248:249], v[250:251]
	v_pk_fma_f32 v[250:251], v[250:251], v[252:253], 0.5 op_sel_hi:[1,1,0] neg_lo:[1,0,0] neg_hi:[1,0,0]
	v_pk_mul_f32 v[248:249], v[32:33], 0.5 op_sel_hi:[1,0]
	v_fma_f32 v55, |v32|, v250, v248
	v_fma_f32 v57, |v33|, v251, v249
	v_fma_f32 v248, |v28|, s60, 1.0
	v_fma_f32 v249, |v29|, s60, 1.0
	v_pk_mul_f32 v[252:253], v[28:29], v[28:29]
	v_rcp_f32_e32 v248, v248
	v_rcp_f32_e32 v249, v249
	v_pk_mul_f32 v[252:253], v[252:253], s[72:73] op_sel_hi:[1,0]
	v_pk_fma_f32 v[250:251], v[248:249], s[62:63], v[254:255] op_sel_hi:[1,0,0]
	v_exp_f32_e32 v252, v252
	v_exp_f32_e32 v253, v253
	v_pk_fma_f32 v[250:251], v[248:249], v[250:251], s[66:67] op_sel_hi:[1,1,0]
	v_pk_fma_f32 v[250:251], v[248:249], v[250:251], s[68:69] op_sel_hi:[1,1,0]
	v_pk_fma_f32 v[250:251], v[248:249], v[250:251], s[70:71] op_sel_hi:[1,1,0]
	v_pk_mul_f32 v[250:251], v[248:249], v[250:251]
	v_pk_fma_f32 v[250:251], v[250:251], v[252:253], 0.5 op_sel_hi:[1,1,0] neg_lo:[1,0,0] neg_hi:[1,0,0]
	v_pk_mul_f32 v[248:249], v[28:29], 0.5 op_sel_hi:[1,0]
	v_fma_f32 v60, |v28|, v250, v248
	v_fma_f32 v59, |v29|, v251, v249
	v_fma_f32 v248, |v26|, s60, 1.0
	v_fma_f32 v249, |v27|, s60, 1.0
	v_pk_mul_f32 v[252:253], v[26:27], v[26:27]
	v_rcp_f32_e32 v248, v248
	v_rcp_f32_e32 v249, v249
	v_pk_mul_f32 v[252:253], v[252:253], s[72:73] op_sel_hi:[1,0]
	v_pk_fma_f32 v[250:251], v[248:249], s[62:63], v[254:255] op_sel_hi:[1,0,0]
	v_exp_f32_e32 v252, v252
	v_exp_f32_e32 v253, v253
	v_pk_fma_f32 v[250:251], v[248:249], v[250:251], s[66:67] op_sel_hi:[1,1,0]
	v_pk_fma_f32 v[250:251], v[248:249], v[250:251], s[68:69] op_sel_hi:[1,1,0]
	v_pk_fma_f32 v[250:251], v[248:249], v[250:251], s[70:71] op_sel_hi:[1,1,0]
	v_pk_mul_f32 v[250:251], v[248:249], v[250:251]
	v_pk_fma_f32 v[250:251], v[250:251], v[252:253], 0.5 op_sel_hi:[1,1,0] neg_lo:[1,0,0] neg_hi:[1,0,0]
	v_pk_mul_f32 v[248:249], v[26:27], 0.5 op_sel_hi:[1,0]
	v_fma_f32 v58, |v26|, v250, v248
	v_fma_f32 v62, |v27|, v251, v249
	s_andn2_b64 vcc, exec, s[88:89]
	s_cbranch_vccnz .LBB0_1338
	v_mov_b32_e32 v63, v59
	v_pk_add_f32 v[66:67], v[58:59], v[62:63]
	v_pk_mul_f32 v[68:69], v[58:59], v[62:63]
	v_mov_b32_e32 v52, v58
	v_mov_b32_e32 v67, v69
	v_pk_mul_f32 v[68:69], v[56:57], v[56:57]
	v_mov_b32_e32 v53, v62
	v_pk_fma_f32 v[68:69], v[54:55], v[54:55], v[68:69]
	v_pk_add_f32 v[64:65], v[54:55], v[56:57]
	v_pk_add_f32 v[68:69], v[68:69], v[68:69] op_sel_hi:[0,1]
	v_mul_f32_e32 v68, v52, v52
	v_pk_fma_f32 v[52:53], v[52:53], v[52:53], v[68:69] op_sel_hi:[1,1,0]
	v_mul_f32_e32 v63, v60, v60
	v_pk_add_f32 v[64:65], v[64:65], v[64:65] op_sel:[0,1] op_sel_hi:[1,0]
	v_mov_b32_e32 v61, v69
	v_mov_b32_e32 v52, v59
	v_mov_b32_e32 v65, v63
	v_pk_add_f32 v[52:53], v[60:61], v[52:53]
	v_pk_add_f32 v[64:65], v[64:65], v[66:67]
	s_nop 0
	v_pk_add_f32 v[52:53], v[64:65], v[52:53]
	s_cbranch_execz .LBB0_1288
	s_branch .LBB0_1289

; __device__ __forceinline__ f32x2 gelu_pk(f32x2 v) {
;     const f32x2 av = __builtin_elementwise_abs(v), d = av * 0.2316418882f + 1.0f;
;     f32x2 t; t.x = __builtin_amdgcn_rcpf(d.x); t.y = __builtin_amdgcn_rcpf(d.y);
;     f32x2 q = t * 0.5307027145f + (-0.7265760135f); q = q * t + 0.7107068705f; q = q * t + (-0.142248368f); q = q * t + 0.127414796f; q = q * t;
;     const f32x2 s = (v * v) * (-0.72134752044f);
;     f32x2 e; e.x = __builtin_amdgcn_exp2f(s.x); e.y = __builtin_amdgcn_exp2f(s.y);
;     const f32x2 m = v * (q * e), r = v - m;
;     f32x2 o; o.x = v.x < 0.f ? m.x : r.x; o.y = v.y < 0.f ? m.y : r.y; return o;
; }
;     __device__ __forceinline__ void operator()(const f32x4 (&acc)[2][2][4][2], const Unit& u, int wr, int wc, int fr, int fq) const {
;     ...
;                     } else if (kind == 2) {
;                         f32x2 a = gelu_pk((f32x2){v0[0], v0[1]}), b = gelu_pk((f32x2){v0[2], v0[3]}), c = gelu_pk((f32x2){v1[0], v1[1]}), d = gelu_pk((f32x2){v1[2], v1[3]});
;                         v0 = (f32x4){a.x, a.y, b.x, b.y}; v1 = (f32x4){c.x, c.y, d.x, d.y};
;                         if (pn >= 9) { const float t1 = (v0[0] + v0[1]) + (v0[2] + v0[3]) + (v1[0] + v1[1]) + (v1[2] + v1[3]);
;                             const float t2 = (v0[0] * v0[0] + v0[1] * v0[1]) + (v0[2] * v0[2] + v0[3] * v0[3]) + (v1[0] * v1[0] + v1[1] * v1[1]) + (v1[2] * v1[2] + v1[3] * v1[3]);
;                             if (bj == 0) { ps = t1; pss = t2; } else { ps += t1; pss += t2; } }
.LBB0_1294:
	s_andn2_b64 vcc, exec, s[22:23]
	v_mov_b64_e32 v[58:59], v[52:53]
	s_cbranch_vccnz .LBB0_1297
	v_mov_b64_e32 v[254:255], s[64:65]
	v_fma_f32 v248, |v22|, s60, 1.0
	v_fma_f32 v249, |v23|, s60, 1.0
	v_pk_mul_f32 v[252:253], v[22:23], v[22:23]
	v_rcp_f32_e32 v248, v248
	v_rcp_f32_e32 v249, v249
	v_pk_mul_f32 v[252:253], v[252:253], s[72:73] op_sel_hi:[1,0]
	v_pk_fma_f32 v[250:251], v[248:249], s[62:63], v[254:255] op_sel_hi:[1,0,0]
	v_exp_f32_e32 v252, v252
	v_exp_f32_e32 v253, v253
	v_pk_fma_f32 v[250:251], v[248:249], v[250:251], s[66:67] op_sel_hi:[1,1,0]
	v_pk_fma_f32 v[250:251], v[248:249], v[250:251], s[68:69] op_sel_hi:[1,1,0]
	v_pk_fma_f32 v[250:251], v[248:249], v[250:251], s[70:71] op_sel_hi:[1,1,0]
	v_pk_mul_f32 v[250:251], v[248:249], v[250:251]
	v_pk_fma_f32 v[250:251], v[250:251], v[252:253], 0.5 op_sel_hi:[1,1,0] neg_lo:[1,0,0] neg_hi:[1,0,0]
	v_pk_mul_f32 v[248:249], v[22:23], 0.5 op_sel_hi:[1,0]
	v_fma_f32 v28, |v22|, v250, v248
	v_fma_f32 v30, |v23|, v251, v249
	v_fma_f32 v248, |v24|, s60, 1.0
	v_fma_f32 v249, |v25|, s60, 1.0
	v_pk_mul_f32 v[252:253], v[24:25], v[24:25]
	v_rcp_f32_e32 v248, v248
	v_rcp_f32_e32 v249, v249
	v_pk_mul_f32 v[252:253], v[252:253], s[72:73] op_sel_hi:[1,0]
	v_pk_fma_f32 v[250:251], v[248:249], s[62:63], v[254:255] op_sel_hi:[1,0,0]
	v_exp_f32_e32 v252, v252
	v_exp_f32_e32 v253, v253
	v_pk_fma_f32 v[250:251], v[248:249], v[250:251], s[66:67] op_sel_hi:[1,1,0]
	v_pk_fma_f32 v[250:251], v[248:249], v[250:251], s[68:69] op_sel_hi:[1,1,0]
	v_pk_fma_f32 v[250:251], v[248:249], v[250:251], s[70:71] op_sel_hi:[1,1,0]
	v_pk_mul_f32 v[250:251], v[248:249], v[250:251]
	v_pk_fma_f32 v[250:251], v[250:251], v[252:253], 0.5 op_sel_hi:[1,1,0] neg_lo:[1,0,0] neg_hi:[1,0,0]
	v_pk_mul_f32 v[248:249], v[24:25], 0.5 op_sel_hi:[1,0]
	v_fma_f32 v29, |v24|, v250, v248
	v_fma_f32 v31, |v25|, v251, v249
	v_fma_f32 v248, |v20|, s60, 1.0
	v_fma_f32 v249, |v21|, s60, 1.0
	v_pk_mul_f32 v[252:253], v[20:21], v[20:21]
	v_rcp_f32_e32 v248, v248
	v_rcp_f32_e32 v249, v249
	v_pk_mul_f32 v[252:253], v[252:253], s[72:73] op_sel_hi:[1,0]
	v_pk_fma_f32 v[250:251], v[248:249], s[62:63], v[254:255] op_sel_hi:[1,0,0]
	v_exp_f32_e32 v252, v252
	v_exp_f32_e32 v253, v253
	v_pk_fma_f32 v[250:251], v[248:249], v[250:251], s[66:67] op_sel_hi:[1,1,0]
	v_pk_fma_f32 v[250:251], v[248:249], v[250:251], s[68:69] op_sel_hi:[1,1,0]
	v_pk_fma_f32 v[250:251], v[248:249], v[250:251], s[70:71] op_sel_hi:[1,1,0]
	v_pk_mul_f32 v[250:251], v[248:249], v[250:251]
	v_pk_fma_f32 v[250:251], v[250:251], v[252:253], 0.5 op_sel_hi:[1,1,0] neg_lo:[1,0,0] neg_hi:[1,0,0]
	v_pk_mul_f32 v[248:249], v[20:21], 0.5 op_sel_hi:[1,0]
	v_fma_f32 v54, |v20|, v250, v248
	v_fma_f32 v33, |v21|, v251, v249
	v_fma_f32 v248, |v18|, s60, 1.0
	v_fma_f32 v249, |v19|, s60, 1.0
	v_pk_mul_f32 v[252:253], v[18:19], v[18:19]
	v_rcp_f32_e32 v248, v248
	v_rcp_f32_e32 v249, v249
	v_pk_mul_f32 v[252:253], v[252:253], s[72:73] op_sel_hi:[1,0]
	v_pk_fma_f32 v[250:251], v[248:249], s[62:63], v[254:255] op_sel_hi:[1,0,0]
	v_exp_f32_e32 v252, v252
	v_exp_f32_e32 v253, v253
	v_pk_fma_f32 v[250:251], v[248:249], v[250:251], s[66:67] op_sel_hi:[1,1,0]
	v_pk_fma_f32 v[250:251], v[248:249], v[250:251], s[68:69] op_sel_hi:[1,1,0]
	v_pk_fma_f32 v[250:251], v[248:249], v[250:251], s[70:71] op_sel_hi:[1,1,0]
	v_pk_mul_f32 v[250:251], v[248:249], v[250:251]
	v_pk_fma_f32 v[250:251], v[250:251], v[252:253], 0.5 op_sel_hi:[1,1,0] neg_lo:[1,0,0] neg_hi:[1,0,0]
	v_pk_mul_f32 v[248:249], v[18:19], 0.5 op_sel_hi:[1,0]
	v_fma_f32 v32, |v18|, v250, v248
	v_fma_f32 v56, |v19|, v251, v249
	s_andn2_b64 vcc, exec, s[88:89]
	v_mov_b64_e32 v[58:59], v[52:53]
	s_cbranch_vccnz .LBB0_1297
	v_mov_b32_e32 v57, v33
	v_pk_add_f32 v[62:63], v[32:33], v[56:57]
	v_pk_mul_f32 v[64:65], v[32:33], v[56:57]
	v_mov_b32_e32 v58, v32
	v_mov_b32_e32 v63, v65
	v_pk_mul_f32 v[64:65], v[30:31], v[30:31]
	v_mov_b32_e32 v59, v56
	v_pk_fma_f32 v[64:65], v[28:29], v[28:29], v[64:65]
	v_pk_add_f32 v[60:61], v[28:29], v[30:31]
	v_pk_add_f32 v[64:65], v[64:65], v[64:65] op_sel_hi:[0,1]
	v_mul_f32_e32 v64, v58, v58
	v_pk_fma_f32 v[58:59], v[58:59], v[58:59], v[64:65] op_sel_hi:[1,1,0]
	v_mul_f32_e32 v57, v54, v54
	v_pk_add_f32 v[60:61], v[60:61], v[60:61] op_sel:[0,1] op_sel_hi:[1,0]
	v_mov_b32_e32 v55, v65
	v_mov_b32_e32 v58, v33
	v_mov_b32_e32 v61, v57
	v_pk_add_f32 v[58:59], v[54:55], v[58:59]
	v_pk_add_f32 v[60:61], v[60:61], v[62:63]
	s_nop 0
	v_pk_add_f32 v[58:59], v[60:61], v[58:59]
	s_nop 0
	v_pk_add_f32 v[58:59], v[58:59], v[52:53]

; __device__ __forceinline__ f32x2 gelu_pk(f32x2 v) {
;     const f32x2 av = __builtin_elementwise_abs(v), d = av * 0.2316418882f + 1.0f;
;     f32x2 t; t.x = __builtin_amdgcn_rcpf(d.x); t.y = __builtin_amdgcn_rcpf(d.y);
;     f32x2 q = t * 0.5307027145f + (-0.7265760135f); q = q * t + 0.7107068705f; q = q * t + (-0.142248368f); q = q * t + 0.127414796f; q = q * t;
;     const f32x2 s = (v * v) * (-0.72134752044f);
;     f32x2 e; e.x = __builtin_amdgcn_exp2f(s.x); e.y = __builtin_amdgcn_exp2f(s.y);
;     const f32x2 m = v * (q * e), r = v - m;
;     f32x2 o; o.x = v.x < 0.f ? m.x : r.x; o.y = v.y < 0.f ? m.y : r.y; return o;
; }
;     __device__ __forceinline__ void operator()(const f32x4 (&acc)[2][2][4][2], const Unit& u, int wr, int wc, int fr, int fq) const {
;     ...
;                     } else if (kind == 2) {
;                         f32x2 a = gelu_pk((f32x2){v0[0], v0[1]}), b = gelu_pk((f32x2){v0[2], v0[3]}), c = gelu_pk((f32x2){v1[0], v1[1]}), d = gelu_pk((f32x2){v1[2], v1[3]});
;                         v0 = (f32x4){a.x, a.y, b.x, b.y}; v1 = (f32x4){c.x, c.y, d.x, d.y};
;                         if (pn >= 9) { const float t1 = (v0[0] + v0[1]) + (v0[2] + v0[3]) + (v1[0] + v1[1]) + (v1[2] + v1[3]);
;                             const float t2 = (v0[0] * v0[0] + v0[1] * v0[1]) + (v0[2] * v0[2] + v0[3] * v0[3]) + (v1[0] * v1[0] + v1[1] * v1[1]) + (v1[2] * v1[2] + v1[3] * v1[3]);
;                             if (bj == 0) { ps = t1; pss = t2; } else { ps += t1; pss += t2; } }
.LBB0_1311:
	s_andn2_b64 vcc, exec, s[20:21]
	s_cbranch_vccnz .LBB0_1339
	s_waitcnt vmcnt(3)
	s_waitcnt vmcnt(2)
	v_mov_b64_e32 v[254:255], s[64:65]
	v_fma_f32 v248, |v14|, s60, 1.0
	v_fma_f32 v249, |v15|, s60, 1.0
	v_pk_mul_f32 v[252:253], v[14:15], v[14:15]
	v_rcp_f32_e32 v248, v248
	v_rcp_f32_e32 v249, v249
	v_pk_mul_f32 v[252:253], v[252:253], s[72:73] op_sel_hi:[1,0]
	v_pk_fma_f32 v[250:251], v[248:249], s[62:63], v[254:255] op_sel_hi:[1,0,0]
	v_exp_f32_e32 v252, v252
	v_exp_f32_e32 v253, v253
	v_pk_fma_f32 v[250:251], v[248:249], v[250:251], s[66:67] op_sel_hi:[1,1,0]
	v_pk_fma_f32 v[250:251], v[248:249], v[250:251], s[68:69] op_sel_hi:[1,1,0]
	v_pk_fma_f32 v[250:251], v[248:249], v[250:251], s[70:71] op_sel_hi:[1,1,0]
	v_pk_mul_f32 v[250:251], v[248:249], v[250:251]
	v_pk_fma_f32 v[250:251], v[250:251], v[252:253], 0.5 op_sel_hi:[1,1,0] neg_lo:[1,0,0] neg_hi:[1,0,0]
	v_pk_mul_f32 v[248:249], v[14:15], 0.5 op_sel_hi:[1,0]
	v_fma_f32 v38, |v14|, v250, v248
	v_fma_f32 v40, |v15|, v251, v249
	v_fma_f32 v248, |v16|, s60, 1.0
	v_fma_f32 v249, |v17|, s60, 1.0
	v_pk_mul_f32 v[252:253], v[16:17], v[16:17]
	v_rcp_f32_e32 v248, v248
	v_rcp_f32_e32 v249, v249
	v_pk_mul_f32 v[252:253], v[252:253], s[72:73] op_sel_hi:[1,0]
	v_pk_fma_f32 v[250:251], v[248:249], s[62:63], v[254:255] op_sel_hi:[1,0,0]
	v_exp_f32_e32 v252, v252
	v_exp_f32_e32 v253, v253
	v_pk_fma_f32 v[250:251], v[248:249], v[250:251], s[66:67] op_sel_hi:[1,1,0]
	v_pk_fma_f32 v[250:251], v[248:249], v[250:251], s[68:69] op_sel_hi:[1,1,0]
	v_pk_fma_f32 v[250:251], v[248:249], v[250:251], s[70:71] op_sel_hi:[1,1,0]
	v_pk_mul_f32 v[250:251], v[248:249], v[250:251]
	v_pk_fma_f32 v[250:251], v[250:251], v[252:253], 0.5 op_sel_hi:[1,1,0] neg_lo:[1,0,0] neg_hi:[1,0,0]
	v_pk_mul_f32 v[248:249], v[16:17], 0.5 op_sel_hi:[1,0]
	v_fma_f32 v39, |v16|, v250, v248
	v_fma_f32 v41, |v17|, v251, v249
	v_fma_f32 v248, |v12|, s60, 1.0
	v_fma_f32 v249, |v13|, s60, 1.0
	v_pk_mul_f32 v[252:253], v[12:13], v[12:13]
	v_rcp_f32_e32 v248, v248
	v_rcp_f32_e32 v249, v249
	v_pk_mul_f32 v[252:253], v[252:253], s[72:73] op_sel_hi:[1,0]
	v_pk_fma_f32 v[250:251], v[248:249], s[62:63], v[254:255] op_sel_hi:[1,0,0]
	v_exp_f32_e32 v252, v252
	v_exp_f32_e32 v253, v253
	v_pk_fma_f32 v[250:251], v[248:249], v[250:251], s[66:67] op_sel_hi:[1,1,0]
	v_pk_fma_f32 v[250:251], v[248:249], v[250:251], s[68:69] op_sel_hi:[1,1,0]
	v_pk_fma_f32 v[250:251], v[248:249], v[250:251], s[70:71] op_sel_hi:[1,1,0]
	v_pk_mul_f32 v[250:251], v[248:249], v[250:251]
	v_pk_fma_f32 v[250:251], v[250:251], v[252:253], 0.5 op_sel_hi:[1,1,0] neg_lo:[1,0,0] neg_hi:[1,0,0]
	v_pk_mul_f32 v[248:249], v[12:13], 0.5 op_sel_hi:[1,0]
	v_fma_f32 v44, |v12|, v250, v248
	v_fma_f32 v43, |v13|, v251, v249
	v_fma_f32 v248, |v10|, s60, 1.0
	v_fma_f32 v249, |v11|, s60, 1.0
	v_pk_mul_f32 v[252:253], v[10:11], v[10:11]
	v_rcp_f32_e32 v248, v248
	v_rcp_f32_e32 v249, v249
	v_pk_mul_f32 v[252:253], v[252:253], s[72:73] op_sel_hi:[1,0]
	v_pk_fma_f32 v[250:251], v[248:249], s[62:63], v[254:255] op_sel_hi:[1,0,0]
	v_exp_f32_e32 v252, v252
	v_exp_f32_e32 v253, v253
	v_pk_fma_f32 v[250:251], v[248:249], v[250:251], s[66:67] op_sel_hi:[1,1,0]
	v_pk_fma_f32 v[250:251], v[248:249], v[250:251], s[68:69] op_sel_hi:[1,1,0]
	v_pk_fma_f32 v[250:251], v[248:249], v[250:251], s[70:71] op_sel_hi:[1,1,0]
	v_pk_mul_f32 v[250:251], v[248:249], v[250:251]
	v_pk_fma_f32 v[250:251], v[250:251], v[252:253], 0.5 op_sel_hi:[1,1,0] neg_lo:[1,0,0] neg_hi:[1,0,0]
	v_pk_mul_f32 v[248:249], v[10:11], 0.5 op_sel_hi:[1,0]
	v_fma_f32 v42, |v10|, v250, v248
	v_fma_f32 v46, |v11|, v251, v249
	s_andn2_b64 vcc, exec, s[88:89]
	s_cbranch_vccnz .LBB0_1339
	v_mov_b32_e32 v47, v43
	v_pk_add_f32 v[50:51], v[42:43], v[46:47]
	v_pk_mul_f32 v[52:53], v[42:43], v[46:47]
	v_mov_b32_e32 v36, v42
	v_mov_b32_e32 v51, v53
	v_pk_mul_f32 v[52:53], v[40:41], v[40:41]
	v_mov_b32_e32 v37, v46
	v_pk_fma_f32 v[52:53], v[38:39], v[38:39], v[52:53]
	v_pk_add_f32 v[48:49], v[38:39], v[40:41]
	v_pk_add_f32 v[52:53], v[52:53], v[52:53] op_sel_hi:[0,1]
	v_mul_f32_e32 v52, v36, v36
	v_pk_fma_f32 v[36:37], v[36:37], v[36:37], v[52:53] op_sel_hi:[1,1,0]
	v_mul_f32_e32 v47, v44, v44
	v_pk_add_f32 v[48:49], v[48:49], v[48:49] op_sel:[0,1] op_sel_hi:[1,0]
	v_mov_b32_e32 v45, v53
	v_mov_b32_e32 v36, v43
	v_mov_b32_e32 v49, v47
	v_pk_add_f32 v[36:37], v[44:45], v[36:37]
	v_pk_add_f32 v[48:49], v[48:49], v[50:51]
	s_nop 0
	v_pk_add_f32 v[36:37], v[48:49], v[36:37]
	s_cbranch_execz .LBB0_1315
	s_branch .LBB0_1316

; __device__ __forceinline__ f32x2 gelu_pk(f32x2 v) {
;     const f32x2 av = __builtin_elementwise_abs(v), d = av * 0.2316418882f + 1.0f;
;     f32x2 t; t.x = __builtin_amdgcn_rcpf(d.x); t.y = __builtin_amdgcn_rcpf(d.y);
;     f32x2 q = t * 0.5307027145f + (-0.7265760135f); q = q * t + 0.7107068705f; q = q * t + (-0.142248368f); q = q * t + 0.127414796f; q = q * t;
;     const f32x2 s = (v * v) * (-0.72134752044f);
;     f32x2 e; e.x = __builtin_amdgcn_exp2f(s.x); e.y = __builtin_amdgcn_exp2f(s.y);
;     const f32x2 m = v * (q * e), r = v - m;
;     f32x2 o; o.x = v.x < 0.f ? m.x : r.x; o.y = v.y < 0.f ? m.y : r.y; return o;
; }
;     __device__ __forceinline__ void operator()(const f32x4 (&acc)[2][2][4][2], const Unit& u, int wr, int wc, int fr, int fq) const {
;     ...
;                     } else if (kind == 2) {
;                         f32x2 a = gelu_pk((f32x2){v0[0], v0[1]}), b = gelu_pk((f32x2){v0[2], v0[3]}), c = gelu_pk((f32x2){v1[0], v1[1]}), d = gelu_pk((f32x2){v1[2], v1[3]});
;                         v0 = (f32x4){a.x, a.y, b.x, b.y}; v1 = (f32x4){c.x, c.y, d.x, d.y};
;                         if (pn >= 9) { const float t1 = (v0[0] + v0[1]) + (v0[2] + v0[3]) + (v1[0] + v1[1]) + (v1[2] + v1[3]);
;                             const float t2 = (v0[0] * v0[0] + v0[1] * v0[1]) + (v0[2] * v0[2] + v0[3] * v0[3]) + (v1[0] * v1[0] + v1[1] * v1[1]) + (v1[2] * v1[2] + v1[3] * v1[3]);
;                             if (bj == 0) { ps = t1; pss = t2; } else { ps += t1; pss += t2; } }
.LBB0_1321:
	s_andn2_b64 vcc, exec, s[12:13]
	v_mov_b64_e32 v[42:43], v[36:37]
	s_cbranch_vccnz .LBB0_1324
	v_mov_b64_e32 v[254:255], s[64:65]
	v_fma_f32 v248, |v6|, s60, 1.0
	v_fma_f32 v249, |v7|, s60, 1.0
	v_pk_mul_f32 v[252:253], v[6:7], v[6:7]
	v_rcp_f32_e32 v248, v248
	v_rcp_f32_e32 v249, v249
	v_pk_mul_f32 v[252:253], v[252:253], s[72:73] op_sel_hi:[1,0]
	v_pk_fma_f32 v[250:251], v[248:249], s[62:63], v[254:255] op_sel_hi:[1,0,0]
	v_exp_f32_e32 v252, v252
	v_exp_f32_e32 v253, v253
	v_pk_fma_f32 v[250:251], v[248:249], v[250:251], s[66:67] op_sel_hi:[1,1,0]
	v_pk_fma_f32 v[250:251], v[248:249], v[250:251], s[68:69] op_sel_hi:[1,1,0]
	v_pk_fma_f32 v[250:251], v[248:249], v[250:251], s[70:71] op_sel_hi:[1,1,0]
	v_pk_mul_f32 v[250:251], v[248:249], v[250:251]
	v_pk_fma_f32 v[250:251], v[250:251], v[252:253], 0.5 op_sel_hi:[1,1,0] neg_lo:[1,0,0] neg_hi:[1,0,0]
	v_pk_mul_f32 v[248:249], v[6:7], 0.5 op_sel_hi:[1,0]
	v_fma_f32 v12, |v6|, v250, v248
	v_fma_f32 v14, |v7|, v251, v249
	v_fma_f32 v248, |v8|, s60, 1.0
	v_fma_f32 v249, |v9|, s60, 1.0
	v_pk_mul_f32 v[252:253], v[8:9], v[8:9]
	v_rcp_f32_e32 v248, v248
	v_rcp_f32_e32 v249, v249
	v_pk_mul_f32 v[252:253], v[252:253], s[72:73] op_sel_hi:[1,0]
	v_pk_fma_f32 v[250:251], v[248:249], s[62:63], v[254:255] op_sel_hi:[1,0,0]
	v_exp_f32_e32 v252, v252
	v_exp_f32_e32 v253, v253
	v_pk_fma_f32 v[250:251], v[248:249], v[250:251], s[66:67] op_sel_hi:[1,1,0]
	v_pk_fma_f32 v[250:251], v[248:249], v[250:251], s[68:69] op_sel_hi:[1,1,0]
	v_pk_fma_f32 v[250:251], v[248:249], v[250:251], s[70:71] op_sel_hi:[1,1,0]
	v_pk_mul_f32 v[250:251], v[248:249], v[250:251]
	v_pk_fma_f32 v[250:251], v[250:251], v[252:253], 0.5 op_sel_hi:[1,1,0] neg_lo:[1,0,0] neg_hi:[1,0,0]
	v_pk_mul_f32 v[248:249], v[8:9], 0.5 op_sel_hi:[1,0]
	v_fma_f32 v13, |v8|, v250, v248
	v_fma_f32 v15, |v9|, v251, v249
	v_fma_f32 v248, |v4|, s60, 1.0
	v_fma_f32 v249, |v5|, s60, 1.0
	v_pk_mul_f32 v[252:253], v[4:5], v[4:5]
	v_rcp_f32_e32 v248, v248
	v_rcp_f32_e32 v249, v249
	v_pk_mul_f32 v[252:253], v[252:253], s[72:73] op_sel_hi:[1,0]
	v_pk_fma_f32 v[250:251], v[248:249], s[62:63], v[254:255] op_sel_hi:[1,0,0]
	v_exp_f32_e32 v252, v252
	v_exp_f32_e32 v253, v253
	v_pk_fma_f32 v[250:251], v[248:249], v[250:251], s[66:67] op_sel_hi:[1,1,0]
	v_pk_fma_f32 v[250:251], v[248:249], v[250:251], s[68:69] op_sel_hi:[1,1,0]
	v_pk_fma_f32 v[250:251], v[248:249], v[250:251], s[70:71] op_sel_hi:[1,1,0]
	v_pk_mul_f32 v[250:251], v[248:249], v[250:251]
	v_pk_fma_f32 v[250:251], v[250:251], v[252:253], 0.5 op_sel_hi:[1,1,0] neg_lo:[1,0,0] neg_hi:[1,0,0]
	v_pk_mul_f32 v[248:249], v[4:5], 0.5 op_sel_hi:[1,0]
	v_fma_f32 v38, |v4|, v250, v248
	v_fma_f32 v17, |v5|, v251, v249
	v_fma_f32 v248, |v2|, s60, 1.0
	v_fma_f32 v249, |v3|, s60, 1.0
	v_pk_mul_f32 v[252:253], v[2:3], v[2:3]
	v_rcp_f32_e32 v248, v248
	v_rcp_f32_e32 v249, v249
	v_pk_mul_f32 v[252:253], v[252:253], s[72:73] op_sel_hi:[1,0]
	v_pk_fma_f32 v[250:251], v[248:249], s[62:63], v[254:255] op_sel_hi:[1,0,0]
	v_exp_f32_e32 v252, v252
	v_exp_f32_e32 v253, v253
	v_pk_fma_f32 v[250:251], v[248:249], v[250:251], s[66:67] op_sel_hi:[1,1,0]
	v_pk_fma_f32 v[250:251], v[248:249], v[250:251], s[68:69] op_sel_hi:[1,1,0]
	v_pk_fma_f32 v[250:251], v[248:249], v[250:251], s[70:71] op_sel_hi:[1,1,0]
	v_pk_mul_f32 v[250:251], v[248:249], v[250:251]
	v_pk_fma_f32 v[250:251], v[250:251], v[252:253], 0.5 op_sel_hi:[1,1,0] neg_lo:[1,0,0] neg_hi:[1,0,0]
	v_pk_mul_f32 v[248:249], v[2:3], 0.5 op_sel_hi:[1,0]
	v_fma_f32 v16, |v2|, v250, v248
	v_fma_f32 v40, |v3|, v251, v249
	s_andn2_b64 vcc, exec, s[88:89]
	v_mov_b64_e32 v[42:43], v[36:37]
	s_cbranch_vccnz .LBB0_1324
	v_mov_b32_e32 v41, v17
	v_pk_add_f32 v[46:47], v[16:17], v[40:41]
	v_pk_mul_f32 v[48:49], v[16:17], v[40:41]
	v_mov_b32_e32 v42, v16
	v_mov_b32_e32 v47, v49
	v_pk_mul_f32 v[48:49], v[14:15], v[14:15]
	v_mov_b32_e32 v43, v40
	v_pk_fma_f32 v[48:49], v[12:13], v[12:13], v[48:49]
	v_pk_add_f32 v[44:45], v[12:13], v[14:15]
	v_pk_add_f32 v[48:49], v[48:49], v[48:49] op_sel_hi:[0,1]
	v_mul_f32_e32 v48, v42, v42
	v_pk_fma_f32 v[42:43], v[42:43], v[42:43], v[48:49] op_sel_hi:[1,1,0]
	v_mul_f32_e32 v41, v38, v38
	v_pk_add_f32 v[44:45], v[44:45], v[44:45] op_sel:[0,1] op_sel_hi:[1,0]
	v_mov_b32_e32 v39, v49
	v_mov_b32_e32 v42, v17
	v_mov_b32_e32 v45, v41
	v_pk_add_f32 v[42:43], v[38:39], v[42:43]
	v_pk_add_f32 v[44:45], v[44:45], v[46:47]
	s_nop 0
	v_pk_add_f32 v[42:43], v[44:45], v[42:43]
	s_nop 0
	v_pk_add_f32 v[42:43], v[42:43], v[36:37]
